# GEMM tile boundaries: the two wave halves keep their one-interval stagger across tiles (re-align barrier only on the last tile, back-edge re-stagger barrier removed)
# baseline (speedup 1.0000x reference)
; #define PG8_STAGE(bufoff, gbase, voff) do { _Pragma("unroll") for (int _i = 0; _i < 2; ++_i) \
;         __builtin_amdgcn_global_load_lds((const unsigned*)((const char*)(gbase) + (voff)[_i]), (LAS unsigned*)(lds + (bufoff) + ldsw + _i * 8192), 16, 0, 0); } while (0)
; #define PG8_LDA(dst, b, h) do { _Pragma("unroll") for (int m = 0; m < 4; ++m) _Pragma("unroll") for (int k = 0; k < 2; ++k) dst[m][k] = *(const LAS bf16x8*)(lds + PG8_SA(b, h) + aoff + m * 2048 + k * 1024); } while (0)
; #define PG8_LDB(dst, b, h) do { _Pragma("unroll") for (int n = 0; n < 2; ++n) _Pragma("unroll") for (int k = 0; k < 2; ++k) dst[n][k] = *(const LAS bf16x8*)(lds + PG8_SB(b, h) + boff + n * 2048 + k * 1024); } while (0)
; #define PG8_MMA(ai, bj, At, Bt) do { __builtin_amdgcn_s_setprio(1); _Pragma("unroll") for (int m = 0; m < 4; ++m) _Pragma("unroll") for (int n = 0; n < 2; ++n) _Pragma("unroll") for (int k = 0; k < 2; ++k) \
;         acc[ai][bj][m][n] = __builtin_amdgcn_mfma_f32_16x16x32_bf16(Bt[n][k], At[m][k], acc[ai][bj][m][n], 0, 0, 0); __builtin_amdgcn_s_setprio(0); } while (0)
; #define PG8_WAIT_V(n) asm volatile("s_waitcnt vmcnt(" #n ")" ::: "memory")
; #define PG8_WAIT_L(n) asm volatile("s_waitcnt lgkmcnt(" #n ")" ::: "memory")
; #define PG8_BAR __builtin_amdgcn_s_barrier()
; #define PG8_SCHED __builtin_amdgcn_sched_barrier(0)
; #define PG8_WAIT_V(n) asm volatile("s_waitcnt vmcnt(" #n ")" ::: "memory")
; #define PG8_WAIT_L(n) asm volatile("s_waitcnt lgkmcnt(" #n ")" ::: "memory")
; template <class Epi, class Sched>
; __device__ __forceinline__ void gemm_phase(LAS unsigned char* lds, const Gemm g, const Sched& S, const Epi& E) {
;     ...
;         for (int t = 0; t < nt; t += 2) {
;             const bool last = (t == nt - 2);
;             const char* a1 = cA + (size_t)(t + 1) * kstep;
;             const char* a2 = last ? nA : cA + (size_t)(t + 2) * kstep; const char* b2 = last ? nB : cB + (size_t)(t + 2) * kstep;
;             const char* a3 = a2 + kstep; const char* b3 = b2 + kstep;
;             PG8_LDB(B0, 0, 0); PG8_LDB(B1, 0, 1); PG8_SCHED; PG8_LDA(At, 0, 0); PG8_STAGE(PG8_SA(1, 1), a1 + hstepA, voffA);
;             PG8_WAIT_V(8); PG8_WAIT_L(0); PG8_BAR; PG8_MMA(0, 0, At, B0); PG8_MMA(0, 1, At, B1); PG8_BAR; PG8_SCHED;
;             PG8_LDA(At, 0, 1); PG8_STAGE(PG8_SB(0, 0), b2, voffB); PG8_STAGE(PG8_SB(0, 1), b2 + hstepB, voffB); PG8_STAGE(PG8_SA(0, 0), a2, voffA);
.LBB0_182:
	s_add_u32 s24, s18, 0xfffc0080
	s_addc_u32 s25, s19, -1
	s_add_i32 s53, 0, 0x10000
	s_cmp_eq_u32 s52, 12
	s_cselect_b32 s27, s13, s25
	s_cselect_b32 s26, s21, s24
	v_add_u32_e32 v151, s53, v154
	s_cselect_b32 s25, s11, s51
	s_cselect_b32 s24, s23, s46
	s_add_i32 s56, 0, 0x14000
	ds_read_b128 v[130:133], v151
	ds_read_b128 v[134:137], v151 offset:1024
	ds_read_b128 v[156:159], v151 offset:2048
	ds_read_b128 v[160:163], v151 offset:3072
	v_add_u32_e32 v151, s56, v154
	ds_read_b128 v[164:167], v151
	ds_read_b128 v[168:171], v151 offset:1024
	ds_read_b128 v[172:175], v151 offset:2048
	ds_read_b128 v[176:179], v151 offset:3072
	v_lshl_add_u64 v[152:153], s[18:19], 0, v[148:149]
	s_add_i32 m0, s36, 0xc000
	ds_read_b128 v[186:189], v155
	ds_read_b128 v[190:193], v155 offset:1024
	ds_read_b128 v[194:197], v155 offset:2048
	ds_read_b128 v[198:201], v155 offset:3072
	ds_read_b128 v[202:205], v155 offset:4096
	ds_read_b128 v[206:209], v155 offset:5120
	ds_read_b128 v[210:213], v155 offset:6144
	ds_read_b128 v[226:229], v155 offset:7168
	global_load_lds_dwordx4 v[152:153], off
	v_lshl_add_u64 v[152:153], s[18:19], 0, v[146:147]
	s_add_i32 m0, s36, 0xe000
	s_nop 0
	global_load_lds_dwordx4 v[152:153], off
	s_waitcnt vmcnt(8)
	s_waitcnt lgkmcnt(0)
	s_barrier
	s_setprio 1
	s_waitcnt lgkmcnt(0)
	v_mfma_f32_16x16x32_bf16 v[126:129], v[130:133], v[186:189], v[126:129]
	v_mfma_f32_16x16x32_bf16 v[122:125], v[156:159], v[186:189], v[122:125]
	v_mfma_f32_16x16x32_bf16 v[110:113], v[130:133], v[194:197], v[110:113]
	v_mfma_f32_16x16x32_bf16 v[106:109], v[156:159], v[194:197], v[106:109]
	v_mfma_f32_16x16x32_bf16 v[94:97], v[130:133], v[202:205], v[94:97]
	v_mfma_f32_16x16x32_bf16 v[90:93], v[156:159], v[202:205], v[90:93]
	v_mfma_f32_16x16x32_bf16 v[78:81], v[130:133], v[210:213], v[78:81]
	v_mfma_f32_16x16x32_bf16 v[74:77], v[156:159], v[210:213], v[74:77]
	v_mfma_f32_16x16x32_bf16 v[126:129], v[134:137], v[190:193], v[126:129]
	v_mfma_f32_16x16x32_bf16 v[122:125], v[160:163], v[190:193], v[122:125]
	v_mfma_f32_16x16x32_bf16 v[110:113], v[134:137], v[198:201], v[110:113]
	v_mfma_f32_16x16x32_bf16 v[106:109], v[160:163], v[198:201], v[106:109]
	v_mfma_f32_16x16x32_bf16 v[94:97], v[134:137], v[206:209], v[94:97]
	v_mfma_f32_16x16x32_bf16 v[90:93], v[160:163], v[206:209], v[90:93]
	v_mfma_f32_16x16x32_bf16 v[78:81], v[134:137], v[226:229], v[78:81]
	v_mfma_f32_16x16x32_bf16 v[74:77], v[160:163], v[226:229], v[74:77]
	s_setprio 0
	s_setprio 1
	v_mfma_f32_16x16x32_bf16 v[118:121], v[164:167], v[186:189], v[118:121]
	v_mfma_f32_16x16x32_bf16 v[114:117], v[172:175], v[186:189], v[114:117]
	v_mfma_f32_16x16x32_bf16 v[102:105], v[164:167], v[194:197], v[102:105]
	v_mfma_f32_16x16x32_bf16 v[98:101], v[172:175], v[194:197], v[98:101]
	v_mfma_f32_16x16x32_bf16 v[86:89], v[164:167], v[202:205], v[86:89]
	v_mfma_f32_16x16x32_bf16 v[82:85], v[172:175], v[202:205], v[82:85]
	v_mfma_f32_16x16x32_bf16 v[70:73], v[164:167], v[210:213], v[70:73]
	v_mfma_f32_16x16x32_bf16 v[66:69], v[172:175], v[210:213], v[66:69]
	v_mfma_f32_16x16x32_bf16 v[118:121], v[168:171], v[190:193], v[118:121]
	v_mfma_f32_16x16x32_bf16 v[114:117], v[176:179], v[190:193], v[114:117]
	v_mfma_f32_16x16x32_bf16 v[102:105], v[168:171], v[198:201], v[102:105]
	v_mfma_f32_16x16x32_bf16 v[98:101], v[176:179], v[198:201], v[98:101]
	v_mfma_f32_16x16x32_bf16 v[86:89], v[168:171], v[206:209], v[86:89]
	v_mfma_f32_16x16x32_bf16 v[82:85], v[176:179], v[206:209], v[82:85]
	v_mfma_f32_16x16x32_bf16 v[70:73], v[168:171], v[226:229], v[70:73]
	v_mfma_f32_16x16x32_bf16 v[66:69], v[176:179], v[226:229], v[66:69]
	s_setprio 0
	s_barrier
	s_add_i32 s53, s53, s31
	v_lshl_add_u64 v[152:153], s[24:25], 0, v[140:141]
	s_mov_b32 m0, s53
	ds_read_b128 v[186:189], v155 offset:16384
	ds_read_b128 v[190:193], v155 offset:17408
	ds_read_b128 v[194:197], v155 offset:18432
	ds_read_b128 v[198:201], v155 offset:19456
	ds_read_b128 v[202:205], v155 offset:20480
	ds_read_b128 v[206:209], v155 offset:21504
	ds_read_b128 v[210:213], v155 offset:22528
	ds_read_b128 v[226:229], v155 offset:23552
	global_load_lds_dwordx4 v[152:153], off
	s_add_i32 m0, s53, 0x2000
	s_add_u32 s54, s24, 0x40000
	v_lshl_add_u64 v[182:183], s[24:25], 0, v[144:145]
	s_addc_u32 s55, s25, 0
	s_add_i32 s53, s56, s31
	global_load_lds_dwordx4 v[182:183], off
	v_lshl_add_u64 v[184:185], s[54:55], 0, v[140:141]
	s_mov_b32 m0, s53
	v_lshl_add_u64 v[214:215], s[26:27], 0, v[142:143]
	global_load_lds_dwordx4 v[184:185], off
	v_lshl_add_u64 v[184:185], s[54:55], 0, v[144:145]
	s_add_i32 m0, s53, 0x2000
	s_nop 0
	global_load_lds_dwordx4 v[184:185], off
	v_lshl_add_u64 v[184:185], s[26:27], 0, v[138:139]
	s_mov_b32 m0, s36
	s_nop 0
	global_load_lds_dwordx4 v[184:185], off
	s_mov_b32 m0, s37
	s_nop 0
	global_load_lds_dwordx4 v[214:215], off
	s_waitcnt vmcnt(8)
	s_waitcnt lgkmcnt(0)
	s_barrier
; #define PG8_STAGE(bufoff, gbase, voff) do { _Pragma("unroll") for (int _i = 0; _i < 2; ++_i) \
;         __builtin_amdgcn_global_load_lds((const unsigned*)((const char*)(gbase) + (voff)[_i]), (LAS unsigned*)(lds + (bufoff) + ldsw + _i * 8192), 16, 0, 0); } while (0)
; #define PG8_LDA(dst, b, h) do { _Pragma("unroll") for (int m = 0; m < 4; ++m) _Pragma("unroll") for (int k = 0; k < 2; ++k) dst[m][k] = *(const LAS bf16x8*)(lds + PG8_SA(b, h) + aoff + m * 2048 + k * 1024); } while (0)
; #define PG8_LDB(dst, b, h) do { _Pragma("unroll") for (int n = 0; n < 2; ++n) _Pragma("unroll") for (int k = 0; k < 2; ++k) dst[n][k] = *(const LAS bf16x8*)(lds + PG8_SB(b, h) + boff + n * 2048 + k * 1024); } while (0)
; #define PG8_MMA(ai, bj, At, Bt) do { __builtin_amdgcn_s_setprio(1); _Pragma("unroll") for (int m = 0; m < 4; ++m) _Pragma("unroll") for (int n = 0; n < 2; ++n) _Pragma("unroll") for (int k = 0; k < 2; ++k) \
;         acc[ai][bj][m][n] = __builtin_amdgcn_mfma_f32_16x16x32_bf16(Bt[n][k], At[m][k], acc[ai][bj][m][n], 0, 0, 0); __builtin_amdgcn_s_setprio(0); } while (0)
; #define PG8_WAIT_V(n) asm volatile("s_waitcnt vmcnt(" #n ")" ::: "memory")
; #define PG8_WAIT_L(n) asm volatile("s_waitcnt lgkmcnt(" #n ")" ::: "memory")
; #define PG8_BAR __builtin_amdgcn_s_barrier()
; #define PG8_SCHED __builtin_amdgcn_sched_barrier(0)
; #define PG8_STAGE(bufoff, gbase, voff) do { _Pragma("unroll") for (int _i = 0; _i < 2; ++_i) \
;         __builtin_amdgcn_global_load_lds((const unsigned*)((const char*)(gbase) + (voff)[_i]), (LAS unsigned*)(lds + (bufoff) + ldsw + _i * 8192), 16, 0, 0); } while (0)
; #define PG8_LDA(dst, b, h) do { _Pragma("unroll") for (int m = 0; m < 4; ++m) _Pragma("unroll") for (int k = 0; k < 2; ++k) dst[m][k] = *(const LAS bf16x8*)(lds + PG8_SA(b, h) + aoff + m * 2048 + k * 1024); } while (0)
; #define PG8_BAR __builtin_amdgcn_s_barrier()
; template <class Epi, class Sched>
; __device__ __forceinline__ void gemm_phase(LAS unsigned char* lds, const Gemm g, const Sched& S, const Epi& E) {
;     ...
;             PG8_WAIT_V(8); PG8_WAIT_L(0); PG8_BAR; PG8_MMA(1, 0, At, B0); PG8_MMA(1, 1, At, B1); PG8_BAR; PG8_SCHED;
;             PG8_LDB(B0, 1, 0); PG8_LDB(B1, 1, 1); PG8_SCHED; PG8_LDA(At, 1, 0); PG8_STAGE(PG8_SA(0, 1), a2 + hstepA, voffA);
;             PG8_WAIT_V(8); PG8_WAIT_L(0); PG8_BAR; PG8_MMA(0, 0, At, B0); PG8_MMA(0, 1, At, B1); PG8_BAR; PG8_SCHED;
	s_setprio 1
	s_waitcnt lgkmcnt(0)
	v_mfma_f32_16x16x32_bf16 v[62:65], v[130:133], v[186:189], v[62:65]
	v_mfma_f32_16x16x32_bf16 v[58:61], v[156:159], v[186:189], v[58:61]
	v_mfma_f32_16x16x32_bf16 v[46:49], v[130:133], v[194:197], v[46:49]
	v_mfma_f32_16x16x32_bf16 v[42:45], v[156:159], v[194:197], v[42:45]
	v_mfma_f32_16x16x32_bf16 v[30:33], v[130:133], v[202:205], v[30:33]
	v_mfma_f32_16x16x32_bf16 v[26:29], v[156:159], v[202:205], v[26:29]
	v_mfma_f32_16x16x32_bf16 v[14:17], v[130:133], v[210:213], v[14:17]
	v_mfma_f32_16x16x32_bf16 v[10:13], v[156:159], v[210:213], v[10:13]
	v_mfma_f32_16x16x32_bf16 v[62:65], v[134:137], v[190:193], v[62:65]
	v_mfma_f32_16x16x32_bf16 v[58:61], v[160:163], v[190:193], v[58:61]
	v_mfma_f32_16x16x32_bf16 v[46:49], v[134:137], v[198:201], v[46:49]
	v_mfma_f32_16x16x32_bf16 v[42:45], v[160:163], v[198:201], v[42:45]
	v_mfma_f32_16x16x32_bf16 v[30:33], v[134:137], v[206:209], v[30:33]
	v_mfma_f32_16x16x32_bf16 v[26:29], v[160:163], v[206:209], v[26:29]
	v_mfma_f32_16x16x32_bf16 v[14:17], v[134:137], v[226:229], v[14:17]
	v_mfma_f32_16x16x32_bf16 v[10:13], v[160:163], v[226:229], v[10:13]
	s_setprio 0
	s_setprio 1
	v_mfma_f32_16x16x32_bf16 v[54:57], v[164:167], v[186:189], v[54:57]
	v_mfma_f32_16x16x32_bf16 v[50:53], v[172:175], v[186:189], v[50:53]
	v_mfma_f32_16x16x32_bf16 v[38:41], v[164:167], v[194:197], v[38:41]
	v_mfma_f32_16x16x32_bf16 v[34:37], v[172:175], v[194:197], v[34:37]
	v_mfma_f32_16x16x32_bf16 v[22:25], v[164:167], v[202:205], v[22:25]
	v_mfma_f32_16x16x32_bf16 v[18:21], v[172:175], v[202:205], v[18:21]
	v_mfma_f32_16x16x32_bf16 v[6:9], v[164:167], v[210:213], v[6:9]
	v_mfma_f32_16x16x32_bf16 v[2:5], v[172:175], v[210:213], v[2:5]
	v_mfma_f32_16x16x32_bf16 v[54:57], v[168:171], v[190:193], v[54:57]
	v_mfma_f32_16x16x32_bf16 v[50:53], v[176:179], v[190:193], v[50:53]
	v_mfma_f32_16x16x32_bf16 v[38:41], v[168:171], v[198:201], v[38:41]
	v_mfma_f32_16x16x32_bf16 v[34:37], v[176:179], v[198:201], v[34:37]
	v_mfma_f32_16x16x32_bf16 v[22:25], v[168:171], v[206:209], v[22:25]
	v_mfma_f32_16x16x32_bf16 v[18:21], v[176:179], v[206:209], v[18:21]
	v_mfma_f32_16x16x32_bf16 v[6:9], v[168:171], v[226:229], v[6:9]
	v_mfma_f32_16x16x32_bf16 v[2:5], v[176:179], v[226:229], v[2:5]
	s_setprio 0
	s_barrier
	s_add_i32 s53, 0, 0x18000
	v_add_u32_e32 v151, s53, v154
	s_add_i32 s54, 0, 0x1c000
	ds_read_b128 v[130:133], v151
	ds_read_b128 v[134:137], v151 offset:1024
	ds_read_b128 v[156:159], v151 offset:2048
	ds_read_b128 v[160:163], v151 offset:3072
	v_add_u32_e32 v151, s54, v154
	ds_read_b128 v[164:167], v151
	ds_read_b128 v[168:171], v151 offset:1024
	ds_read_b128 v[172:175], v151 offset:2048
	ds_read_b128 v[176:179], v151 offset:3072
	s_add_u32 s26, s26, 0x40000
	s_addc_u32 s27, s27, 0
	s_mov_b32 m0, s38
	v_lshl_add_u64 v[230:231], s[26:27], 0, v[138:139]
	ds_read_b128 v[186:189], v155 offset:32768
	ds_read_b128 v[190:193], v155 offset:33792
	ds_read_b128 v[194:197], v155 offset:34816
	ds_read_b128 v[198:201], v155 offset:35840
	ds_read_b128 v[202:205], v155 offset:36864
	ds_read_b128 v[206:209], v155 offset:37888
	ds_read_b128 v[210:213], v155 offset:38912
	ds_read_b128 v[226:229], v155 offset:39936
	global_load_lds_dwordx4 v[230:231], off
	v_lshl_add_u64 v[230:231], s[26:27], 0, v[142:143]
	s_mov_b32 m0, s39
	s_nop 0
	global_load_lds_dwordx4 v[230:231], off
	s_waitcnt vmcnt(8)
	s_waitcnt lgkmcnt(0)
	s_barrier
	s_setprio 1
	s_waitcnt lgkmcnt(0)
	v_mfma_f32_16x16x32_bf16 v[126:129], v[130:133], v[186:189], v[126:129]
	v_mfma_f32_16x16x32_bf16 v[122:125], v[156:159], v[186:189], v[122:125]
	v_mfma_f32_16x16x32_bf16 v[110:113], v[130:133], v[194:197], v[110:113]
	v_mfma_f32_16x16x32_bf16 v[106:109], v[156:159], v[194:197], v[106:109]
	v_mfma_f32_16x16x32_bf16 v[94:97], v[130:133], v[202:205], v[94:97]
	v_mfma_f32_16x16x32_bf16 v[90:93], v[156:159], v[202:205], v[90:93]
	v_mfma_f32_16x16x32_bf16 v[78:81], v[130:133], v[210:213], v[78:81]
	v_mfma_f32_16x16x32_bf16 v[74:77], v[156:159], v[210:213], v[74:77]
	v_mfma_f32_16x16x32_bf16 v[126:129], v[134:137], v[190:193], v[126:129]
	v_mfma_f32_16x16x32_bf16 v[122:125], v[160:163], v[190:193], v[122:125]
	v_mfma_f32_16x16x32_bf16 v[110:113], v[134:137], v[198:201], v[110:113]
	v_mfma_f32_16x16x32_bf16 v[106:109], v[160:163], v[198:201], v[106:109]
	v_mfma_f32_16x16x32_bf16 v[94:97], v[134:137], v[206:209], v[94:97]
	v_mfma_f32_16x16x32_bf16 v[90:93], v[160:163], v[206:209], v[90:93]
	v_mfma_f32_16x16x32_bf16 v[78:81], v[134:137], v[226:229], v[78:81]
	v_mfma_f32_16x16x32_bf16 v[74:77], v[160:163], v[226:229], v[74:77]
	s_setprio 0
	s_setprio 1
	v_mfma_f32_16x16x32_bf16 v[118:121], v[164:167], v[186:189], v[118:121]
	v_mfma_f32_16x16x32_bf16 v[114:117], v[172:175], v[186:189], v[114:117]
	v_mfma_f32_16x16x32_bf16 v[102:105], v[164:167], v[194:197], v[102:105]
	v_mfma_f32_16x16x32_bf16 v[98:101], v[172:175], v[194:197], v[98:101]
	v_mfma_f32_16x16x32_bf16 v[86:89], v[164:167], v[202:205], v[86:89]
	v_mfma_f32_16x16x32_bf16 v[82:85], v[172:175], v[202:205], v[82:85]
	v_mfma_f32_16x16x32_bf16 v[70:73], v[164:167], v[210:213], v[70:73]
	v_mfma_f32_16x16x32_bf16 v[66:69], v[172:175], v[210:213], v[66:69]
	v_mfma_f32_16x16x32_bf16 v[118:121], v[168:171], v[190:193], v[118:121]
	v_mfma_f32_16x16x32_bf16 v[114:117], v[176:179], v[190:193], v[114:117]
	v_mfma_f32_16x16x32_bf16 v[102:105], v[168:171], v[198:201], v[102:105]
	v_mfma_f32_16x16x32_bf16 v[98:101], v[176:179], v[198:201], v[98:101]
	v_mfma_f32_16x16x32_bf16 v[86:89], v[168:171], v[206:209], v[86:89]
	v_mfma_f32_16x16x32_bf16 v[82:85], v[176:179], v[206:209], v[82:85]
	v_mfma_f32_16x16x32_bf16 v[70:73], v[168:171], v[226:229], v[70:73]
	v_mfma_f32_16x16x32_bf16 v[66:69], v[176:179], v[226:229], v[66:69]
	s_setprio 0
	s_barrier
; #define PG8_STAGE(bufoff, gbase, voff) do { _Pragma("unroll") for (int _i = 0; _i < 2; ++_i) \
;         __builtin_amdgcn_global_load_lds((const unsigned*)((const char*)(gbase) + (voff)[_i]), (LAS unsigned*)(lds + (bufoff) + ldsw + _i * 8192), 16, 0, 0); } while (0)
; #define PG8_LDA(dst, b, h) do { _Pragma("unroll") for (int m = 0; m < 4; ++m) _Pragma("unroll") for (int k = 0; k < 2; ++k) dst[m][k] = *(const LAS bf16x8*)(lds + PG8_SA(b, h) + aoff + m * 2048 + k * 1024); } while (0)
; #define PG8_MMA(ai, bj, At, Bt) do { __builtin_amdgcn_s_setprio(1); _Pragma("unroll") for (int m = 0; m < 4; ++m) _Pragma("unroll") for (int n = 0; n < 2; ++n) _Pragma("unroll") for (int k = 0; k < 2; ++k) \
;         acc[ai][bj][m][n] = __builtin_amdgcn_mfma_f32_16x16x32_bf16(Bt[n][k], At[m][k], acc[ai][bj][m][n], 0, 0, 0); __builtin_amdgcn_s_setprio(0); } while (0)
; #define PG8_WAIT_V(n) asm volatile("s_waitcnt vmcnt(" #n ")" ::: "memory")
; #define PG8_WAIT_L(n) asm volatile("s_waitcnt lgkmcnt(" #n ")" ::: "memory")
; #define PG8_BAR __builtin_amdgcn_s_barrier()
; #define PG8_SCHED __builtin_amdgcn_sched_barrier(0)
; #define PG8_STAGE(bufoff, gbase, voff) do { _Pragma("unroll") for (int _i = 0; _i < 2; ++_i) \
;         __builtin_amdgcn_global_load_lds((const unsigned*)((const char*)(gbase) + (voff)[_i]), (LAS unsigned*)(lds + (bufoff) + ldsw + _i * 8192), 16, 0, 0); } while (0)
; #define PG8_LDA(dst, b, h) do { _Pragma("unroll") for (int m = 0; m < 4; ++m) _Pragma("unroll") for (int k = 0; k < 2; ++k) dst[m][k] = *(const LAS bf16x8*)(lds + PG8_SA(b, h) + aoff + m * 2048 + k * 1024); } while (0)
; #define PG8_WAIT_V(n) asm volatile("s_waitcnt vmcnt(" #n ")" ::: "memory")
; #define PG8_WAIT_L(n) asm volatile("s_waitcnt lgkmcnt(" #n ")" ::: "memory")
; #define PG8_BAR __builtin_amdgcn_s_barrier()
; #define PG8_SCHED __builtin_amdgcn_sched_barrier(0)
; template <class Epi, class Sched>
; __device__ __forceinline__ void gemm_phase(LAS unsigned char* lds, const Gemm g, const Sched& S, const Epi& E) {
;     ...
;             PG8_LDA(At, 1, 1); PG8_STAGE(PG8_SB(1, 0), b3, voffB); PG8_STAGE(PG8_SB(1, 1), b3 + hstepB, voffB); PG8_STAGE(PG8_SA(1, 0), a3, voffA);
;             PG8_WAIT_V(8); PG8_WAIT_L(0); PG8_BAR; PG8_MMA(1, 0, At, B0); PG8_MMA(1, 1, At, B1); PG8_BAR; PG8_SCHED;
;         }
;         if (wr == 0) PG8_BAR;
	s_add_i32 s26, s53, s31
	v_lshl_add_u64 v[152:153], v[152:153], 0, s[86:87]
	s_mov_b32 m0, s26
	ds_read_b128 v[186:189], v155 offset:49152
	ds_read_b128 v[190:193], v155 offset:50176
	ds_read_b128 v[194:197], v155 offset:51200
	ds_read_b128 v[198:201], v155 offset:52224
	ds_read_b128 v[202:205], v155 offset:53248
	ds_read_b128 v[206:209], v155 offset:54272
	ds_read_b128 v[210:213], v155 offset:55296
	ds_read_b128 v[226:229], v155 offset:56320
	global_load_lds_dwordx4 v[152:153], off
	s_add_i32 m0, s26, 0x2000
	s_add_u32 s24, s24, 0x40080
	v_lshl_add_u64 v[152:153], v[182:183], 0, s[86:87]
	s_addc_u32 s25, s25, 0
	s_add_i32 s26, s54, s31
	global_load_lds_dwordx4 v[152:153], off
	v_lshl_add_u64 v[152:153], s[24:25], 0, v[140:141]
	s_mov_b32 m0, s26
	s_nop 0
	global_load_lds_dwordx4 v[152:153], off
	v_lshl_add_u64 v[152:153], s[24:25], 0, v[144:145]
	s_add_i32 m0, s26, 0x2000
	s_nop 0
	global_load_lds_dwordx4 v[152:153], off
	v_lshl_add_u64 v[152:153], v[184:185], 0, s[86:87]
	s_mov_b32 m0, s48
	s_nop 0
	global_load_lds_dwordx4 v[152:153], off
	v_lshl_add_u64 v[152:153], v[214:215], 0, s[86:87]
	s_mov_b32 m0, s49
	s_nop 0
	global_load_lds_dwordx4 v[152:153], off
	s_waitcnt vmcnt(8)
	s_waitcnt lgkmcnt(0)
	s_barrier
	s_setprio 1
	s_waitcnt lgkmcnt(0)
	v_mfma_f32_16x16x32_bf16 v[62:65], v[130:133], v[186:189], v[62:65]
	v_mfma_f32_16x16x32_bf16 v[58:61], v[156:159], v[186:189], v[58:61]
	v_mfma_f32_16x16x32_bf16 v[46:49], v[130:133], v[194:197], v[46:49]
	v_mfma_f32_16x16x32_bf16 v[42:45], v[156:159], v[194:197], v[42:45]
	v_mfma_f32_16x16x32_bf16 v[30:33], v[130:133], v[202:205], v[30:33]
	v_mfma_f32_16x16x32_bf16 v[26:29], v[156:159], v[202:205], v[26:29]
	v_mfma_f32_16x16x32_bf16 v[14:17], v[130:133], v[210:213], v[14:17]
	v_mfma_f32_16x16x32_bf16 v[10:13], v[156:159], v[210:213], v[10:13]
	v_mfma_f32_16x16x32_bf16 v[62:65], v[134:137], v[190:193], v[62:65]
	v_mfma_f32_16x16x32_bf16 v[58:61], v[160:163], v[190:193], v[58:61]
	v_mfma_f32_16x16x32_bf16 v[46:49], v[134:137], v[198:201], v[46:49]
	v_mfma_f32_16x16x32_bf16 v[42:45], v[160:163], v[198:201], v[42:45]
	v_mfma_f32_16x16x32_bf16 v[30:33], v[134:137], v[206:209], v[30:33]
	v_mfma_f32_16x16x32_bf16 v[26:29], v[160:163], v[206:209], v[26:29]
	v_mfma_f32_16x16x32_bf16 v[14:17], v[134:137], v[226:229], v[14:17]
	v_mfma_f32_16x16x32_bf16 v[10:13], v[160:163], v[226:229], v[10:13]
	s_setprio 0
	s_setprio 1
	v_mfma_f32_16x16x32_bf16 v[54:57], v[164:167], v[186:189], v[54:57]
	v_mfma_f32_16x16x32_bf16 v[50:53], v[172:175], v[186:189], v[50:53]
	v_mfma_f32_16x16x32_bf16 v[38:41], v[164:167], v[194:197], v[38:41]
	v_mfma_f32_16x16x32_bf16 v[34:37], v[172:175], v[194:197], v[34:37]
	v_mfma_f32_16x16x32_bf16 v[22:25], v[164:167], v[202:205], v[22:25]
	v_mfma_f32_16x16x32_bf16 v[18:21], v[172:175], v[202:205], v[18:21]
	v_mfma_f32_16x16x32_bf16 v[6:9], v[164:167], v[210:213], v[6:9]
	v_mfma_f32_16x16x32_bf16 v[2:5], v[172:175], v[210:213], v[2:5]
	v_mfma_f32_16x16x32_bf16 v[54:57], v[168:171], v[190:193], v[54:57]
	v_mfma_f32_16x16x32_bf16 v[50:53], v[176:179], v[190:193], v[50:53]
	v_mfma_f32_16x16x32_bf16 v[38:41], v[168:171], v[198:201], v[38:41]
	v_mfma_f32_16x16x32_bf16 v[34:37], v[176:179], v[198:201], v[34:37]
	v_mfma_f32_16x16x32_bf16 v[22:25], v[168:171], v[206:209], v[22:25]
	v_mfma_f32_16x16x32_bf16 v[18:21], v[176:179], v[206:209], v[18:21]
	v_mfma_f32_16x16x32_bf16 v[6:9], v[168:171], v[226:229], v[6:9]
	v_mfma_f32_16x16x32_bf16 v[2:5], v[176:179], v[226:229], v[2:5]
	s_setprio 0
	s_barrier
	s_add_i32 s52, s52, 2
	s_add_u32 s46, s46, 0x100
	s_addc_u32 s51, s51, 0
	s_add_u32 s18, s18, 0x100
	s_addc_u32 s19, s19, 0
	s_cmp_gt_u32 s52, 13
	s_cbranch_scc0 .LBB0_182
	s_and_b64 vcc, exec, s[8:9]
	s_andn2_b64 vcc, vcc, s[6:7]
	s_cbranch_vccz .LBB0_185
	s_barrier

; #define PG8_BAR __builtin_amdgcn_s_barrier()
; #define PG8_BAR __builtin_amdgcn_s_barrier()
; template <class Epi, class Sched>
; __device__ __forceinline__ void gemm_phase(LAS unsigned char* lds, const Gemm g, const Sched& S, const Epi& E) {
;     ...
;         if (!has_next) break;
; #pragma unroll
;         for (int a = 0; a < 2; ++a)
; #pragma unroll
;             for (int b = 0; b < 2; ++b)
; #pragma unroll
;                 for (int m = 0; m < 4; ++m)
; #pragma unroll
;                     for (int n = 0; n < 2; ++n) acc[a][b][m][n] = (f32x4){0.f, 0.f, 0.f, 0.f};
;         cur = nxt; cA = nA; cB = nB; ++ui;
;         if (wr == 1) PG8_BAR;
.LBB0_292:
	v_cvt_pk_bf16_f32 v2, v10, v11
	v_cvt_pk_bf16_f32 v3, v12, v13
	v_cvt_pk_bf16_f32 v4, v14, v15
	v_cvt_pk_bf16_f32 v5, v16, v17
	global_store_dwordx4 v[18:19], v[2:5], off offset:256
	s_andn2_b64 vcc, exec, s[6:7]
	s_mov_b64 s[6:7], -1
	s_cbranch_vccnz .LBB0_178
	s_branch .LBB0_177

; #define PG8_STAGE(bufoff, gbase, voff) do { _Pragma("unroll") for (int _i = 0; _i < 2; ++_i) \
;         __builtin_amdgcn_global_load_lds((const unsigned*)((const char*)(gbase) + (voff)[_i]), (LAS unsigned*)(lds + (bufoff) + ldsw + _i * 8192), 16, 0, 0); } while (0)
; #define PG8_LDA(dst, b, h) do { _Pragma("unroll") for (int m = 0; m < 4; ++m) _Pragma("unroll") for (int k = 0; k < 2; ++k) dst[m][k] = *(const LAS bf16x8*)(lds + PG8_SA(b, h) + aoff + m * 2048 + k * 1024); } while (0)
; #define PG8_LDB(dst, b, h) do { _Pragma("unroll") for (int n = 0; n < 2; ++n) _Pragma("unroll") for (int k = 0; k < 2; ++k) dst[n][k] = *(const LAS bf16x8*)(lds + PG8_SB(b, h) + boff + n * 2048 + k * 1024); } while (0)
; #define PG8_MMA(ai, bj, At, Bt) do { __builtin_amdgcn_s_setprio(1); _Pragma("unroll") for (int m = 0; m < 4; ++m) _Pragma("unroll") for (int n = 0; n < 2; ++n) _Pragma("unroll") for (int k = 0; k < 2; ++k) \
;         acc[ai][bj][m][n] = __builtin_amdgcn_mfma_f32_16x16x32_bf16(Bt[n][k], At[m][k], acc[ai][bj][m][n], 0, 0, 0); __builtin_amdgcn_s_setprio(0); } while (0)
; #define PG8_WAIT_V(n) asm volatile("s_waitcnt vmcnt(" #n ")" ::: "memory")
; #define PG8_WAIT_L(n) asm volatile("s_waitcnt lgkmcnt(" #n ")" ::: "memory")
; #define PG8_BAR __builtin_amdgcn_s_barrier()
; #define PG8_SCHED __builtin_amdgcn_sched_barrier(0)
; #define PG8_WAIT_V(n) asm volatile("s_waitcnt vmcnt(" #n ")" ::: "memory")
; #define PG8_WAIT_L(n) asm volatile("s_waitcnt lgkmcnt(" #n ")" ::: "memory")
; template <class Epi, class Sched>
; __device__ __forceinline__ void gemm_phase(LAS unsigned char* lds, const Gemm g, const Sched& S, const Epi& E) {
;     ...
;         for (int t = 0; t < nt; t += 2) {
;             const bool last = (t == nt - 2);
;             const char* a1 = cA + (size_t)(t + 1) * kstep;
;             const char* a2 = last ? nA : cA + (size_t)(t + 2) * kstep; const char* b2 = last ? nB : cB + (size_t)(t + 2) * kstep;
;             const char* a3 = a2 + kstep; const char* b3 = b2 + kstep;
;             PG8_LDB(B0, 0, 0); PG8_LDB(B1, 0, 1); PG8_SCHED; PG8_LDA(At, 0, 0); PG8_STAGE(PG8_SA(1, 1), a1 + hstepA, voffA);
;             PG8_WAIT_V(8); PG8_WAIT_L(0); PG8_BAR; PG8_MMA(0, 0, At, B0); PG8_MMA(0, 1, At, B1); PG8_BAR; PG8_SCHED;
;             PG8_LDA(At, 0, 1); PG8_STAGE(PG8_SB(0, 0), b2, voffB); PG8_STAGE(PG8_SB(0, 1), b2 + hstepB, voffB); PG8_STAGE(PG8_SA(0, 0), a2, voffA);
.LBB0_831:
	s_add_u32 s22, s20, 0xfffc0080
	s_addc_u32 s23, s21, -1
	s_add_i32 s52, 0, 0x10000
	s_cmp_eq_u32 s51, 12
	s_cselect_b32 s25, s15, s23
	s_cselect_b32 s24, s46, s22
	v_add_u32_e32 v144, s52, v1
	s_cselect_b32 s23, s13, s50
	s_cselect_b32 s22, s48, s49
	s_add_i32 s54, 0, 0x14000
	ds_read_b128 v[148:151], v144
	ds_read_b128 v[152:155], v144 offset:1024
	ds_read_b128 v[156:159], v144 offset:2048
	ds_read_b128 v[160:163], v144 offset:3072
	v_add_u32_e32 v144, s54, v1
	ds_read_b128 v[164:167], v144
	ds_read_b128 v[168:171], v144 offset:1024
	ds_read_b128 v[172:175], v144 offset:2048
	ds_read_b128 v[176:179], v144 offset:3072
	v_lshl_add_u64 v[144:145], s[20:21], 0, v[142:143]
	s_add_i32 m0, s36, 0xc000
	ds_read_b128 v[182:185], v147
	ds_read_b128 v[186:189], v147 offset:1024
	ds_read_b128 v[190:193], v147 offset:2048
	ds_read_b128 v[194:197], v147 offset:3072
	ds_read_b128 v[198:201], v147 offset:4096
	ds_read_b128 v[202:205], v147 offset:5120
	ds_read_b128 v[206:209], v147 offset:6144
	ds_read_b128 v[210:213], v147 offset:7168
	global_load_lds_dwordx4 v[144:145], off
	v_lshl_add_u64 v[144:145], s[20:21], 0, v[140:141]
	s_add_i32 m0, s36, 0xe000
	s_nop 0
	global_load_lds_dwordx4 v[144:145], off
	s_waitcnt vmcnt(8)
	s_waitcnt lgkmcnt(0)
	s_barrier
	s_setprio 1
	s_waitcnt lgkmcnt(0)
	v_mfma_f32_16x16x32_bf16 v[126:129], v[148:151], v[182:185], v[126:129]
	v_mfma_f32_16x16x32_bf16 v[122:125], v[156:159], v[182:185], v[122:125]
	v_mfma_f32_16x16x32_bf16 v[110:113], v[148:151], v[190:193], v[110:113]
	v_mfma_f32_16x16x32_bf16 v[106:109], v[156:159], v[190:193], v[106:109]
	v_mfma_f32_16x16x32_bf16 v[94:97], v[148:151], v[198:201], v[94:97]
	v_mfma_f32_16x16x32_bf16 v[90:93], v[156:159], v[198:201], v[90:93]
	v_mfma_f32_16x16x32_bf16 v[78:81], v[148:151], v[206:209], v[78:81]
	v_mfma_f32_16x16x32_bf16 v[74:77], v[156:159], v[206:209], v[74:77]
	v_mfma_f32_16x16x32_bf16 v[126:129], v[152:155], v[186:189], v[126:129]
	v_mfma_f32_16x16x32_bf16 v[122:125], v[160:163], v[186:189], v[122:125]
	v_mfma_f32_16x16x32_bf16 v[110:113], v[152:155], v[194:197], v[110:113]
	v_mfma_f32_16x16x32_bf16 v[106:109], v[160:163], v[194:197], v[106:109]
	v_mfma_f32_16x16x32_bf16 v[94:97], v[152:155], v[202:205], v[94:97]
	v_mfma_f32_16x16x32_bf16 v[90:93], v[160:163], v[202:205], v[90:93]
	v_mfma_f32_16x16x32_bf16 v[78:81], v[152:155], v[210:213], v[78:81]
	v_mfma_f32_16x16x32_bf16 v[74:77], v[160:163], v[210:213], v[74:77]
	s_setprio 0
	s_setprio 1
	v_mfma_f32_16x16x32_bf16 v[118:121], v[164:167], v[182:185], v[118:121]
	v_mfma_f32_16x16x32_bf16 v[114:117], v[172:175], v[182:185], v[114:117]
	v_mfma_f32_16x16x32_bf16 v[102:105], v[164:167], v[190:193], v[102:105]
	v_mfma_f32_16x16x32_bf16 v[98:101], v[172:175], v[190:193], v[98:101]
	v_mfma_f32_16x16x32_bf16 v[86:89], v[164:167], v[198:201], v[86:89]
	v_mfma_f32_16x16x32_bf16 v[82:85], v[172:175], v[198:201], v[82:85]
	v_mfma_f32_16x16x32_bf16 v[70:73], v[164:167], v[206:209], v[70:73]
	v_mfma_f32_16x16x32_bf16 v[66:69], v[172:175], v[206:209], v[66:69]
	v_mfma_f32_16x16x32_bf16 v[118:121], v[168:171], v[186:189], v[118:121]
	v_mfma_f32_16x16x32_bf16 v[114:117], v[176:179], v[186:189], v[114:117]
	v_mfma_f32_16x16x32_bf16 v[102:105], v[168:171], v[194:197], v[102:105]
	v_mfma_f32_16x16x32_bf16 v[98:101], v[176:179], v[194:197], v[98:101]
	v_mfma_f32_16x16x32_bf16 v[86:89], v[168:171], v[202:205], v[86:89]
	v_mfma_f32_16x16x32_bf16 v[82:85], v[176:179], v[202:205], v[82:85]
	v_mfma_f32_16x16x32_bf16 v[70:73], v[168:171], v[210:213], v[70:73]
	v_mfma_f32_16x16x32_bf16 v[66:69], v[176:179], v[210:213], v[66:69]
	s_setprio 0
	s_barrier
	s_add_i32 s52, s52, s30
	v_lshl_add_u64 v[144:145], s[22:23], 0, v[134:135]
	s_mov_b32 m0, s52
	ds_read_b128 v[182:185], v147 offset:16384
	ds_read_b128 v[186:189], v147 offset:17408
	ds_read_b128 v[190:193], v147 offset:18432
	ds_read_b128 v[194:197], v147 offset:19456
	ds_read_b128 v[198:201], v147 offset:20480
	ds_read_b128 v[202:205], v147 offset:21504
	ds_read_b128 v[206:209], v147 offset:22528
	ds_read_b128 v[210:213], v147 offset:23552
	global_load_lds_dwordx4 v[144:145], off
	s_add_i32 m0, s52, 0x2000
	s_add_u32 s52, s22, 0x40000
	v_lshl_add_u64 v[214:215], s[22:23], 0, v[130:131]
	s_addc_u32 s53, s23, 0
	s_add_i32 s54, s54, s30
	global_load_lds_dwordx4 v[214:215], off
	v_lshl_add_u64 v[226:227], s[52:53], 0, v[134:135]
	s_mov_b32 m0, s54
	v_lshl_add_u64 v[228:229], s[24:25], 0, v[132:133]
	global_load_lds_dwordx4 v[226:227], off
	v_lshl_add_u64 v[226:227], s[52:53], 0, v[130:131]
	s_add_i32 m0, s54, 0x2000
	s_nop 0
	global_load_lds_dwordx4 v[226:227], off
	v_lshl_add_u64 v[226:227], s[24:25], 0, v[136:137]
	s_mov_b32 m0, s36
	s_nop 0
	global_load_lds_dwordx4 v[226:227], off
	s_mov_b32 m0, s37
	s_nop 0
	global_load_lds_dwordx4 v[228:229], off
	s_waitcnt vmcnt(8)
	s_waitcnt lgkmcnt(0)
	s_barrier
; #define PG8_STAGE(bufoff, gbase, voff) do { _Pragma("unroll") for (int _i = 0; _i < 2; ++_i) \
;         __builtin_amdgcn_global_load_lds((const unsigned*)((const char*)(gbase) + (voff)[_i]), (LAS unsigned*)(lds + (bufoff) + ldsw + _i * 8192), 16, 0, 0); } while (0)
; #define PG8_LDA(dst, b, h) do { _Pragma("unroll") for (int m = 0; m < 4; ++m) _Pragma("unroll") for (int k = 0; k < 2; ++k) dst[m][k] = *(const LAS bf16x8*)(lds + PG8_SA(b, h) + aoff + m * 2048 + k * 1024); } while (0)
; #define PG8_LDB(dst, b, h) do { _Pragma("unroll") for (int n = 0; n < 2; ++n) _Pragma("unroll") for (int k = 0; k < 2; ++k) dst[n][k] = *(const LAS bf16x8*)(lds + PG8_SB(b, h) + boff + n * 2048 + k * 1024); } while (0)
; #define PG8_MMA(ai, bj, At, Bt) do { __builtin_amdgcn_s_setprio(1); _Pragma("unroll") for (int m = 0; m < 4; ++m) _Pragma("unroll") for (int n = 0; n < 2; ++n) _Pragma("unroll") for (int k = 0; k < 2; ++k) \
;         acc[ai][bj][m][n] = __builtin_amdgcn_mfma_f32_16x16x32_bf16(Bt[n][k], At[m][k], acc[ai][bj][m][n], 0, 0, 0); __builtin_amdgcn_s_setprio(0); } while (0)
; #define PG8_WAIT_V(n) asm volatile("s_waitcnt vmcnt(" #n ")" ::: "memory")
; #define PG8_WAIT_L(n) asm volatile("s_waitcnt lgkmcnt(" #n ")" ::: "memory")
; #define PG8_BAR __builtin_amdgcn_s_barrier()
; #define PG8_SCHED __builtin_amdgcn_sched_barrier(0)
; #define PG8_STAGE(bufoff, gbase, voff) do { _Pragma("unroll") for (int _i = 0; _i < 2; ++_i) \
;         __builtin_amdgcn_global_load_lds((const unsigned*)((const char*)(gbase) + (voff)[_i]), (LAS unsigned*)(lds + (bufoff) + ldsw + _i * 8192), 16, 0, 0); } while (0)
; #define PG8_LDA(dst, b, h) do { _Pragma("unroll") for (int m = 0; m < 4; ++m) _Pragma("unroll") for (int k = 0; k < 2; ++k) dst[m][k] = *(const LAS bf16x8*)(lds + PG8_SA(b, h) + aoff + m * 2048 + k * 1024); } while (0)
; #define PG8_BAR __builtin_amdgcn_s_barrier()
; template <class Epi, class Sched>
; __device__ __forceinline__ void gemm_phase(LAS unsigned char* lds, const Gemm g, const Sched& S, const Epi& E) {
;     ...
;             PG8_WAIT_V(8); PG8_WAIT_L(0); PG8_BAR; PG8_MMA(1, 0, At, B0); PG8_MMA(1, 1, At, B1); PG8_BAR; PG8_SCHED;
;             PG8_LDB(B0, 1, 0); PG8_LDB(B1, 1, 1); PG8_SCHED; PG8_LDA(At, 1, 0); PG8_STAGE(PG8_SA(0, 1), a2 + hstepA, voffA);
;             PG8_WAIT_V(8); PG8_WAIT_L(0); PG8_BAR; PG8_MMA(0, 0, At, B0); PG8_MMA(0, 1, At, B1); PG8_BAR; PG8_SCHED;
	s_setprio 1
	s_waitcnt lgkmcnt(0)
	v_mfma_f32_16x16x32_bf16 v[62:65], v[148:151], v[182:185], v[62:65]
	v_mfma_f32_16x16x32_bf16 v[58:61], v[156:159], v[182:185], v[58:61]
	v_mfma_f32_16x16x32_bf16 v[46:49], v[148:151], v[190:193], v[46:49]
	v_mfma_f32_16x16x32_bf16 v[42:45], v[156:159], v[190:193], v[42:45]
	v_mfma_f32_16x16x32_bf16 v[30:33], v[148:151], v[198:201], v[30:33]
	v_mfma_f32_16x16x32_bf16 v[26:29], v[156:159], v[198:201], v[26:29]
	v_mfma_f32_16x16x32_bf16 v[14:17], v[148:151], v[206:209], v[14:17]
	v_mfma_f32_16x16x32_bf16 v[10:13], v[156:159], v[206:209], v[10:13]
	v_mfma_f32_16x16x32_bf16 v[62:65], v[152:155], v[186:189], v[62:65]
	v_mfma_f32_16x16x32_bf16 v[58:61], v[160:163], v[186:189], v[58:61]
	v_mfma_f32_16x16x32_bf16 v[46:49], v[152:155], v[194:197], v[46:49]
	v_mfma_f32_16x16x32_bf16 v[42:45], v[160:163], v[194:197], v[42:45]
	v_mfma_f32_16x16x32_bf16 v[30:33], v[152:155], v[202:205], v[30:33]
	v_mfma_f32_16x16x32_bf16 v[26:29], v[160:163], v[202:205], v[26:29]
	v_mfma_f32_16x16x32_bf16 v[14:17], v[152:155], v[210:213], v[14:17]
	v_mfma_f32_16x16x32_bf16 v[10:13], v[160:163], v[210:213], v[10:13]
	s_setprio 0
	s_setprio 1
	v_mfma_f32_16x16x32_bf16 v[54:57], v[164:167], v[182:185], v[54:57]
	v_mfma_f32_16x16x32_bf16 v[50:53], v[172:175], v[182:185], v[50:53]
	v_mfma_f32_16x16x32_bf16 v[38:41], v[164:167], v[190:193], v[38:41]
	v_mfma_f32_16x16x32_bf16 v[34:37], v[172:175], v[190:193], v[34:37]
	v_mfma_f32_16x16x32_bf16 v[22:25], v[164:167], v[198:201], v[22:25]
	v_mfma_f32_16x16x32_bf16 v[18:21], v[172:175], v[198:201], v[18:21]
	v_mfma_f32_16x16x32_bf16 v[6:9], v[164:167], v[206:209], v[6:9]
	v_mfma_f32_16x16x32_bf16 v[2:5], v[172:175], v[206:209], v[2:5]
	v_mfma_f32_16x16x32_bf16 v[54:57], v[168:171], v[186:189], v[54:57]
	v_mfma_f32_16x16x32_bf16 v[50:53], v[176:179], v[186:189], v[50:53]
	v_mfma_f32_16x16x32_bf16 v[38:41], v[168:171], v[194:197], v[38:41]
	v_mfma_f32_16x16x32_bf16 v[34:37], v[176:179], v[194:197], v[34:37]
	v_mfma_f32_16x16x32_bf16 v[22:25], v[168:171], v[202:205], v[22:25]
	v_mfma_f32_16x16x32_bf16 v[18:21], v[176:179], v[202:205], v[18:21]
	v_mfma_f32_16x16x32_bf16 v[6:9], v[168:171], v[210:213], v[6:9]
	v_mfma_f32_16x16x32_bf16 v[2:5], v[176:179], v[210:213], v[2:5]
	s_setprio 0
	s_barrier
	s_add_i32 s52, 0, 0x18000
	s_add_i32 s53, 0, 0x1c000
	v_add_u32_e32 v160, s52, v1
	v_add_u32_e32 v176, s53, v1
	ds_read_b128 v[148:151], v160
	ds_read_b128 v[152:155], v160 offset:1024
	ds_read_b128 v[156:159], v160 offset:2048
	ds_read_b128 v[160:163], v160 offset:3072
	ds_read_b128 v[164:167], v176
	ds_read_b128 v[168:171], v176 offset:1024
	ds_read_b128 v[172:175], v176 offset:2048
	ds_read_b128 v[176:179], v176 offset:3072
	s_add_u32 s24, s24, 0x40000
	s_addc_u32 s25, s25, 0
	s_mov_b32 m0, s38
	v_lshl_add_u64 v[232:233], s[24:25], 0, v[136:137]
	ds_read_b128 v[182:185], v147 offset:32768
	ds_read_b128 v[186:189], v147 offset:33792
	ds_read_b128 v[190:193], v147 offset:34816
	ds_read_b128 v[194:197], v147 offset:35840
	ds_read_b128 v[198:201], v147 offset:36864
	ds_read_b128 v[202:205], v147 offset:37888
	ds_read_b128 v[206:209], v147 offset:38912
	ds_read_b128 v[210:213], v147 offset:39936
	global_load_lds_dwordx4 v[232:233], off
	v_lshl_add_u64 v[232:233], s[24:25], 0, v[132:133]
	s_mov_b32 m0, s39
	s_nop 0
	global_load_lds_dwordx4 v[232:233], off
	s_waitcnt vmcnt(8)
	s_waitcnt lgkmcnt(0)
	s_barrier
	s_setprio 1
	s_waitcnt lgkmcnt(0)
	v_mfma_f32_16x16x32_bf16 v[126:129], v[148:151], v[182:185], v[126:129]
	v_mfma_f32_16x16x32_bf16 v[122:125], v[156:159], v[182:185], v[122:125]
	v_mfma_f32_16x16x32_bf16 v[110:113], v[148:151], v[190:193], v[110:113]
	v_mfma_f32_16x16x32_bf16 v[106:109], v[156:159], v[190:193], v[106:109]
	v_mfma_f32_16x16x32_bf16 v[94:97], v[148:151], v[198:201], v[94:97]
	v_mfma_f32_16x16x32_bf16 v[90:93], v[156:159], v[198:201], v[90:93]
	v_mfma_f32_16x16x32_bf16 v[78:81], v[148:151], v[206:209], v[78:81]
	v_mfma_f32_16x16x32_bf16 v[74:77], v[156:159], v[206:209], v[74:77]
	v_mfma_f32_16x16x32_bf16 v[126:129], v[152:155], v[186:189], v[126:129]
	v_mfma_f32_16x16x32_bf16 v[122:125], v[160:163], v[186:189], v[122:125]
	v_mfma_f32_16x16x32_bf16 v[110:113], v[152:155], v[194:197], v[110:113]
	v_mfma_f32_16x16x32_bf16 v[106:109], v[160:163], v[194:197], v[106:109]
	v_mfma_f32_16x16x32_bf16 v[94:97], v[152:155], v[202:205], v[94:97]
	v_mfma_f32_16x16x32_bf16 v[90:93], v[160:163], v[202:205], v[90:93]
	v_mfma_f32_16x16x32_bf16 v[78:81], v[152:155], v[210:213], v[78:81]
	v_mfma_f32_16x16x32_bf16 v[74:77], v[160:163], v[210:213], v[74:77]
	s_setprio 0
	s_setprio 1
	v_mfma_f32_16x16x32_bf16 v[118:121], v[164:167], v[182:185], v[118:121]
	v_mfma_f32_16x16x32_bf16 v[114:117], v[172:175], v[182:185], v[114:117]
	v_mfma_f32_16x16x32_bf16 v[102:105], v[164:167], v[190:193], v[102:105]
	v_mfma_f32_16x16x32_bf16 v[98:101], v[172:175], v[190:193], v[98:101]
	v_mfma_f32_16x16x32_bf16 v[86:89], v[164:167], v[198:201], v[86:89]
	v_mfma_f32_16x16x32_bf16 v[82:85], v[172:175], v[198:201], v[82:85]
	v_mfma_f32_16x16x32_bf16 v[70:73], v[164:167], v[206:209], v[70:73]
	v_mfma_f32_16x16x32_bf16 v[66:69], v[172:175], v[206:209], v[66:69]
	v_mfma_f32_16x16x32_bf16 v[118:121], v[168:171], v[186:189], v[118:121]
	v_mfma_f32_16x16x32_bf16 v[114:117], v[176:179], v[186:189], v[114:117]
	v_mfma_f32_16x16x32_bf16 v[102:105], v[168:171], v[194:197], v[102:105]
	v_mfma_f32_16x16x32_bf16 v[98:101], v[176:179], v[194:197], v[98:101]
	v_mfma_f32_16x16x32_bf16 v[86:89], v[168:171], v[202:205], v[86:89]
	v_mfma_f32_16x16x32_bf16 v[82:85], v[176:179], v[202:205], v[82:85]
	v_mfma_f32_16x16x32_bf16 v[70:73], v[168:171], v[210:213], v[70:73]
	v_mfma_f32_16x16x32_bf16 v[66:69], v[176:179], v[210:213], v[66:69]
	s_setprio 0
	s_barrier
; #define PG8_STAGE(bufoff, gbase, voff) do { _Pragma("unroll") for (int _i = 0; _i < 2; ++_i) \
;         __builtin_amdgcn_global_load_lds((const unsigned*)((const char*)(gbase) + (voff)[_i]), (LAS unsigned*)(lds + (bufoff) + ldsw + _i * 8192), 16, 0, 0); } while (0)
; #define PG8_LDA(dst, b, h) do { _Pragma("unroll") for (int m = 0; m < 4; ++m) _Pragma("unroll") for (int k = 0; k < 2; ++k) dst[m][k] = *(const LAS bf16x8*)(lds + PG8_SA(b, h) + aoff + m * 2048 + k * 1024); } while (0)
; #define PG8_MMA(ai, bj, At, Bt) do { __builtin_amdgcn_s_setprio(1); _Pragma("unroll") for (int m = 0; m < 4; ++m) _Pragma("unroll") for (int n = 0; n < 2; ++n) _Pragma("unroll") for (int k = 0; k < 2; ++k) \
;         acc[ai][bj][m][n] = __builtin_amdgcn_mfma_f32_16x16x32_bf16(Bt[n][k], At[m][k], acc[ai][bj][m][n], 0, 0, 0); __builtin_amdgcn_s_setprio(0); } while (0)
; #define PG8_WAIT_V(n) asm volatile("s_waitcnt vmcnt(" #n ")" ::: "memory")
; #define PG8_WAIT_L(n) asm volatile("s_waitcnt lgkmcnt(" #n ")" ::: "memory")
; #define PG8_BAR __builtin_amdgcn_s_barrier()
; #define PG8_SCHED __builtin_amdgcn_sched_barrier(0)
; #define PG8_STAGE(bufoff, gbase, voff) do { _Pragma("unroll") for (int _i = 0; _i < 2; ++_i) \
;         __builtin_amdgcn_global_load_lds((const unsigned*)((const char*)(gbase) + (voff)[_i]), (LAS unsigned*)(lds + (bufoff) + ldsw + _i * 8192), 16, 0, 0); } while (0)
; #define PG8_WAIT_V(n) asm volatile("s_waitcnt vmcnt(" #n ")" ::: "memory")
; template <class Epi, class Sched>
; __device__ __forceinline__ void gemm_phase(LAS unsigned char* lds, const Gemm g, const Sched& S, const Epi& E) {
;     ...
;             PG8_LDA(At, 1, 1); PG8_STAGE(PG8_SB(1, 0), b3, voffB); PG8_STAGE(PG8_SB(1, 1), b3 + hstepB, voffB); PG8_STAGE(PG8_SA(1, 0), a3, voffA);
;             PG8_WAIT_V(8); PG8_WAIT_L(0); PG8_BAR; PG8_MMA(1, 0, At, B0); PG8_MMA(1, 1, At, B1); PG8_BAR; PG8_SCHED;
;         }
;         if (wr == 0) PG8_BAR;
;     __device__ __forceinline__ void operator()(f32x4 (&acc)[2][2][4][2], const Unit& u, int wr, int wc, int fr, int fq) const {
;         const int b = u.pn >> 2; const size_t cbase = (size_t)b * (b == 1 ? O_DK : O_FK / 2);     const int wave = wr * 4 + wc, lane = fq * 16 + fr;
;         EPI_LOOP_BEGIN
;             (void)row;
;             const f32x4 b0 = *(const f32x4*)(gb + col), b1 = *(const f32x4*)(gb + col + 4);
	s_add_i32 s24, s52, s30
	v_lshl_add_u64 v[144:145], v[144:145], 0, s[86:87]
	s_mov_b32 m0, s24
	ds_read_b128 v[182:185], v147 offset:49152
	ds_read_b128 v[186:189], v147 offset:50176
	ds_read_b128 v[190:193], v147 offset:51200
	ds_read_b128 v[194:197], v147 offset:52224
	ds_read_b128 v[198:201], v147 offset:53248
	ds_read_b128 v[202:205], v147 offset:54272
	ds_read_b128 v[206:209], v147 offset:55296
	ds_read_b128 v[210:213], v147 offset:56320
	global_load_lds_dwordx4 v[144:145], off
	s_add_i32 m0, s24, 0x2000
	s_add_u32 s22, s22, 0x40080
	v_lshl_add_u64 v[144:145], v[214:215], 0, s[86:87]
	s_addc_u32 s23, s23, 0
	s_add_i32 s24, s53, s30
	global_load_lds_dwordx4 v[144:145], off
	v_lshl_add_u64 v[144:145], s[22:23], 0, v[134:135]
	s_mov_b32 m0, s24
	s_nop 0
	global_load_lds_dwordx4 v[144:145], off
	v_lshl_add_u64 v[144:145], s[22:23], 0, v[130:131]
	s_add_i32 m0, s24, 0x2000
	s_nop 0
	global_load_lds_dwordx4 v[144:145], off
	v_lshl_add_u64 v[144:145], v[226:227], 0, s[86:87]
	s_mov_b32 m0, s42
	s_nop 0
	global_load_lds_dwordx4 v[144:145], off
	v_lshl_add_u64 v[144:145], v[228:229], 0, s[86:87]
	s_mov_b32 m0, s43
	s_nop 0
	global_load_lds_dwordx4 v[144:145], off
	s_waitcnt vmcnt(8)
	s_waitcnt lgkmcnt(0)
	s_barrier
	s_setprio 1
	s_waitcnt lgkmcnt(0)
	v_mfma_f32_16x16x32_bf16 v[62:65], v[148:151], v[182:185], v[62:65]
	v_mfma_f32_16x16x32_bf16 v[58:61], v[156:159], v[182:185], v[58:61]
	v_mfma_f32_16x16x32_bf16 v[46:49], v[148:151], v[190:193], v[46:49]
	v_mfma_f32_16x16x32_bf16 v[42:45], v[156:159], v[190:193], v[42:45]
	v_mfma_f32_16x16x32_bf16 v[30:33], v[148:151], v[198:201], v[30:33]
	v_mfma_f32_16x16x32_bf16 v[26:29], v[156:159], v[198:201], v[26:29]
	v_mfma_f32_16x16x32_bf16 v[14:17], v[148:151], v[206:209], v[14:17]
	v_mfma_f32_16x16x32_bf16 v[10:13], v[156:159], v[206:209], v[10:13]
	v_mfma_f32_16x16x32_bf16 v[62:65], v[152:155], v[186:189], v[62:65]
	v_mfma_f32_16x16x32_bf16 v[58:61], v[160:163], v[186:189], v[58:61]
	v_mfma_f32_16x16x32_bf16 v[46:49], v[152:155], v[194:197], v[46:49]
	v_mfma_f32_16x16x32_bf16 v[42:45], v[160:163], v[194:197], v[42:45]
	v_mfma_f32_16x16x32_bf16 v[30:33], v[152:155], v[202:205], v[30:33]
	v_mfma_f32_16x16x32_bf16 v[26:29], v[160:163], v[202:205], v[26:29]
	v_mfma_f32_16x16x32_bf16 v[14:17], v[152:155], v[210:213], v[14:17]
	v_mfma_f32_16x16x32_bf16 v[10:13], v[160:163], v[210:213], v[10:13]
	s_setprio 0
	s_setprio 1
	v_mfma_f32_16x16x32_bf16 v[54:57], v[164:167], v[182:185], v[54:57]
	v_mfma_f32_16x16x32_bf16 v[50:53], v[172:175], v[182:185], v[50:53]
	v_mfma_f32_16x16x32_bf16 v[38:41], v[164:167], v[190:193], v[38:41]
	v_mfma_f32_16x16x32_bf16 v[34:37], v[172:175], v[190:193], v[34:37]
	v_mfma_f32_16x16x32_bf16 v[22:25], v[164:167], v[198:201], v[22:25]
	v_mfma_f32_16x16x32_bf16 v[18:21], v[172:175], v[198:201], v[18:21]
	v_mfma_f32_16x16x32_bf16 v[6:9], v[164:167], v[206:209], v[6:9]
	v_mfma_f32_16x16x32_bf16 v[2:5], v[172:175], v[206:209], v[2:5]
	v_mfma_f32_16x16x32_bf16 v[54:57], v[168:171], v[186:189], v[54:57]
	v_mfma_f32_16x16x32_bf16 v[50:53], v[176:179], v[186:189], v[50:53]
	v_mfma_f32_16x16x32_bf16 v[38:41], v[168:171], v[194:197], v[38:41]
	v_mfma_f32_16x16x32_bf16 v[34:37], v[176:179], v[194:197], v[34:37]
	v_mfma_f32_16x16x32_bf16 v[22:25], v[168:171], v[202:205], v[22:25]
	v_mfma_f32_16x16x32_bf16 v[18:21], v[176:179], v[202:205], v[18:21]
	v_mfma_f32_16x16x32_bf16 v[6:9], v[168:171], v[210:213], v[6:9]
	v_mfma_f32_16x16x32_bf16 v[2:5], v[176:179], v[210:213], v[2:5]
	s_setprio 0
	s_barrier
	s_add_i32 s51, s51, 2
	s_add_u32 s49, s49, 0x100
	s_addc_u32 s50, s50, 0
	s_add_u32 s20, s20, 0x100
	s_addc_u32 s21, s21, 0
	s_cmp_gt_u32 s51, 13
	s_cbranch_scc0 .LBB0_831
	s_and_b64 vcc, exec, s[10:11]
	s_andn2_b64 vcc, vcc, s[6:7]
	s_cbranch_vccz .LBB0_834
	s_barrier
.LBB0_834:
	v_lshl_or_b32 v144, s3, 8, v146
	v_ashrrev_i32_e32 v145, 31, v144
	v_lshl_add_u64 v[144:145], v[144:145], 2, s[8:9]
	global_load_dwordx4 v[148:151], v[144:145], off
	global_load_dwordx4 v[152:155], v[144:145], off offset:16
	global_load_dwordx4 v[156:159], v[144:145], off offset:512
	global_load_dwordx4 v[160:163], v[144:145], off offset:528
	s_ashr_i32 s13, s3, 2
	s_cmp_eq_u32 s13, 1
	s_mov_b32 s15, 0x5000000
	s_cselect_b32 s15, s15, 0x4000000
	s_lshl_b32 s3, s3, 3
	s_lshl_b32 s2, s2, 5
	s_and_b32 s3, s3, 24
	s_or_b32 s2, s3, s2
	s_or_b32 s2, s2, s40
	s_lshl_b32 s2, s2, 4
	s_add_i32 s2, s2, s41
	s_mul_hi_i32 s21, s15, s13
	s_mul_i32 s20, s15, s13
	s_ashr_i32 s3, s2, 31
	v_lshl_add_u64 v[182:183], s[20:21], 1, v[138:139]
	s_lshl_b64 s[20:21], s[2:3], 10
	v_lshl_add_u64 v[182:183], v[182:183], 0, s[20:21]
	s_mov_b64 s[20:21], 0x1000
	v_lshl_add_u64 v[184:185], v[182:183], 0, s[20:21]
	v_lshl_add_u64 v[186:187], v[184:185], 0, s[20:21]
	v_lshl_add_u64 v[188:189], v[186:187], 0, s[20:21]
	s_mov_b32 s20, 0xbfb8aa3b
	s_mov_b32 s2, 1.0
	s_waitcnt vmcnt(0)
; __device__ __forceinline__ float sigmoidf_(float x) { return fast_rcp(1.0f + fast_exp2(-x * LOG2E)); }
; #define EPI_LOOP_END } if (m == 3) asm volatile("" ::: "memory"); }
; __device__ __forceinline__ u32x4 pack8(f32x4 v0, f32x4 v1) { u32x4 w; w.x = cvt_pk_bf16(v0[0], v0[1]); w.y = cvt_pk_bf16(v0[2], v0[3]); w.z = cvt_pk_bf16(v1[0], v1[1]); w.w = cvt_pk_bf16(v1[2], v1[3]); return w; }
;     __device__ __forceinline__ void operator()(f32x4 (&acc)[2][2][4][2], const Unit& u, int wr, int wc, int fr, int fq) const {
;     ...
;         EPI_LOOP_BEGIN
;             (void)row;
;             const f32x4 b0 = *(const f32x4*)(gb + col), b1 = *(const f32x4*)(gb + col + 4);
; #pragma unroll
;             for (int e = 0; e < 4; ++e) { v0[e] = sigmoidf_(v0[e] + b0[e]); v1[e] = sigmoidf_(v1[e] + b1[e]); }
;             *(u32x4*)(O + gate_frag_off(u.pm, u.pn & 3, wave, ai, m, bj, lane, cbase)) = pack8(v0, v1);
;         EPI_LOOP_END
	v_pk_add_f32 v[126:127], v[126:127], v[148:149]
	v_pk_add_f32 v[128:129], v[128:129], v[150:151]
	v_pk_add_f32 v[122:123], v[122:123], v[152:153]
	v_pk_add_f32 v[124:125], v[124:125], v[154:155]
	v_pk_mul_f32 v[126:127], v[126:127], s[20:21] op_sel_hi:[1,0]
	v_pk_mul_f32 v[128:129], v[128:129], s[20:21] op_sel_hi:[1,0]
	v_pk_mul_f32 v[122:123], v[122:123], s[20:21] op_sel_hi:[1,0]
	v_pk_mul_f32 v[124:125], v[124:125], s[20:21] op_sel_hi:[1,0]
	v_exp_f32_e32 v126, v126
	v_exp_f32_e32 v127, v127
	v_exp_f32_e32 v128, v128
	v_exp_f32_e32 v129, v129
	v_exp_f32_e32 v122, v122
	v_exp_f32_e32 v123, v123
	v_exp_f32_e32 v124, v124
	v_exp_f32_e32 v125, v125
	v_pk_add_f32 v[126:127], v[126:127], s[2:3] op_sel_hi:[1,0]
	v_pk_add_f32 v[128:129], v[128:129], s[2:3] op_sel_hi:[1,0]
	v_pk_add_f32 v[122:123], v[122:123], s[2:3] op_sel_hi:[1,0]
	v_pk_add_f32 v[124:125], v[124:125], s[2:3] op_sel_hi:[1,0]
	v_rcp_f32_e32 v126, v126
	v_rcp_f32_e32 v127, v127
	v_rcp_f32_e32 v128, v128
	v_rcp_f32_e32 v129, v129
	v_rcp_f32_e32 v122, v122
	v_rcp_f32_e32 v123, v123
	v_rcp_f32_e32 v124, v124
	v_rcp_f32_e32 v125, v125
	v_cvt_pk_bf16_f32 v164, v126, v127
	v_cvt_pk_bf16_f32 v165, v128, v129
	v_cvt_pk_bf16_f32 v166, v122, v123
	v_cvt_pk_bf16_f32 v167, v124, v125
	global_store_dwordx4 v[182:183], v[164:167], off
	v_pk_add_f32 v[118:119], v[118:119], v[156:157]
	v_pk_add_f32 v[120:121], v[120:121], v[158:159]
	v_pk_add_f32 v[114:115], v[114:115], v[160:161]
	v_pk_add_f32 v[116:117], v[116:117], v[162:163]
	v_pk_mul_f32 v[118:119], v[118:119], s[20:21] op_sel_hi:[1,0]
	v_pk_mul_f32 v[120:121], v[120:121], s[20:21] op_sel_hi:[1,0]
	v_pk_mul_f32 v[114:115], v[114:115], s[20:21] op_sel_hi:[1,0]
	v_pk_mul_f32 v[116:117], v[116:117], s[20:21] op_sel_hi:[1,0]
	v_exp_f32_e32 v118, v118
	v_exp_f32_e32 v119, v119
	v_exp_f32_e32 v120, v120
	v_exp_f32_e32 v121, v121
	v_exp_f32_e32 v114, v114
	v_exp_f32_e32 v115, v115
	v_exp_f32_e32 v116, v116
	v_exp_f32_e32 v117, v117
	v_pk_add_f32 v[118:119], v[118:119], s[2:3] op_sel_hi:[1,0]
	v_pk_add_f32 v[120:121], v[120:121], s[2:3] op_sel_hi:[1,0]
	v_pk_add_f32 v[114:115], v[114:115], s[2:3] op_sel_hi:[1,0]
	v_pk_add_f32 v[116:117], v[116:117], s[2:3] op_sel_hi:[1,0]
	v_rcp_f32_e32 v118, v118
	v_rcp_f32_e32 v119, v119
	v_rcp_f32_e32 v120, v120
	v_rcp_f32_e32 v121, v121
	v_rcp_f32_e32 v114, v114
	v_rcp_f32_e32 v115, v115
	v_rcp_f32_e32 v116, v116
	v_rcp_f32_e32 v117, v117
	v_cvt_pk_bf16_f32 v168, v118, v119
	v_cvt_pk_bf16_f32 v169, v120, v121
	v_cvt_pk_bf16_f32 v170, v114, v115
	v_cvt_pk_bf16_f32 v171, v116, v117
	global_store_dwordx4 v[182:183], v[168:171], off offset:1024
	v_pk_add_f32 v[110:111], v[110:111], v[148:149]
	v_pk_add_f32 v[112:113], v[112:113], v[150:151]
	v_pk_add_f32 v[106:107], v[106:107], v[152:153]
	v_pk_add_f32 v[108:109], v[108:109], v[154:155]
	v_pk_mul_f32 v[110:111], v[110:111], s[20:21] op_sel_hi:[1,0]
	v_pk_mul_f32 v[112:113], v[112:113], s[20:21] op_sel_hi:[1,0]
	v_pk_mul_f32 v[106:107], v[106:107], s[20:21] op_sel_hi:[1,0]
	v_pk_mul_f32 v[108:109], v[108:109], s[20:21] op_sel_hi:[1,0]
	v_exp_f32_e32 v110, v110
	v_exp_f32_e32 v111, v111
	v_exp_f32_e32 v112, v112
	v_exp_f32_e32 v113, v113
	v_exp_f32_e32 v106, v106
	v_exp_f32_e32 v107, v107
	v_exp_f32_e32 v108, v108
	v_exp_f32_e32 v109, v109
	v_pk_add_f32 v[110:111], v[110:111], s[2:3] op_sel_hi:[1,0]
	v_pk_add_f32 v[112:113], v[112:113], s[2:3] op_sel_hi:[1,0]
	v_pk_add_f32 v[106:107], v[106:107], s[2:3] op_sel_hi:[1,0]
	v_pk_add_f32 v[108:109], v[108:109], s[2:3] op_sel_hi:[1,0]
	v_rcp_f32_e32 v110, v110
	v_rcp_f32_e32 v111, v111
	v_rcp_f32_e32 v112, v112
	v_rcp_f32_e32 v113, v113
	v_rcp_f32_e32 v106, v106
	v_rcp_f32_e32 v107, v107
	v_rcp_f32_e32 v108, v108
	v_rcp_f32_e32 v109, v109
	v_cvt_pk_bf16_f32 v172, v110, v111
	v_cvt_pk_bf16_f32 v173, v112, v113
	v_cvt_pk_bf16_f32 v174, v106, v107
	v_cvt_pk_bf16_f32 v175, v108, v109
	global_store_dwordx4 v[182:183], v[172:175], off offset:2048
	v_pk_add_f32 v[102:103], v[102:103], v[156:157]
	v_pk_add_f32 v[104:105], v[104:105], v[158:159]
	v_pk_add_f32 v[98:99], v[98:99], v[160:161]
	v_pk_add_f32 v[100:101], v[100:101], v[162:163]
	v_pk_mul_f32 v[102:103], v[102:103], s[20:21] op_sel_hi:[1,0]
	v_pk_mul_f32 v[104:105], v[104:105], s[20:21] op_sel_hi:[1,0]
	v_pk_mul_f32 v[98:99], v[98:99], s[20:21] op_sel_hi:[1,0]
	v_pk_mul_f32 v[100:101], v[100:101], s[20:21] op_sel_hi:[1,0]
	v_exp_f32_e32 v102, v102
	v_exp_f32_e32 v103, v103
	v_exp_f32_e32 v104, v104
	v_exp_f32_e32 v105, v105
	v_exp_f32_e32 v98, v98
	v_exp_f32_e32 v99, v99
	v_exp_f32_e32 v100, v100
	v_exp_f32_e32 v101, v101
	v_pk_add_f32 v[102:103], v[102:103], s[2:3] op_sel_hi:[1,0]
	v_pk_add_f32 v[104:105], v[104:105], s[2:3] op_sel_hi:[1,0]
	v_pk_add_f32 v[98:99], v[98:99], s[2:3] op_sel_hi:[1,0]
	v_pk_add_f32 v[100:101], v[100:101], s[2:3] op_sel_hi:[1,0]
	v_rcp_f32_e32 v102, v102
	v_rcp_f32_e32 v103, v103
	v_rcp_f32_e32 v104, v104
	v_rcp_f32_e32 v105, v105
	v_rcp_f32_e32 v98, v98
	v_rcp_f32_e32 v99, v99
	v_rcp_f32_e32 v100, v100
	v_rcp_f32_e32 v101, v101
	v_cvt_pk_bf16_f32 v176, v102, v103
	v_cvt_pk_bf16_f32 v177, v104, v105
	v_cvt_pk_bf16_f32 v178, v98, v99
	v_cvt_pk_bf16_f32 v179, v100, v101
	global_store_dwordx4 v[182:183], v[176:179], off offset:3072
	v_pk_add_f32 v[94:95], v[94:95], v[148:149]
	v_pk_add_f32 v[96:97], v[96:97], v[150:151]
	v_pk_add_f32 v[90:91], v[90:91], v[152:153]
	v_pk_add_f32 v[92:93], v[92:93], v[154:155]
	v_pk_mul_f32 v[94:95], v[94:95], s[20:21] op_sel_hi:[1,0]
	v_pk_mul_f32 v[96:97], v[96:97], s[20:21] op_sel_hi:[1,0]
	v_pk_mul_f32 v[90:91], v[90:91], s[20:21] op_sel_hi:[1,0]
	v_pk_mul_f32 v[92:93], v[92:93], s[20:21] op_sel_hi:[1,0]
; __device__ __forceinline__ float sigmoidf_(float x) { return fast_rcp(1.0f + fast_exp2(-x * LOG2E)); }
; #define EPI_LOOP_END } if (m == 3) asm volatile("" ::: "memory"); }
; __device__ __forceinline__ u32x4 pack8(f32x4 v0, f32x4 v1) { u32x4 w; w.x = cvt_pk_bf16(v0[0], v0[1]); w.y = cvt_pk_bf16(v0[2], v0[3]); w.z = cvt_pk_bf16(v1[0], v1[1]); w.w = cvt_pk_bf16(v1[2], v1[3]); return w; }
;     __device__ __forceinline__ void operator()(f32x4 (&acc)[2][2][4][2], const Unit& u, int wr, int wc, int fr, int fq) const {
;     ...
;         EPI_LOOP_BEGIN
;             (void)row;
;             const f32x4 b0 = *(const f32x4*)(gb + col), b1 = *(const f32x4*)(gb + col + 4);
; #pragma unroll
;             for (int e = 0; e < 4; ++e) { v0[e] = sigmoidf_(v0[e] + b0[e]); v1[e] = sigmoidf_(v1[e] + b1[e]); }
;             *(u32x4*)(O + gate_frag_off(u.pm, u.pn & 3, wave, ai, m, bj, lane, cbase)) = pack8(v0, v1);
;         EPI_LOOP_END
	v_exp_f32_e32 v94, v94
	v_exp_f32_e32 v95, v95
	v_exp_f32_e32 v96, v96
	v_exp_f32_e32 v97, v97
	v_exp_f32_e32 v90, v90
	v_exp_f32_e32 v91, v91
	v_exp_f32_e32 v92, v92
	v_exp_f32_e32 v93, v93
	v_pk_add_f32 v[94:95], v[94:95], s[2:3] op_sel_hi:[1,0]
	v_pk_add_f32 v[96:97], v[96:97], s[2:3] op_sel_hi:[1,0]
	v_pk_add_f32 v[90:91], v[90:91], s[2:3] op_sel_hi:[1,0]
	v_pk_add_f32 v[92:93], v[92:93], s[2:3] op_sel_hi:[1,0]
	v_rcp_f32_e32 v94, v94
	v_rcp_f32_e32 v95, v95
	v_rcp_f32_e32 v96, v96
	v_rcp_f32_e32 v97, v97
	v_rcp_f32_e32 v90, v90
	v_rcp_f32_e32 v91, v91
	v_rcp_f32_e32 v92, v92
	v_rcp_f32_e32 v93, v93
	v_cvt_pk_bf16_f32 v164, v94, v95
	v_cvt_pk_bf16_f32 v165, v96, v97
	v_cvt_pk_bf16_f32 v166, v90, v91
	v_cvt_pk_bf16_f32 v167, v92, v93
	global_store_dwordx4 v[184:185], v[164:167], off
	v_pk_add_f32 v[86:87], v[86:87], v[156:157]
	v_pk_add_f32 v[88:89], v[88:89], v[158:159]
	v_pk_add_f32 v[82:83], v[82:83], v[160:161]
	v_pk_add_f32 v[84:85], v[84:85], v[162:163]
	v_pk_mul_f32 v[86:87], v[86:87], s[20:21] op_sel_hi:[1,0]
	v_pk_mul_f32 v[88:89], v[88:89], s[20:21] op_sel_hi:[1,0]
	v_pk_mul_f32 v[82:83], v[82:83], s[20:21] op_sel_hi:[1,0]
	v_pk_mul_f32 v[84:85], v[84:85], s[20:21] op_sel_hi:[1,0]
	v_exp_f32_e32 v86, v86
	v_exp_f32_e32 v87, v87
	v_exp_f32_e32 v88, v88
	v_exp_f32_e32 v89, v89
	v_exp_f32_e32 v82, v82
	v_exp_f32_e32 v83, v83
	v_exp_f32_e32 v84, v84
	v_exp_f32_e32 v85, v85
	v_pk_add_f32 v[86:87], v[86:87], s[2:3] op_sel_hi:[1,0]
	v_pk_add_f32 v[88:89], v[88:89], s[2:3] op_sel_hi:[1,0]
	v_pk_add_f32 v[82:83], v[82:83], s[2:3] op_sel_hi:[1,0]
	v_pk_add_f32 v[84:85], v[84:85], s[2:3] op_sel_hi:[1,0]
	v_rcp_f32_e32 v86, v86
	v_rcp_f32_e32 v87, v87
	v_rcp_f32_e32 v88, v88
	v_rcp_f32_e32 v89, v89
	v_rcp_f32_e32 v82, v82
	v_rcp_f32_e32 v83, v83
	v_rcp_f32_e32 v84, v84
	v_rcp_f32_e32 v85, v85
	v_cvt_pk_bf16_f32 v168, v86, v87
	v_cvt_pk_bf16_f32 v169, v88, v89
	v_cvt_pk_bf16_f32 v170, v82, v83
	v_cvt_pk_bf16_f32 v171, v84, v85
	global_store_dwordx4 v[184:185], v[168:171], off offset:1024
	v_pk_add_f32 v[78:79], v[78:79], v[148:149]
	v_pk_add_f32 v[80:81], v[80:81], v[150:151]
	v_pk_add_f32 v[74:75], v[74:75], v[152:153]
	v_pk_add_f32 v[76:77], v[76:77], v[154:155]
	v_pk_mul_f32 v[78:79], v[78:79], s[20:21] op_sel_hi:[1,0]
	v_pk_mul_f32 v[80:81], v[80:81], s[20:21] op_sel_hi:[1,0]
	v_pk_mul_f32 v[74:75], v[74:75], s[20:21] op_sel_hi:[1,0]
	v_pk_mul_f32 v[76:77], v[76:77], s[20:21] op_sel_hi:[1,0]
	v_exp_f32_e32 v78, v78
	v_exp_f32_e32 v79, v79
	v_exp_f32_e32 v80, v80
	v_exp_f32_e32 v81, v81
	v_exp_f32_e32 v74, v74
	v_exp_f32_e32 v75, v75
	v_exp_f32_e32 v76, v76
	v_exp_f32_e32 v77, v77
	v_pk_add_f32 v[78:79], v[78:79], s[2:3] op_sel_hi:[1,0]
	v_pk_add_f32 v[80:81], v[80:81], s[2:3] op_sel_hi:[1,0]
	v_pk_add_f32 v[74:75], v[74:75], s[2:3] op_sel_hi:[1,0]
	v_pk_add_f32 v[76:77], v[76:77], s[2:3] op_sel_hi:[1,0]
	v_rcp_f32_e32 v78, v78
	v_rcp_f32_e32 v79, v79
	v_rcp_f32_e32 v80, v80
	v_rcp_f32_e32 v81, v81
	v_rcp_f32_e32 v74, v74
	v_rcp_f32_e32 v75, v75
	v_rcp_f32_e32 v76, v76
	v_rcp_f32_e32 v77, v77
	v_cvt_pk_bf16_f32 v172, v78, v79
	v_cvt_pk_bf16_f32 v173, v80, v81
	v_cvt_pk_bf16_f32 v174, v74, v75
	v_cvt_pk_bf16_f32 v175, v76, v77
	global_store_dwordx4 v[184:185], v[172:175], off offset:2048
	v_pk_add_f32 v[70:71], v[70:71], v[156:157]
	v_pk_add_f32 v[72:73], v[72:73], v[158:159]
	v_pk_add_f32 v[66:67], v[66:67], v[160:161]
	v_pk_add_f32 v[68:69], v[68:69], v[162:163]
	v_pk_mul_f32 v[70:71], v[70:71], s[20:21] op_sel_hi:[1,0]
	v_pk_mul_f32 v[72:73], v[72:73], s[20:21] op_sel_hi:[1,0]
	v_pk_mul_f32 v[66:67], v[66:67], s[20:21] op_sel_hi:[1,0]
	v_pk_mul_f32 v[68:69], v[68:69], s[20:21] op_sel_hi:[1,0]
	v_exp_f32_e32 v70, v70
	v_exp_f32_e32 v71, v71
	v_exp_f32_e32 v72, v72
	v_exp_f32_e32 v73, v73
	v_exp_f32_e32 v66, v66
	v_exp_f32_e32 v67, v67
	v_exp_f32_e32 v68, v68
	v_exp_f32_e32 v69, v69
	v_pk_add_f32 v[70:71], v[70:71], s[2:3] op_sel_hi:[1,0]
	v_pk_add_f32 v[72:73], v[72:73], s[2:3] op_sel_hi:[1,0]
	v_pk_add_f32 v[66:67], v[66:67], s[2:3] op_sel_hi:[1,0]
	v_pk_add_f32 v[68:69], v[68:69], s[2:3] op_sel_hi:[1,0]
	v_rcp_f32_e32 v70, v70
	v_rcp_f32_e32 v71, v71
	v_rcp_f32_e32 v72, v72
	v_rcp_f32_e32 v73, v73
	v_rcp_f32_e32 v66, v66
	v_rcp_f32_e32 v67, v67
	v_rcp_f32_e32 v68, v68
	v_rcp_f32_e32 v69, v69
	v_cvt_pk_bf16_f32 v176, v70, v71
	v_cvt_pk_bf16_f32 v177, v72, v73
	v_cvt_pk_bf16_f32 v178, v66, v67
	v_cvt_pk_bf16_f32 v179, v68, v69
	global_store_dwordx4 v[184:185], v[176:179], off offset:3072
	v_pk_add_f32 v[62:63], v[62:63], v[148:149]
	v_pk_add_f32 v[64:65], v[64:65], v[150:151]
	v_pk_add_f32 v[58:59], v[58:59], v[152:153]
	v_pk_add_f32 v[60:61], v[60:61], v[154:155]
	v_pk_mul_f32 v[62:63], v[62:63], s[20:21] op_sel_hi:[1,0]
	v_pk_mul_f32 v[64:65], v[64:65], s[20:21] op_sel_hi:[1,0]
	v_pk_mul_f32 v[58:59], v[58:59], s[20:21] op_sel_hi:[1,0]
	v_pk_mul_f32 v[60:61], v[60:61], s[20:21] op_sel_hi:[1,0]
	v_exp_f32_e32 v62, v62
	v_exp_f32_e32 v63, v63
	v_exp_f32_e32 v64, v64
	v_exp_f32_e32 v65, v65
	v_exp_f32_e32 v58, v58
	v_exp_f32_e32 v59, v59
	v_exp_f32_e32 v60, v60
	v_exp_f32_e32 v61, v61
	v_pk_add_f32 v[62:63], v[62:63], s[2:3] op_sel_hi:[1,0]
	v_pk_add_f32 v[64:65], v[64:65], s[2:3] op_sel_hi:[1,0]
	v_pk_add_f32 v[58:59], v[58:59], s[2:3] op_sel_hi:[1,0]
	v_pk_add_f32 v[60:61], v[60:61], s[2:3] op_sel_hi:[1,0]
	v_rcp_f32_e32 v62, v62
	v_rcp_f32_e32 v63, v63
	v_rcp_f32_e32 v64, v64
	v_rcp_f32_e32 v65, v65
	v_rcp_f32_e32 v58, v58
	v_rcp_f32_e32 v59, v59
	v_rcp_f32_e32 v60, v60
	v_rcp_f32_e32 v61, v61
	v_cvt_pk_bf16_f32 v164, v62, v63
	v_cvt_pk_bf16_f32 v165, v64, v65
	v_cvt_pk_bf16_f32 v166, v58, v59
	v_cvt_pk_bf16_f32 v167, v60, v61
; __device__ __forceinline__ float sigmoidf_(float x) { return fast_rcp(1.0f + fast_exp2(-x * LOG2E)); }
; #define EPI_LOOP_END } if (m == 3) asm volatile("" ::: "memory"); }
; __device__ __forceinline__ u32x4 pack8(f32x4 v0, f32x4 v1) { u32x4 w; w.x = cvt_pk_bf16(v0[0], v0[1]); w.y = cvt_pk_bf16(v0[2], v0[3]); w.z = cvt_pk_bf16(v1[0], v1[1]); w.w = cvt_pk_bf16(v1[2], v1[3]); return w; }
;     __device__ __forceinline__ void operator()(f32x4 (&acc)[2][2][4][2], const Unit& u, int wr, int wc, int fr, int fq) const {
;     ...
;         EPI_LOOP_BEGIN
;             (void)row;
;             const f32x4 b0 = *(const f32x4*)(gb + col), b1 = *(const f32x4*)(gb + col + 4);
; #pragma unroll
;             for (int e = 0; e < 4; ++e) { v0[e] = sigmoidf_(v0[e] + b0[e]); v1[e] = sigmoidf_(v1[e] + b1[e]); }
;             *(u32x4*)(O + gate_frag_off(u.pm, u.pn & 3, wave, ai, m, bj, lane, cbase)) = pack8(v0, v1);
;         EPI_LOOP_END
	global_store_dwordx4 v[186:187], v[164:167], off
	v_pk_add_f32 v[54:55], v[54:55], v[156:157]
	v_pk_add_f32 v[56:57], v[56:57], v[158:159]
	v_pk_add_f32 v[50:51], v[50:51], v[160:161]
	v_pk_add_f32 v[52:53], v[52:53], v[162:163]
	v_pk_mul_f32 v[54:55], v[54:55], s[20:21] op_sel_hi:[1,0]
	v_pk_mul_f32 v[56:57], v[56:57], s[20:21] op_sel_hi:[1,0]
	v_pk_mul_f32 v[50:51], v[50:51], s[20:21] op_sel_hi:[1,0]
	v_pk_mul_f32 v[52:53], v[52:53], s[20:21] op_sel_hi:[1,0]
	v_exp_f32_e32 v54, v54
	v_exp_f32_e32 v55, v55
	v_exp_f32_e32 v56, v56
	v_exp_f32_e32 v57, v57
	v_exp_f32_e32 v50, v50
	v_exp_f32_e32 v51, v51
	v_exp_f32_e32 v52, v52
	v_exp_f32_e32 v53, v53
	v_pk_add_f32 v[54:55], v[54:55], s[2:3] op_sel_hi:[1,0]
	v_pk_add_f32 v[56:57], v[56:57], s[2:3] op_sel_hi:[1,0]
	v_pk_add_f32 v[50:51], v[50:51], s[2:3] op_sel_hi:[1,0]
	v_pk_add_f32 v[52:53], v[52:53], s[2:3] op_sel_hi:[1,0]
	v_rcp_f32_e32 v54, v54
	v_rcp_f32_e32 v55, v55
	v_rcp_f32_e32 v56, v56
	v_rcp_f32_e32 v57, v57
	v_rcp_f32_e32 v50, v50
	v_rcp_f32_e32 v51, v51
	v_rcp_f32_e32 v52, v52
	v_rcp_f32_e32 v53, v53
	v_cvt_pk_bf16_f32 v168, v54, v55
	v_cvt_pk_bf16_f32 v169, v56, v57
	v_cvt_pk_bf16_f32 v170, v50, v51
	v_cvt_pk_bf16_f32 v171, v52, v53
	global_store_dwordx4 v[186:187], v[168:171], off offset:1024
	v_pk_add_f32 v[46:47], v[46:47], v[148:149]
	v_pk_add_f32 v[48:49], v[48:49], v[150:151]
	v_pk_add_f32 v[42:43], v[42:43], v[152:153]
	v_pk_add_f32 v[44:45], v[44:45], v[154:155]
	v_pk_mul_f32 v[46:47], v[46:47], s[20:21] op_sel_hi:[1,0]
	v_pk_mul_f32 v[48:49], v[48:49], s[20:21] op_sel_hi:[1,0]
	v_pk_mul_f32 v[42:43], v[42:43], s[20:21] op_sel_hi:[1,0]
	v_pk_mul_f32 v[44:45], v[44:45], s[20:21] op_sel_hi:[1,0]
	v_exp_f32_e32 v46, v46
	v_exp_f32_e32 v47, v47
	v_exp_f32_e32 v48, v48
	v_exp_f32_e32 v49, v49
	v_exp_f32_e32 v42, v42
	v_exp_f32_e32 v43, v43
	v_exp_f32_e32 v44, v44
	v_exp_f32_e32 v45, v45
	v_pk_add_f32 v[46:47], v[46:47], s[2:3] op_sel_hi:[1,0]
	v_pk_add_f32 v[48:49], v[48:49], s[2:3] op_sel_hi:[1,0]
	v_pk_add_f32 v[42:43], v[42:43], s[2:3] op_sel_hi:[1,0]
	v_pk_add_f32 v[44:45], v[44:45], s[2:3] op_sel_hi:[1,0]
	v_rcp_f32_e32 v46, v46
	v_rcp_f32_e32 v47, v47
	v_rcp_f32_e32 v48, v48
	v_rcp_f32_e32 v49, v49
	v_rcp_f32_e32 v42, v42
	v_rcp_f32_e32 v43, v43
	v_rcp_f32_e32 v44, v44
	v_rcp_f32_e32 v45, v45
	v_cvt_pk_bf16_f32 v172, v46, v47
	v_cvt_pk_bf16_f32 v173, v48, v49
	v_cvt_pk_bf16_f32 v174, v42, v43
	v_cvt_pk_bf16_f32 v175, v44, v45
	global_store_dwordx4 v[186:187], v[172:175], off offset:2048
	v_pk_add_f32 v[38:39], v[38:39], v[156:157]
	v_pk_add_f32 v[40:41], v[40:41], v[158:159]
	v_pk_add_f32 v[34:35], v[34:35], v[160:161]
	v_pk_add_f32 v[36:37], v[36:37], v[162:163]
	v_pk_mul_f32 v[38:39], v[38:39], s[20:21] op_sel_hi:[1,0]
	v_pk_mul_f32 v[40:41], v[40:41], s[20:21] op_sel_hi:[1,0]
	v_pk_mul_f32 v[34:35], v[34:35], s[20:21] op_sel_hi:[1,0]
	v_pk_mul_f32 v[36:37], v[36:37], s[20:21] op_sel_hi:[1,0]
	v_exp_f32_e32 v38, v38
	v_exp_f32_e32 v39, v39
	v_exp_f32_e32 v40, v40
	v_exp_f32_e32 v41, v41
	v_exp_f32_e32 v34, v34
	v_exp_f32_e32 v35, v35
	v_exp_f32_e32 v36, v36
	v_exp_f32_e32 v37, v37
	v_pk_add_f32 v[38:39], v[38:39], s[2:3] op_sel_hi:[1,0]
	v_pk_add_f32 v[40:41], v[40:41], s[2:3] op_sel_hi:[1,0]
	v_pk_add_f32 v[34:35], v[34:35], s[2:3] op_sel_hi:[1,0]
	v_pk_add_f32 v[36:37], v[36:37], s[2:3] op_sel_hi:[1,0]
	v_rcp_f32_e32 v38, v38
	v_rcp_f32_e32 v39, v39
	v_rcp_f32_e32 v40, v40
	v_rcp_f32_e32 v41, v41
	v_rcp_f32_e32 v34, v34
	v_rcp_f32_e32 v35, v35
	v_rcp_f32_e32 v36, v36
	v_rcp_f32_e32 v37, v37
	v_cvt_pk_bf16_f32 v176, v38, v39
	v_cvt_pk_bf16_f32 v177, v40, v41
	v_cvt_pk_bf16_f32 v178, v34, v35
	v_cvt_pk_bf16_f32 v179, v36, v37
	global_store_dwordx4 v[186:187], v[176:179], off offset:3072
	v_pk_add_f32 v[30:31], v[30:31], v[148:149]
	v_pk_add_f32 v[32:33], v[32:33], v[150:151]
	v_pk_add_f32 v[26:27], v[26:27], v[152:153]
	v_pk_add_f32 v[28:29], v[28:29], v[154:155]
	v_pk_mul_f32 v[30:31], v[30:31], s[20:21] op_sel_hi:[1,0]
	v_pk_mul_f32 v[32:33], v[32:33], s[20:21] op_sel_hi:[1,0]
	v_pk_mul_f32 v[26:27], v[26:27], s[20:21] op_sel_hi:[1,0]
	v_pk_mul_f32 v[28:29], v[28:29], s[20:21] op_sel_hi:[1,0]
	v_exp_f32_e32 v30, v30
	v_exp_f32_e32 v31, v31
	v_exp_f32_e32 v32, v32
	v_exp_f32_e32 v33, v33
	v_exp_f32_e32 v26, v26
	v_exp_f32_e32 v27, v27
	v_exp_f32_e32 v28, v28
; __device__ __forceinline__ float sigmoidf_(float x) { return fast_rcp(1.0f + fast_exp2(-x * LOG2E)); }
; #define PG8_BAR __builtin_amdgcn_s_barrier()
; #define PG8_BAR __builtin_amdgcn_s_barrier()
; #define EPI_LOOP_END } if (m == 3) asm volatile("" ::: "memory"); }
; __device__ __forceinline__ u32x4 pack8(f32x4 v0, f32x4 v1) { u32x4 w; w.x = cvt_pk_bf16(v0[0], v0[1]); w.y = cvt_pk_bf16(v0[2], v0[3]); w.z = cvt_pk_bf16(v1[0], v1[1]); w.w = cvt_pk_bf16(v1[2], v1[3]); return w; }
; template <class Epi, class Sched>
; __device__ __forceinline__ void gemm_phase(LAS unsigned char* lds, const Gemm g, const Sched& S, const Epi& E) {
;     ...
;         if (!has_next) break;
; #pragma unroll
;         for (int a = 0; a < 2; ++a)
; #pragma unroll
;             for (int b = 0; b < 2; ++b)
; #pragma unroll
;                 for (int m = 0; m < 4; ++m)
; #pragma unroll
;                     for (int n = 0; n < 2; ++n) acc[a][b][m][n] = (f32x4){0.f, 0.f, 0.f, 0.f};
;         cur = nxt; cA = nA; cB = nB; ++ui;
;         if (wr == 1) PG8_BAR;
;     __device__ __forceinline__ void operator()(f32x4 (&acc)[2][2][4][2], const Unit& u, int wr, int wc, int fr, int fq) const {
;     ...
;         EPI_LOOP_BEGIN
;             (void)row;
;             const f32x4 b0 = *(const f32x4*)(gb + col), b1 = *(const f32x4*)(gb + col + 4);
; #pragma unroll
;             for (int e = 0; e < 4; ++e) { v0[e] = sigmoidf_(v0[e] + b0[e]); v1[e] = sigmoidf_(v1[e] + b1[e]); }
;             *(u32x4*)(O + gate_frag_off(u.pm, u.pn & 3, wave, ai, m, bj, lane, cbase)) = pack8(v0, v1);
;         EPI_LOOP_END
	v_exp_f32_e32 v29, v29
	v_pk_add_f32 v[30:31], v[30:31], s[2:3] op_sel_hi:[1,0]
	v_pk_add_f32 v[32:33], v[32:33], s[2:3] op_sel_hi:[1,0]
	v_pk_add_f32 v[26:27], v[26:27], s[2:3] op_sel_hi:[1,0]
	v_pk_add_f32 v[28:29], v[28:29], s[2:3] op_sel_hi:[1,0]
	v_rcp_f32_e32 v30, v30
	v_rcp_f32_e32 v31, v31
	v_rcp_f32_e32 v32, v32
	v_rcp_f32_e32 v33, v33
	v_rcp_f32_e32 v26, v26
	v_rcp_f32_e32 v27, v27
	v_rcp_f32_e32 v28, v28
	v_rcp_f32_e32 v29, v29
	v_cvt_pk_bf16_f32 v164, v30, v31
	v_cvt_pk_bf16_f32 v165, v32, v33
	v_cvt_pk_bf16_f32 v166, v26, v27
	v_cvt_pk_bf16_f32 v167, v28, v29
	global_store_dwordx4 v[188:189], v[164:167], off
	v_pk_add_f32 v[22:23], v[22:23], v[156:157]
	v_pk_add_f32 v[24:25], v[24:25], v[158:159]
	v_pk_add_f32 v[18:19], v[18:19], v[160:161]
	v_pk_add_f32 v[20:21], v[20:21], v[162:163]
	v_pk_mul_f32 v[22:23], v[22:23], s[20:21] op_sel_hi:[1,0]
	v_pk_mul_f32 v[24:25], v[24:25], s[20:21] op_sel_hi:[1,0]
	v_pk_mul_f32 v[18:19], v[18:19], s[20:21] op_sel_hi:[1,0]
	v_pk_mul_f32 v[20:21], v[20:21], s[20:21] op_sel_hi:[1,0]
	v_exp_f32_e32 v22, v22
	v_exp_f32_e32 v23, v23
	v_exp_f32_e32 v24, v24
	v_exp_f32_e32 v25, v25
	v_exp_f32_e32 v18, v18
	v_exp_f32_e32 v19, v19
	v_exp_f32_e32 v20, v20
	v_exp_f32_e32 v21, v21
	v_pk_add_f32 v[22:23], v[22:23], s[2:3] op_sel_hi:[1,0]
	v_pk_add_f32 v[24:25], v[24:25], s[2:3] op_sel_hi:[1,0]
	v_pk_add_f32 v[18:19], v[18:19], s[2:3] op_sel_hi:[1,0]
	v_pk_add_f32 v[20:21], v[20:21], s[2:3] op_sel_hi:[1,0]
	v_rcp_f32_e32 v22, v22
	v_rcp_f32_e32 v23, v23
	v_rcp_f32_e32 v24, v24
	v_rcp_f32_e32 v25, v25
	v_rcp_f32_e32 v18, v18
	v_rcp_f32_e32 v19, v19
	v_rcp_f32_e32 v20, v20
	v_rcp_f32_e32 v21, v21
	v_cvt_pk_bf16_f32 v168, v22, v23
	v_cvt_pk_bf16_f32 v169, v24, v25
	v_cvt_pk_bf16_f32 v170, v18, v19
	v_cvt_pk_bf16_f32 v171, v20, v21
	global_store_dwordx4 v[188:189], v[168:171], off offset:1024
	v_pk_add_f32 v[14:15], v[14:15], v[148:149]
	v_pk_add_f32 v[16:17], v[16:17], v[150:151]
	v_pk_add_f32 v[10:11], v[10:11], v[152:153]
	v_pk_add_f32 v[12:13], v[12:13], v[154:155]
	v_pk_mul_f32 v[14:15], v[14:15], s[20:21] op_sel_hi:[1,0]
	v_pk_mul_f32 v[16:17], v[16:17], s[20:21] op_sel_hi:[1,0]
	v_pk_mul_f32 v[10:11], v[10:11], s[20:21] op_sel_hi:[1,0]
	v_pk_mul_f32 v[12:13], v[12:13], s[20:21] op_sel_hi:[1,0]
	v_exp_f32_e32 v14, v14
	v_exp_f32_e32 v15, v15
	v_exp_f32_e32 v16, v16
	v_exp_f32_e32 v17, v17
	v_exp_f32_e32 v10, v10
	v_exp_f32_e32 v11, v11
	v_exp_f32_e32 v12, v12
	v_exp_f32_e32 v13, v13
	v_pk_add_f32 v[14:15], v[14:15], s[2:3] op_sel_hi:[1,0]
	v_pk_add_f32 v[16:17], v[16:17], s[2:3] op_sel_hi:[1,0]
	v_pk_add_f32 v[10:11], v[10:11], s[2:3] op_sel_hi:[1,0]
	v_pk_add_f32 v[12:13], v[12:13], s[2:3] op_sel_hi:[1,0]
	v_rcp_f32_e32 v14, v14
	v_rcp_f32_e32 v15, v15
	v_rcp_f32_e32 v16, v16
	v_rcp_f32_e32 v17, v17
	v_rcp_f32_e32 v10, v10
	v_rcp_f32_e32 v11, v11
	v_rcp_f32_e32 v12, v12
	v_rcp_f32_e32 v13, v13
	v_cvt_pk_bf16_f32 v172, v14, v15
	v_cvt_pk_bf16_f32 v173, v16, v17
	v_cvt_pk_bf16_f32 v174, v10, v11
	v_cvt_pk_bf16_f32 v175, v12, v13
	global_store_dwordx4 v[188:189], v[172:175], off offset:2048
	v_pk_add_f32 v[6:7], v[6:7], v[156:157]
	v_pk_add_f32 v[8:9], v[8:9], v[158:159]
	v_pk_add_f32 v[2:3], v[2:3], v[160:161]
	v_pk_add_f32 v[4:5], v[4:5], v[162:163]
	v_pk_mul_f32 v[6:7], v[6:7], s[20:21] op_sel_hi:[1,0]
	v_pk_mul_f32 v[8:9], v[8:9], s[20:21] op_sel_hi:[1,0]
	v_pk_mul_f32 v[2:3], v[2:3], s[20:21] op_sel_hi:[1,0]
	v_pk_mul_f32 v[4:5], v[4:5], s[20:21] op_sel_hi:[1,0]
	v_exp_f32_e32 v6, v6
	v_exp_f32_e32 v7, v7
	v_exp_f32_e32 v8, v8
	v_exp_f32_e32 v9, v9
	v_exp_f32_e32 v2, v2
	v_exp_f32_e32 v3, v3
	v_exp_f32_e32 v4, v4
	v_exp_f32_e32 v5, v5
	v_pk_add_f32 v[6:7], v[6:7], s[2:3] op_sel_hi:[1,0]
	v_pk_add_f32 v[8:9], v[8:9], s[2:3] op_sel_hi:[1,0]
	v_pk_add_f32 v[2:3], v[2:3], s[2:3] op_sel_hi:[1,0]
	v_pk_add_f32 v[4:5], v[4:5], s[2:3] op_sel_hi:[1,0]
	v_rcp_f32_e32 v6, v6
	v_rcp_f32_e32 v7, v7
	v_rcp_f32_e32 v8, v8
	v_rcp_f32_e32 v9, v9
	v_rcp_f32_e32 v2, v2
	v_rcp_f32_e32 v3, v3
	v_rcp_f32_e32 v4, v4
	v_rcp_f32_e32 v5, v5
	v_cvt_pk_bf16_f32 v176, v6, v7
	v_cvt_pk_bf16_f32 v177, v8, v9
	v_cvt_pk_bf16_f32 v178, v2, v3
	v_cvt_pk_bf16_f32 v179, v4, v5
	global_store_dwordx4 v[188:189], v[176:179], off offset:3072
	s_andn2_b64 vcc, exec, s[6:7]
	s_mov_b64 s[2:3], -1
	s_cbranch_vccnz .LBB0_827
	s_branch .LBB0_826

; #define PG8_STAGE(bufoff, gbase, voff) do { _Pragma("unroll") for (int _i = 0; _i < 2; ++_i) \
;         __builtin_amdgcn_global_load_lds((const unsigned*)((const char*)(gbase) + (voff)[_i]), (LAS unsigned*)(lds + (bufoff) + ldsw + _i * 8192), 16, 0, 0); } while (0)
; #define PG8_LDA(dst, b, h) do { _Pragma("unroll") for (int m = 0; m < 4; ++m) _Pragma("unroll") for (int k = 0; k < 2; ++k) dst[m][k] = *(const LAS bf16x8*)(lds + PG8_SA(b, h) + aoff + m * 2048 + k * 1024); } while (0)
; #define PG8_LDB(dst, b, h) do { _Pragma("unroll") for (int n = 0; n < 2; ++n) _Pragma("unroll") for (int k = 0; k < 2; ++k) dst[n][k] = *(const LAS bf16x8*)(lds + PG8_SB(b, h) + boff + n * 2048 + k * 1024); } while (0)
; #define PG8_MMA(ai, bj, At, Bt) do { __builtin_amdgcn_s_setprio(1); _Pragma("unroll") for (int m = 0; m < 4; ++m) _Pragma("unroll") for (int n = 0; n < 2; ++n) _Pragma("unroll") for (int k = 0; k < 2; ++k) \
;         acc[ai][bj][m][n] = __builtin_amdgcn_mfma_f32_16x16x32_bf16(Bt[n][k], At[m][k], acc[ai][bj][m][n], 0, 0, 0); __builtin_amdgcn_s_setprio(0); } while (0)
; #define PG8_WAIT_V(n) asm volatile("s_waitcnt vmcnt(" #n ")" ::: "memory")
; #define PG8_WAIT_L(n) asm volatile("s_waitcnt lgkmcnt(" #n ")" ::: "memory")
; #define PG8_BAR __builtin_amdgcn_s_barrier()
; #define PG8_SCHED __builtin_amdgcn_sched_barrier(0)
; #define PG8_WAIT_V(n) asm volatile("s_waitcnt vmcnt(" #n ")" ::: "memory")
; #define PG8_WAIT_L(n) asm volatile("s_waitcnt lgkmcnt(" #n ")" ::: "memory")
; template <class Epi, class Sched>
; __device__ __forceinline__ void gemm_phase(LAS unsigned char* lds, const Gemm g, const Sched& S, const Epi& E) {
;     ...
;         for (int t = 0; t < nt; t += 2) {
;             const bool last = (t == nt - 2);
;             const char* a1 = cA + (size_t)(t + 1) * kstep;
;             const char* a2 = last ? nA : cA + (size_t)(t + 2) * kstep; const char* b2 = last ? nB : cB + (size_t)(t + 2) * kstep;
;             const char* a3 = a2 + kstep; const char* b3 = b2 + kstep;
;             PG8_LDB(B0, 0, 0); PG8_LDB(B1, 0, 1); PG8_SCHED; PG8_LDA(At, 0, 0); PG8_STAGE(PG8_SA(1, 1), a1 + hstepA, voffA);
;             PG8_WAIT_V(8); PG8_WAIT_L(0); PG8_BAR; PG8_MMA(0, 0, At, B0); PG8_MMA(0, 1, At, B1); PG8_BAR; PG8_SCHED;
;             PG8_LDA(At, 0, 1); PG8_STAGE(PG8_SB(0, 0), b2, voffB); PG8_STAGE(PG8_SB(0, 1), b2 + hstepB, voffB); PG8_STAGE(PG8_SA(0, 0), a2, voffA);
.LBB0_1051:
	s_add_u32 s36, s34, 0xfffc0080
	s_addc_u32 s37, s35, -1
	s_add_i32 s66, 0, 0x10000
	s_cmp_eq_u32 s62, 12
	s_cselect_b32 s39, s23, s37
	s_cselect_b32 s38, s29, s36
	v_add_u32_e32 v146, s66, v148
	s_cselect_b32 s37, s21, s58
	s_cselect_b32 s36, s56, s57
	s_add_i32 s70, 0, 0x14000
	ds_read_b128 v[142:145], v146
	ds_read_b128 v[152:155], v146 offset:1024
	ds_read_b128 v[156:159], v146 offset:2048
	ds_read_b128 v[160:163], v146 offset:3072
	v_add_u32_e32 v146, s70, v148
	ds_read_b128 v[164:167], v146
	ds_read_b128 v[168:171], v146 offset:1024
	ds_read_b128 v[172:175], v146 offset:2048
	ds_read_b128 v[176:179], v146 offset:3072
	v_lshl_add_u64 v[146:147], s[34:35], 0, v[140:141]
	s_add_i32 m0, s31, 0xc000
	ds_read_b128 v[182:185], v150
	ds_read_b128 v[186:189], v150 offset:1024
	ds_read_b128 v[190:193], v150 offset:2048
	ds_read_b128 v[194:197], v150 offset:3072
	ds_read_b128 v[198:201], v150 offset:4096
	ds_read_b128 v[202:205], v150 offset:5120
	ds_read_b128 v[206:209], v150 offset:6144
	ds_read_b128 v[210:213], v150 offset:7168
	global_load_lds_dwordx4 v[146:147], off
	v_lshl_add_u64 v[146:147], s[34:35], 0, v[138:139]
	s_add_i32 m0, s31, 0xe000
	s_nop 0
	global_load_lds_dwordx4 v[146:147], off
	s_waitcnt vmcnt(8)
	s_waitcnt lgkmcnt(0)
	s_barrier
	s_setprio 1
	s_waitcnt lgkmcnt(0)
	v_mfma_f32_16x16x32_bf16 v[126:129], v[142:145], v[182:185], v[126:129]
	v_mfma_f32_16x16x32_bf16 v[122:125], v[156:159], v[182:185], v[122:125]
	v_mfma_f32_16x16x32_bf16 v[110:113], v[142:145], v[190:193], v[110:113]
	v_mfma_f32_16x16x32_bf16 v[106:109], v[156:159], v[190:193], v[106:109]
	v_mfma_f32_16x16x32_bf16 v[94:97], v[142:145], v[198:201], v[94:97]
	v_mfma_f32_16x16x32_bf16 v[90:93], v[156:159], v[198:201], v[90:93]
	v_mfma_f32_16x16x32_bf16 v[78:81], v[142:145], v[206:209], v[78:81]
	v_mfma_f32_16x16x32_bf16 v[74:77], v[156:159], v[206:209], v[74:77]
	v_mfma_f32_16x16x32_bf16 v[126:129], v[152:155], v[186:189], v[126:129]
	v_mfma_f32_16x16x32_bf16 v[122:125], v[160:163], v[186:189], v[122:125]
	v_mfma_f32_16x16x32_bf16 v[110:113], v[152:155], v[194:197], v[110:113]
	v_mfma_f32_16x16x32_bf16 v[106:109], v[160:163], v[194:197], v[106:109]
	v_mfma_f32_16x16x32_bf16 v[94:97], v[152:155], v[202:205], v[94:97]
	v_mfma_f32_16x16x32_bf16 v[90:93], v[160:163], v[202:205], v[90:93]
	v_mfma_f32_16x16x32_bf16 v[78:81], v[152:155], v[210:213], v[78:81]
	v_mfma_f32_16x16x32_bf16 v[74:77], v[160:163], v[210:213], v[74:77]
	s_setprio 0
	s_setprio 1
	v_mfma_f32_16x16x32_bf16 v[118:121], v[164:167], v[182:185], v[118:121]
	v_mfma_f32_16x16x32_bf16 v[114:117], v[172:175], v[182:185], v[114:117]
	v_mfma_f32_16x16x32_bf16 v[102:105], v[164:167], v[190:193], v[102:105]
	v_mfma_f32_16x16x32_bf16 v[98:101], v[172:175], v[190:193], v[98:101]
	v_mfma_f32_16x16x32_bf16 v[86:89], v[164:167], v[198:201], v[86:89]
	v_mfma_f32_16x16x32_bf16 v[82:85], v[172:175], v[198:201], v[82:85]
	v_mfma_f32_16x16x32_bf16 v[70:73], v[164:167], v[206:209], v[70:73]
	v_mfma_f32_16x16x32_bf16 v[66:69], v[172:175], v[206:209], v[66:69]
	v_mfma_f32_16x16x32_bf16 v[118:121], v[168:171], v[186:189], v[118:121]
	v_mfma_f32_16x16x32_bf16 v[114:117], v[176:179], v[186:189], v[114:117]
	v_mfma_f32_16x16x32_bf16 v[102:105], v[168:171], v[194:197], v[102:105]
	v_mfma_f32_16x16x32_bf16 v[98:101], v[176:179], v[194:197], v[98:101]
	v_mfma_f32_16x16x32_bf16 v[86:89], v[168:171], v[202:205], v[86:89]
	v_mfma_f32_16x16x32_bf16 v[82:85], v[176:179], v[202:205], v[82:85]
	v_mfma_f32_16x16x32_bf16 v[70:73], v[168:171], v[210:213], v[70:73]
	v_mfma_f32_16x16x32_bf16 v[66:69], v[176:179], v[210:213], v[66:69]
	s_setprio 0
	s_barrier
	s_add_i32 s66, s66, s44
	v_lshl_add_u64 v[146:147], s[36:37], 0, v[132:133]
	s_mov_b32 m0, s66
	ds_read_b128 v[182:185], v150 offset:16384
	ds_read_b128 v[186:189], v150 offset:17408
	ds_read_b128 v[190:193], v150 offset:18432
	ds_read_b128 v[194:197], v150 offset:19456
	ds_read_b128 v[198:201], v150 offset:20480
	ds_read_b128 v[202:205], v150 offset:21504
	ds_read_b128 v[206:209], v150 offset:22528
	ds_read_b128 v[210:213], v150 offset:23552
	global_load_lds_dwordx4 v[146:147], off
	s_add_i32 m0, s66, 0x2000
	s_add_u32 s66, s36, 0x40000
	v_lshl_add_u64 v[214:215], s[36:37], 0, v[136:137]
	s_addc_u32 s67, s37, 0
	s_add_i32 s70, s70, s44
	global_load_lds_dwordx4 v[214:215], off
	v_lshl_add_u64 v[226:227], s[66:67], 0, v[132:133]
	s_mov_b32 m0, s70
	v_lshl_add_u64 v[228:229], s[38:39], 0, v[134:135]
	global_load_lds_dwordx4 v[226:227], off
	v_lshl_add_u64 v[226:227], s[66:67], 0, v[136:137]
	s_add_i32 m0, s70, 0x2000
	s_nop 0
	global_load_lds_dwordx4 v[226:227], off
	v_lshl_add_u64 v[226:227], s[38:39], 0, v[130:131]
	s_mov_b32 m0, s31
	s_nop 0
	global_load_lds_dwordx4 v[226:227], off
	s_mov_b32 m0, s48
	s_nop 0
	global_load_lds_dwordx4 v[228:229], off
	s_waitcnt vmcnt(8)
	s_waitcnt lgkmcnt(0)
	s_barrier
; #define PG8_STAGE(bufoff, gbase, voff) do { _Pragma("unroll") for (int _i = 0; _i < 2; ++_i) \
;         __builtin_amdgcn_global_load_lds((const unsigned*)((const char*)(gbase) + (voff)[_i]), (LAS unsigned*)(lds + (bufoff) + ldsw + _i * 8192), 16, 0, 0); } while (0)
; #define PG8_LDA(dst, b, h) do { _Pragma("unroll") for (int m = 0; m < 4; ++m) _Pragma("unroll") for (int k = 0; k < 2; ++k) dst[m][k] = *(const LAS bf16x8*)(lds + PG8_SA(b, h) + aoff + m * 2048 + k * 1024); } while (0)
; #define PG8_LDB(dst, b, h) do { _Pragma("unroll") for (int n = 0; n < 2; ++n) _Pragma("unroll") for (int k = 0; k < 2; ++k) dst[n][k] = *(const LAS bf16x8*)(lds + PG8_SB(b, h) + boff + n * 2048 + k * 1024); } while (0)
; #define PG8_MMA(ai, bj, At, Bt) do { __builtin_amdgcn_s_setprio(1); _Pragma("unroll") for (int m = 0; m < 4; ++m) _Pragma("unroll") for (int n = 0; n < 2; ++n) _Pragma("unroll") for (int k = 0; k < 2; ++k) \
;         acc[ai][bj][m][n] = __builtin_amdgcn_mfma_f32_16x16x32_bf16(Bt[n][k], At[m][k], acc[ai][bj][m][n], 0, 0, 0); __builtin_amdgcn_s_setprio(0); } while (0)
; #define PG8_WAIT_V(n) asm volatile("s_waitcnt vmcnt(" #n ")" ::: "memory")
; #define PG8_WAIT_L(n) asm volatile("s_waitcnt lgkmcnt(" #n ")" ::: "memory")
; #define PG8_BAR __builtin_amdgcn_s_barrier()
; #define PG8_SCHED __builtin_amdgcn_sched_barrier(0)
; #define PG8_STAGE(bufoff, gbase, voff) do { _Pragma("unroll") for (int _i = 0; _i < 2; ++_i) \
;         __builtin_amdgcn_global_load_lds((const unsigned*)((const char*)(gbase) + (voff)[_i]), (LAS unsigned*)(lds + (bufoff) + ldsw + _i * 8192), 16, 0, 0); } while (0)
; #define PG8_LDA(dst, b, h) do { _Pragma("unroll") for (int m = 0; m < 4; ++m) _Pragma("unroll") for (int k = 0; k < 2; ++k) dst[m][k] = *(const LAS bf16x8*)(lds + PG8_SA(b, h) + aoff + m * 2048 + k * 1024); } while (0)
; #define PG8_BAR __builtin_amdgcn_s_barrier()
; template <class Epi, class Sched>
; __device__ __forceinline__ void gemm_phase(LAS unsigned char* lds, const Gemm g, const Sched& S, const Epi& E) {
;     ...
;             PG8_WAIT_V(8); PG8_WAIT_L(0); PG8_BAR; PG8_MMA(1, 0, At, B0); PG8_MMA(1, 1, At, B1); PG8_BAR; PG8_SCHED;
;             PG8_LDB(B0, 1, 0); PG8_LDB(B1, 1, 1); PG8_SCHED; PG8_LDA(At, 1, 0); PG8_STAGE(PG8_SA(0, 1), a2 + hstepA, voffA);
;             PG8_WAIT_V(8); PG8_WAIT_L(0); PG8_BAR; PG8_MMA(0, 0, At, B0); PG8_MMA(0, 1, At, B1); PG8_BAR; PG8_SCHED;
	s_setprio 1
	s_waitcnt lgkmcnt(0)
	v_mfma_f32_16x16x32_bf16 v[62:65], v[142:145], v[182:185], v[62:65]
	v_mfma_f32_16x16x32_bf16 v[58:61], v[156:159], v[182:185], v[58:61]
	v_mfma_f32_16x16x32_bf16 v[46:49], v[142:145], v[190:193], v[46:49]
	v_mfma_f32_16x16x32_bf16 v[42:45], v[156:159], v[190:193], v[42:45]
	v_mfma_f32_16x16x32_bf16 v[30:33], v[142:145], v[198:201], v[30:33]
	v_mfma_f32_16x16x32_bf16 v[26:29], v[156:159], v[198:201], v[26:29]
	v_mfma_f32_16x16x32_bf16 v[14:17], v[142:145], v[206:209], v[14:17]
	v_mfma_f32_16x16x32_bf16 v[10:13], v[156:159], v[206:209], v[10:13]
	v_mfma_f32_16x16x32_bf16 v[62:65], v[152:155], v[186:189], v[62:65]
	v_mfma_f32_16x16x32_bf16 v[58:61], v[160:163], v[186:189], v[58:61]
	v_mfma_f32_16x16x32_bf16 v[46:49], v[152:155], v[194:197], v[46:49]
	v_mfma_f32_16x16x32_bf16 v[42:45], v[160:163], v[194:197], v[42:45]
	v_mfma_f32_16x16x32_bf16 v[30:33], v[152:155], v[202:205], v[30:33]
	v_mfma_f32_16x16x32_bf16 v[26:29], v[160:163], v[202:205], v[26:29]
	v_mfma_f32_16x16x32_bf16 v[14:17], v[152:155], v[210:213], v[14:17]
	v_mfma_f32_16x16x32_bf16 v[10:13], v[160:163], v[210:213], v[10:13]
	s_setprio 0
	s_setprio 1
	v_mfma_f32_16x16x32_bf16 v[54:57], v[164:167], v[182:185], v[54:57]
	v_mfma_f32_16x16x32_bf16 v[50:53], v[172:175], v[182:185], v[50:53]
	v_mfma_f32_16x16x32_bf16 v[38:41], v[164:167], v[190:193], v[38:41]
	v_mfma_f32_16x16x32_bf16 v[34:37], v[172:175], v[190:193], v[34:37]
	v_mfma_f32_16x16x32_bf16 v[22:25], v[164:167], v[198:201], v[22:25]
	v_mfma_f32_16x16x32_bf16 v[18:21], v[172:175], v[198:201], v[18:21]
	v_mfma_f32_16x16x32_bf16 v[6:9], v[164:167], v[206:209], v[6:9]
	v_mfma_f32_16x16x32_bf16 v[2:5], v[172:175], v[206:209], v[2:5]
	v_mfma_f32_16x16x32_bf16 v[54:57], v[168:171], v[186:189], v[54:57]
	v_mfma_f32_16x16x32_bf16 v[50:53], v[176:179], v[186:189], v[50:53]
	v_mfma_f32_16x16x32_bf16 v[38:41], v[168:171], v[194:197], v[38:41]
	v_mfma_f32_16x16x32_bf16 v[34:37], v[176:179], v[194:197], v[34:37]
	v_mfma_f32_16x16x32_bf16 v[22:25], v[168:171], v[202:205], v[22:25]
	v_mfma_f32_16x16x32_bf16 v[18:21], v[176:179], v[202:205], v[18:21]
	v_mfma_f32_16x16x32_bf16 v[6:9], v[168:171], v[210:213], v[6:9]
	v_mfma_f32_16x16x32_bf16 v[2:5], v[176:179], v[210:213], v[2:5]
	s_setprio 0
	s_barrier
	s_add_i32 s66, 0, 0x18000
	v_add_u32_e32 v151, s66, v148
	s_add_i32 s67, 0, 0x1c000
	ds_read_b128 v[142:145], v151
	ds_read_b128 v[152:155], v151 offset:1024
	ds_read_b128 v[156:159], v151 offset:2048
	ds_read_b128 v[160:163], v151 offset:3072
	v_add_u32_e32 v151, s67, v148
	ds_read_b128 v[164:167], v151
	ds_read_b128 v[168:171], v151 offset:1024
	ds_read_b128 v[172:175], v151 offset:2048
	ds_read_b128 v[176:179], v151 offset:3072
	s_add_u32 s38, s38, 0x40000
	s_addc_u32 s39, s39, 0
	s_mov_b32 m0, s49
	v_lshl_add_u64 v[232:233], s[38:39], 0, v[130:131]
	ds_read_b128 v[182:185], v150 offset:32768
	ds_read_b128 v[186:189], v150 offset:33792
	ds_read_b128 v[190:193], v150 offset:34816
	ds_read_b128 v[194:197], v150 offset:35840
	ds_read_b128 v[198:201], v150 offset:36864
	ds_read_b128 v[202:205], v150 offset:37888
	ds_read_b128 v[206:209], v150 offset:38912
	ds_read_b128 v[210:213], v150 offset:39936
	global_load_lds_dwordx4 v[232:233], off
	v_lshl_add_u64 v[232:233], s[38:39], 0, v[134:135]
	s_mov_b32 m0, s50
	s_nop 0
	global_load_lds_dwordx4 v[232:233], off
	s_waitcnt vmcnt(8)
	s_waitcnt lgkmcnt(0)
	s_barrier
	s_setprio 1
	s_waitcnt lgkmcnt(0)
	v_mfma_f32_16x16x32_bf16 v[126:129], v[142:145], v[182:185], v[126:129]
	v_mfma_f32_16x16x32_bf16 v[122:125], v[156:159], v[182:185], v[122:125]
	v_mfma_f32_16x16x32_bf16 v[110:113], v[142:145], v[190:193], v[110:113]
	v_mfma_f32_16x16x32_bf16 v[106:109], v[156:159], v[190:193], v[106:109]
	v_mfma_f32_16x16x32_bf16 v[94:97], v[142:145], v[198:201], v[94:97]
	v_mfma_f32_16x16x32_bf16 v[90:93], v[156:159], v[198:201], v[90:93]
	v_mfma_f32_16x16x32_bf16 v[78:81], v[142:145], v[206:209], v[78:81]
	v_mfma_f32_16x16x32_bf16 v[74:77], v[156:159], v[206:209], v[74:77]
	v_mfma_f32_16x16x32_bf16 v[126:129], v[152:155], v[186:189], v[126:129]
	v_mfma_f32_16x16x32_bf16 v[122:125], v[160:163], v[186:189], v[122:125]
	v_mfma_f32_16x16x32_bf16 v[110:113], v[152:155], v[194:197], v[110:113]
	v_mfma_f32_16x16x32_bf16 v[106:109], v[160:163], v[194:197], v[106:109]
	v_mfma_f32_16x16x32_bf16 v[94:97], v[152:155], v[202:205], v[94:97]
	v_mfma_f32_16x16x32_bf16 v[90:93], v[160:163], v[202:205], v[90:93]
	v_mfma_f32_16x16x32_bf16 v[78:81], v[152:155], v[210:213], v[78:81]
	v_mfma_f32_16x16x32_bf16 v[74:77], v[160:163], v[210:213], v[74:77]
	s_setprio 0
	s_setprio 1
	v_mfma_f32_16x16x32_bf16 v[118:121], v[164:167], v[182:185], v[118:121]
	v_mfma_f32_16x16x32_bf16 v[114:117], v[172:175], v[182:185], v[114:117]
	v_mfma_f32_16x16x32_bf16 v[102:105], v[164:167], v[190:193], v[102:105]
	v_mfma_f32_16x16x32_bf16 v[98:101], v[172:175], v[190:193], v[98:101]
	v_mfma_f32_16x16x32_bf16 v[86:89], v[164:167], v[198:201], v[86:89]
	v_mfma_f32_16x16x32_bf16 v[82:85], v[172:175], v[198:201], v[82:85]
	v_mfma_f32_16x16x32_bf16 v[70:73], v[164:167], v[206:209], v[70:73]
	v_mfma_f32_16x16x32_bf16 v[66:69], v[172:175], v[206:209], v[66:69]
	v_mfma_f32_16x16x32_bf16 v[118:121], v[168:171], v[186:189], v[118:121]
	v_mfma_f32_16x16x32_bf16 v[114:117], v[176:179], v[186:189], v[114:117]
	v_mfma_f32_16x16x32_bf16 v[102:105], v[168:171], v[194:197], v[102:105]
	v_mfma_f32_16x16x32_bf16 v[98:101], v[176:179], v[194:197], v[98:101]
	v_mfma_f32_16x16x32_bf16 v[86:89], v[168:171], v[202:205], v[86:89]
	v_mfma_f32_16x16x32_bf16 v[82:85], v[176:179], v[202:205], v[82:85]
	v_mfma_f32_16x16x32_bf16 v[70:73], v[168:171], v[210:213], v[70:73]
	v_mfma_f32_16x16x32_bf16 v[66:69], v[176:179], v[210:213], v[66:69]
	s_setprio 0
	s_barrier
; #define PG8_STAGE(bufoff, gbase, voff) do { _Pragma("unroll") for (int _i = 0; _i < 2; ++_i) \
;         __builtin_amdgcn_global_load_lds((const unsigned*)((const char*)(gbase) + (voff)[_i]), (LAS unsigned*)(lds + (bufoff) + ldsw + _i * 8192), 16, 0, 0); } while (0)
; #define PG8_LDA(dst, b, h) do { _Pragma("unroll") for (int m = 0; m < 4; ++m) _Pragma("unroll") for (int k = 0; k < 2; ++k) dst[m][k] = *(const LAS bf16x8*)(lds + PG8_SA(b, h) + aoff + m * 2048 + k * 1024); } while (0)
; #define PG8_MMA(ai, bj, At, Bt) do { __builtin_amdgcn_s_setprio(1); _Pragma("unroll") for (int m = 0; m < 4; ++m) _Pragma("unroll") for (int n = 0; n < 2; ++n) _Pragma("unroll") for (int k = 0; k < 2; ++k) \
;         acc[ai][bj][m][n] = __builtin_amdgcn_mfma_f32_16x16x32_bf16(Bt[n][k], At[m][k], acc[ai][bj][m][n], 0, 0, 0); __builtin_amdgcn_s_setprio(0); } while (0)
; #define PG8_WAIT_V(n) asm volatile("s_waitcnt vmcnt(" #n ")" ::: "memory")
; #define PG8_WAIT_L(n) asm volatile("s_waitcnt lgkmcnt(" #n ")" ::: "memory")
; #define PG8_BAR __builtin_amdgcn_s_barrier()
; #define PG8_SCHED __builtin_amdgcn_sched_barrier(0)
; #define PG8_STAGE(bufoff, gbase, voff) do { _Pragma("unroll") for (int _i = 0; _i < 2; ++_i) \
;         __builtin_amdgcn_global_load_lds((const unsigned*)((const char*)(gbase) + (voff)[_i]), (LAS unsigned*)(lds + (bufoff) + ldsw + _i * 8192), 16, 0, 0); } while (0)
; #define PG8_LDA(dst, b, h) do { _Pragma("unroll") for (int m = 0; m < 4; ++m) _Pragma("unroll") for (int k = 0; k < 2; ++k) dst[m][k] = *(const LAS bf16x8*)(lds + PG8_SA(b, h) + aoff + m * 2048 + k * 1024); } while (0)
; #define PG8_WAIT_V(n) asm volatile("s_waitcnt vmcnt(" #n ")" ::: "memory")
; #define PG8_WAIT_L(n) asm volatile("s_waitcnt lgkmcnt(" #n ")" ::: "memory")
; #define PG8_BAR __builtin_amdgcn_s_barrier()
; #define PG8_SCHED __builtin_amdgcn_sched_barrier(0)
; template <class Epi, class Sched>
; __device__ __forceinline__ void gemm_phase(LAS unsigned char* lds, const Gemm g, const Sched& S, const Epi& E) {
;     ...
;             PG8_LDA(At, 1, 1); PG8_STAGE(PG8_SB(1, 0), b3, voffB); PG8_STAGE(PG8_SB(1, 1), b3 + hstepB, voffB); PG8_STAGE(PG8_SA(1, 0), a3, voffA);
;             PG8_WAIT_V(8); PG8_WAIT_L(0); PG8_BAR; PG8_MMA(1, 0, At, B0); PG8_MMA(1, 1, At, B1); PG8_BAR; PG8_SCHED;
;         }
;         if (wr == 0) PG8_BAR;
	s_add_i32 s38, s66, s44
	v_lshl_add_u64 v[146:147], v[146:147], 0, s[86:87]
	s_mov_b32 m0, s38
	ds_read_b128 v[182:185], v150 offset:49152
	ds_read_b128 v[186:189], v150 offset:50176
	ds_read_b128 v[190:193], v150 offset:51200
	ds_read_b128 v[194:197], v150 offset:52224
	ds_read_b128 v[198:201], v150 offset:53248
	ds_read_b128 v[202:205], v150 offset:54272
	ds_read_b128 v[206:209], v150 offset:55296
	ds_read_b128 v[210:213], v150 offset:56320
	global_load_lds_dwordx4 v[146:147], off
	s_add_i32 m0, s38, 0x2000
	s_add_u32 s36, s36, 0x40080
	v_lshl_add_u64 v[146:147], v[214:215], 0, s[86:87]
	s_addc_u32 s37, s37, 0
	s_add_i32 s38, s67, s44
	global_load_lds_dwordx4 v[146:147], off
	v_lshl_add_u64 v[146:147], s[36:37], 0, v[132:133]
	s_mov_b32 m0, s38
	s_nop 0
	global_load_lds_dwordx4 v[146:147], off
	v_lshl_add_u64 v[146:147], s[36:37], 0, v[136:137]
	s_add_i32 m0, s38, 0x2000
	s_nop 0
	global_load_lds_dwordx4 v[146:147], off
	v_lshl_add_u64 v[146:147], v[226:227], 0, s[86:87]
	s_mov_b32 m0, s51
	s_nop 0
	global_load_lds_dwordx4 v[146:147], off
	v_lshl_add_u64 v[146:147], v[228:229], 0, s[86:87]
	s_mov_b32 m0, s52
	s_nop 0
	global_load_lds_dwordx4 v[146:147], off
	s_waitcnt vmcnt(8)
	s_waitcnt lgkmcnt(0)
	s_barrier
	s_setprio 1
	s_waitcnt lgkmcnt(0)
	v_mfma_f32_16x16x32_bf16 v[62:65], v[142:145], v[182:185], v[62:65]
	v_mfma_f32_16x16x32_bf16 v[58:61], v[156:159], v[182:185], v[58:61]
	v_mfma_f32_16x16x32_bf16 v[46:49], v[142:145], v[190:193], v[46:49]
	v_mfma_f32_16x16x32_bf16 v[42:45], v[156:159], v[190:193], v[42:45]
	v_mfma_f32_16x16x32_bf16 v[30:33], v[142:145], v[198:201], v[30:33]
	v_mfma_f32_16x16x32_bf16 v[26:29], v[156:159], v[198:201], v[26:29]
	v_mfma_f32_16x16x32_bf16 v[14:17], v[142:145], v[206:209], v[14:17]
	v_mfma_f32_16x16x32_bf16 v[10:13], v[156:159], v[206:209], v[10:13]
	v_mfma_f32_16x16x32_bf16 v[62:65], v[152:155], v[186:189], v[62:65]
	v_mfma_f32_16x16x32_bf16 v[58:61], v[160:163], v[186:189], v[58:61]
	v_mfma_f32_16x16x32_bf16 v[46:49], v[152:155], v[194:197], v[46:49]
	v_mfma_f32_16x16x32_bf16 v[42:45], v[160:163], v[194:197], v[42:45]
	v_mfma_f32_16x16x32_bf16 v[30:33], v[152:155], v[202:205], v[30:33]
	v_mfma_f32_16x16x32_bf16 v[26:29], v[160:163], v[202:205], v[26:29]
	v_mfma_f32_16x16x32_bf16 v[14:17], v[152:155], v[210:213], v[14:17]
	v_mfma_f32_16x16x32_bf16 v[10:13], v[160:163], v[210:213], v[10:13]
	s_setprio 0
	s_setprio 1
	v_mfma_f32_16x16x32_bf16 v[54:57], v[164:167], v[182:185], v[54:57]
	v_mfma_f32_16x16x32_bf16 v[50:53], v[172:175], v[182:185], v[50:53]
	v_mfma_f32_16x16x32_bf16 v[38:41], v[164:167], v[190:193], v[38:41]
	v_mfma_f32_16x16x32_bf16 v[34:37], v[172:175], v[190:193], v[34:37]
	v_mfma_f32_16x16x32_bf16 v[22:25], v[164:167], v[198:201], v[22:25]
	v_mfma_f32_16x16x32_bf16 v[18:21], v[172:175], v[198:201], v[18:21]
	v_mfma_f32_16x16x32_bf16 v[6:9], v[164:167], v[206:209], v[6:9]
	v_mfma_f32_16x16x32_bf16 v[2:5], v[172:175], v[206:209], v[2:5]
	v_mfma_f32_16x16x32_bf16 v[54:57], v[168:171], v[186:189], v[54:57]
	v_mfma_f32_16x16x32_bf16 v[50:53], v[176:179], v[186:189], v[50:53]
	v_mfma_f32_16x16x32_bf16 v[38:41], v[168:171], v[194:197], v[38:41]
	v_mfma_f32_16x16x32_bf16 v[34:37], v[176:179], v[194:197], v[34:37]
	v_mfma_f32_16x16x32_bf16 v[22:25], v[168:171], v[202:205], v[22:25]
	v_mfma_f32_16x16x32_bf16 v[18:21], v[176:179], v[202:205], v[18:21]
	v_mfma_f32_16x16x32_bf16 v[6:9], v[168:171], v[210:213], v[6:9]
	v_mfma_f32_16x16x32_bf16 v[2:5], v[176:179], v[210:213], v[2:5]
	s_setprio 0
	s_barrier
	s_add_i32 s62, s62, 2
	s_add_u32 s57, s57, 0x100
	s_addc_u32 s58, s58, 0
	s_add_u32 s34, s34, 0x100
	s_addc_u32 s35, s35, 0
	s_cmp_gt_u32 s62, 13
	s_cbranch_scc0 .LBB0_1051
	s_and_b64 vcc, exec, s[18:19]
	s_andn2_b64 vcc, vcc, s[8:9]
	s_cbranch_vccz .LBB0_1054
	s_barrier

; #define PG8_BAR __builtin_amdgcn_s_barrier()
; #define PG8_BAR __builtin_amdgcn_s_barrier()
; template <class Epi, class Sched>
; __device__ __forceinline__ void gemm_phase(LAS unsigned char* lds, const Gemm g, const Sched& S, const Epi& E) {
;     ...
;         if (!has_next) break;
; #pragma unroll
;         for (int a = 0; a < 2; ++a)
; #pragma unroll
;             for (int b = 0; b < 2; ++b)
; #pragma unroll
;                 for (int m = 0; m < 4; ++m)
; #pragma unroll
;                     for (int n = 0; n < 2; ++n) acc[a][b][m][n] = (f32x4){0.f, 0.f, 0.f, 0.f};
;         cur = nxt; cA = nA; cB = nB; ++ui;
;         if (wr == 1) PG8_BAR;
.LBB0_1070:
	s_or_b64 exec, exec, s[28:29]
	s_andn2_b64 vcc, exec, s[8:9]
	s_mov_b64 s[8:9], -1
	s_cbranch_vccnz .LBB0_1043
	s_branch .LBB0_1042

; #define PG8_STAGE(bufoff, gbase, voff) do { _Pragma("unroll") for (int _i = 0; _i < 2; ++_i) \
;         __builtin_amdgcn_global_load_lds((const unsigned*)((const char*)(gbase) + (voff)[_i]), (LAS unsigned*)(lds + (bufoff) + ldsw + _i * 8192), 16, 0, 0); } while (0)
; #define PG8_LDA(dst, b, h) do { _Pragma("unroll") for (int m = 0; m < 4; ++m) _Pragma("unroll") for (int k = 0; k < 2; ++k) dst[m][k] = *(const LAS bf16x8*)(lds + PG8_SA(b, h) + aoff + m * 2048 + k * 1024); } while (0)
; #define PG8_LDB(dst, b, h) do { _Pragma("unroll") for (int n = 0; n < 2; ++n) _Pragma("unroll") for (int k = 0; k < 2; ++k) dst[n][k] = *(const LAS bf16x8*)(lds + PG8_SB(b, h) + boff + n * 2048 + k * 1024); } while (0)
; #define PG8_MMA(ai, bj, At, Bt) do { __builtin_amdgcn_s_setprio(1); _Pragma("unroll") for (int m = 0; m < 4; ++m) _Pragma("unroll") for (int n = 0; n < 2; ++n) _Pragma("unroll") for (int k = 0; k < 2; ++k) \
;         acc[ai][bj][m][n] = __builtin_amdgcn_mfma_f32_16x16x32_bf16(Bt[n][k], At[m][k], acc[ai][bj][m][n], 0, 0, 0); __builtin_amdgcn_s_setprio(0); } while (0)
; #define PG8_WAIT_V(n) asm volatile("s_waitcnt vmcnt(" #n ")" ::: "memory")
; #define PG8_WAIT_L(n) asm volatile("s_waitcnt lgkmcnt(" #n ")" ::: "memory")
; #define PG8_BAR __builtin_amdgcn_s_barrier()
; #define PG8_SCHED __builtin_amdgcn_sched_barrier(0)
; #define PG8_WAIT_V(n) asm volatile("s_waitcnt vmcnt(" #n ")" ::: "memory")
; #define PG8_WAIT_L(n) asm volatile("s_waitcnt lgkmcnt(" #n ")" ::: "memory")
; template <class Epi, class Sched>
; __device__ __forceinline__ void gemm_phase(LAS unsigned char* lds, const Gemm g, const Sched& S, const Epi& E) {
;     ...
;         for (int t = 0; t < nt; t += 2) {
;             const bool last = (t == nt - 2);
;             const char* a1 = cA + (size_t)(t + 1) * kstep;
;             const char* a2 = last ? nA : cA + (size_t)(t + 2) * kstep; const char* b2 = last ? nB : cB + (size_t)(t + 2) * kstep;
;             const char* a3 = a2 + kstep; const char* b3 = b2 + kstep;
;             PG8_LDB(B0, 0, 0); PG8_LDB(B1, 0, 1); PG8_SCHED; PG8_LDA(At, 0, 0); PG8_STAGE(PG8_SA(1, 1), a1 + hstepA, voffA);
;             PG8_WAIT_V(8); PG8_WAIT_L(0); PG8_BAR; PG8_MMA(0, 0, At, B0); PG8_MMA(0, 1, At, B1); PG8_BAR; PG8_SCHED;
;             PG8_LDA(At, 0, 1); PG8_STAGE(PG8_SB(0, 0), b2, voffB); PG8_STAGE(PG8_SB(0, 1), b2 + hstepB, voffB); PG8_STAGE(PG8_SA(0, 0), a2, voffA);
.LBB0_1131:
	s_add_u32 s54, s52, 0xfffc0080
	s_addc_u32 s55, s53, -1
	s_add_i32 s91, 0, 0x10000
	s_cmp_eq_u32 s90, 12
	s_cselect_b32 s57, s41, s55
	s_cselect_b32 s56, s49, s54
	s_cselect_b32 s55, s37, s76
	s_cselect_b32 s54, s51, s67
	s_add_i32 s94, 0, 0x14000
	v_add_u32_e32 v126, s91, v231
	v_add_u32_e32 v142, s94, v231
	ds_read_b128 v[114:117], v126
	ds_read_b128 v[118:121], v126 offset:1024
	ds_read_b128 v[122:125], v126 offset:2048
	ds_read_b128 v[126:129], v126 offset:3072
	ds_read_b128 v[130:133], v142
	ds_read_b128 v[134:137], v142 offset:1024
	ds_read_b128 v[138:141], v142 offset:2048
	ds_read_b128 v[142:145], v142 offset:3072
	v_lshl_add_u64 v[210:211], s[52:53], 0, v[174:175]
	s_add_i32 m0, s78, 0xc000
	ds_read_b128 v[176:179], v233
	ds_read_b128 v[182:185], v233 offset:1024
	ds_read_b128 v[186:189], v233 offset:2048
	ds_read_b128 v[190:193], v233 offset:3072
	ds_read_b128 v[194:197], v233 offset:4096
	ds_read_b128 v[198:201], v233 offset:5120
	ds_read_b128 v[202:205], v233 offset:6144
	ds_read_b128 v[206:209], v233 offset:7168
	global_load_lds_dwordx4 v[210:211], off
	v_lshl_add_u64 v[210:211], s[52:53], 0, v[172:173]
	s_add_i32 m0, s78, 0xe000
	s_nop 0
	global_load_lds_dwordx4 v[210:211], off
	s_waitcnt vmcnt(8)
	s_waitcnt lgkmcnt(0)
	s_barrier
	s_setprio 1
	s_waitcnt lgkmcnt(0)
	v_mfma_f32_16x16x32_bf16 v[158:161], v[114:117], v[176:179], v[158:161]
	v_mfma_f32_16x16x32_bf16 v[62:65], v[122:125], v[176:179], v[62:65]
	v_mfma_f32_16x16x32_bf16 v[150:153], v[114:117], v[186:189], v[150:153]
	v_mfma_f32_16x16x32_bf16 v[54:57], v[122:125], v[186:189], v[54:57]
	v_mfma_f32_16x16x32_bf16 v[110:113], v[114:117], v[194:197], v[110:113]
	v_mfma_f32_16x16x32_bf16 v[46:49], v[122:125], v[194:197], v[46:49]
	v_mfma_f32_16x16x32_bf16 v[102:105], v[114:117], v[202:205], v[102:105]
	v_mfma_f32_16x16x32_bf16 v[38:41], v[122:125], v[202:205], v[38:41]
	v_mfma_f32_16x16x32_bf16 v[158:161], v[118:121], v[182:185], v[158:161]
	v_mfma_f32_16x16x32_bf16 v[62:65], v[126:129], v[182:185], v[62:65]
	v_mfma_f32_16x16x32_bf16 v[150:153], v[118:121], v[190:193], v[150:153]
	v_mfma_f32_16x16x32_bf16 v[54:57], v[126:129], v[190:193], v[54:57]
	v_mfma_f32_16x16x32_bf16 v[110:113], v[118:121], v[198:201], v[110:113]
	v_mfma_f32_16x16x32_bf16 v[46:49], v[126:129], v[198:201], v[46:49]
	v_mfma_f32_16x16x32_bf16 v[102:105], v[118:121], v[206:209], v[102:105]
	v_mfma_f32_16x16x32_bf16 v[38:41], v[126:129], v[206:209], v[38:41]
	s_setprio 0
	s_setprio 1
	v_mfma_f32_16x16x32_bf16 v[154:157], v[130:133], v[176:179], v[154:157]
	v_mfma_f32_16x16x32_bf16 v[58:61], v[138:141], v[176:179], v[58:61]
	v_mfma_f32_16x16x32_bf16 v[146:149], v[130:133], v[186:189], v[146:149]
	v_mfma_f32_16x16x32_bf16 v[50:53], v[138:141], v[186:189], v[50:53]
	v_mfma_f32_16x16x32_bf16 v[106:109], v[130:133], v[194:197], v[106:109]
	v_mfma_f32_16x16x32_bf16 v[42:45], v[138:141], v[194:197], v[42:45]
	v_mfma_f32_16x16x32_bf16 v[98:101], v[130:133], v[202:205], v[98:101]
	v_mfma_f32_16x16x32_bf16 v[34:37], v[138:141], v[202:205], v[34:37]
	v_mfma_f32_16x16x32_bf16 v[154:157], v[134:137], v[182:185], v[154:157]
	v_mfma_f32_16x16x32_bf16 v[58:61], v[142:145], v[182:185], v[58:61]
	v_mfma_f32_16x16x32_bf16 v[146:149], v[134:137], v[190:193], v[146:149]
	v_mfma_f32_16x16x32_bf16 v[50:53], v[142:145], v[190:193], v[50:53]
	v_mfma_f32_16x16x32_bf16 v[106:109], v[134:137], v[198:201], v[106:109]
	v_mfma_f32_16x16x32_bf16 v[42:45], v[142:145], v[198:201], v[42:45]
	v_mfma_f32_16x16x32_bf16 v[98:101], v[134:137], v[206:209], v[98:101]
	v_mfma_f32_16x16x32_bf16 v[34:37], v[142:145], v[206:209], v[34:37]
	s_setprio 0
	s_barrier
	s_add_i32 s91, s91, s75
	v_lshl_add_u64 v[210:211], s[54:55], 0, v[164:165]
	s_mov_b32 m0, s91
	ds_read_b128 v[176:179], v233 offset:16384
	ds_read_b128 v[182:185], v233 offset:17408
	ds_read_b128 v[186:189], v233 offset:18432
	ds_read_b128 v[190:193], v233 offset:19456
	ds_read_b128 v[194:197], v233 offset:20480
	ds_read_b128 v[198:201], v233 offset:21504
	ds_read_b128 v[202:205], v233 offset:22528
	ds_read_b128 v[206:209], v233 offset:23552
	global_load_lds_dwordx4 v[210:211], off
	s_add_i32 m0, s91, 0x2000
	s_add_u32 s92, s54, 0x40000
	v_lshl_add_u64 v[212:213], s[54:55], 0, v[168:169]
	s_addc_u32 s93, s55, 0
	s_add_i32 s91, s94, s75
	global_load_lds_dwordx4 v[212:213], off
	v_lshl_add_u64 v[214:215], s[92:93], 0, v[164:165]
	s_mov_b32 m0, s91
	v_lshl_add_u64 v[226:227], s[56:57], 0, v[166:167]
	global_load_lds_dwordx4 v[214:215], off
	v_lshl_add_u64 v[214:215], s[92:93], 0, v[168:169]
	s_add_i32 m0, s91, 0x2000
	s_nop 0
	global_load_lds_dwordx4 v[214:215], off
	v_lshl_add_u64 v[214:215], s[56:57], 0, v[162:163]
	s_mov_b32 m0, s78
	s_nop 0
	global_load_lds_dwordx4 v[214:215], off
	s_mov_b32 m0, s80
	s_nop 0
	global_load_lds_dwordx4 v[226:227], off
	s_waitcnt vmcnt(8)
	s_waitcnt lgkmcnt(0)
	s_barrier
; #define PG8_STAGE(bufoff, gbase, voff) do { _Pragma("unroll") for (int _i = 0; _i < 2; ++_i) \
;         __builtin_amdgcn_global_load_lds((const unsigned*)((const char*)(gbase) + (voff)[_i]), (LAS unsigned*)(lds + (bufoff) + ldsw + _i * 8192), 16, 0, 0); } while (0)
; #define PG8_LDA(dst, b, h) do { _Pragma("unroll") for (int m = 0; m < 4; ++m) _Pragma("unroll") for (int k = 0; k < 2; ++k) dst[m][k] = *(const LAS bf16x8*)(lds + PG8_SA(b, h) + aoff + m * 2048 + k * 1024); } while (0)
; #define PG8_LDB(dst, b, h) do { _Pragma("unroll") for (int n = 0; n < 2; ++n) _Pragma("unroll") for (int k = 0; k < 2; ++k) dst[n][k] = *(const LAS bf16x8*)(lds + PG8_SB(b, h) + boff + n * 2048 + k * 1024); } while (0)
; #define PG8_MMA(ai, bj, At, Bt) do { __builtin_amdgcn_s_setprio(1); _Pragma("unroll") for (int m = 0; m < 4; ++m) _Pragma("unroll") for (int n = 0; n < 2; ++n) _Pragma("unroll") for (int k = 0; k < 2; ++k) \
;         acc[ai][bj][m][n] = __builtin_amdgcn_mfma_f32_16x16x32_bf16(Bt[n][k], At[m][k], acc[ai][bj][m][n], 0, 0, 0); __builtin_amdgcn_s_setprio(0); } while (0)
; #define PG8_WAIT_V(n) asm volatile("s_waitcnt vmcnt(" #n ")" ::: "memory")
; #define PG8_WAIT_L(n) asm volatile("s_waitcnt lgkmcnt(" #n ")" ::: "memory")
; #define PG8_BAR __builtin_amdgcn_s_barrier()
; #define PG8_SCHED __builtin_amdgcn_sched_barrier(0)
; #define PG8_STAGE(bufoff, gbase, voff) do { _Pragma("unroll") for (int _i = 0; _i < 2; ++_i) \
;         __builtin_amdgcn_global_load_lds((const unsigned*)((const char*)(gbase) + (voff)[_i]), (LAS unsigned*)(lds + (bufoff) + ldsw + _i * 8192), 16, 0, 0); } while (0)
; #define PG8_LDA(dst, b, h) do { _Pragma("unroll") for (int m = 0; m < 4; ++m) _Pragma("unroll") for (int k = 0; k < 2; ++k) dst[m][k] = *(const LAS bf16x8*)(lds + PG8_SA(b, h) + aoff + m * 2048 + k * 1024); } while (0)
; #define PG8_BAR __builtin_amdgcn_s_barrier()
; template <class Epi, class Sched>
; __device__ __forceinline__ void gemm_phase(LAS unsigned char* lds, const Gemm g, const Sched& S, const Epi& E) {
;     ...
;             PG8_WAIT_V(8); PG8_WAIT_L(0); PG8_BAR; PG8_MMA(1, 0, At, B0); PG8_MMA(1, 1, At, B1); PG8_BAR; PG8_SCHED;
;             PG8_LDB(B0, 1, 0); PG8_LDB(B1, 1, 1); PG8_SCHED; PG8_LDA(At, 1, 0); PG8_STAGE(PG8_SA(0, 1), a2 + hstepA, voffA);
;             PG8_WAIT_V(8); PG8_WAIT_L(0); PG8_BAR; PG8_MMA(0, 0, At, B0); PG8_MMA(0, 1, At, B1); PG8_BAR; PG8_SCHED;
	s_setprio 1
	s_waitcnt lgkmcnt(0)
	v_mfma_f32_16x16x32_bf16 v[94:97], v[114:117], v[176:179], v[94:97]
	v_mfma_f32_16x16x32_bf16 v[30:33], v[122:125], v[176:179], v[30:33]
	v_mfma_f32_16x16x32_bf16 v[86:89], v[114:117], v[186:189], v[86:89]
	v_mfma_f32_16x16x32_bf16 v[22:25], v[122:125], v[186:189], v[22:25]
	v_mfma_f32_16x16x32_bf16 v[78:81], v[114:117], v[194:197], v[78:81]
	v_mfma_f32_16x16x32_bf16 v[14:17], v[122:125], v[194:197], v[14:17]
	v_mfma_f32_16x16x32_bf16 v[70:73], v[114:117], v[202:205], v[70:73]
	v_mfma_f32_16x16x32_bf16 v[6:9], v[122:125], v[202:205], v[6:9]
	v_mfma_f32_16x16x32_bf16 v[94:97], v[118:121], v[182:185], v[94:97]
	v_mfma_f32_16x16x32_bf16 v[30:33], v[126:129], v[182:185], v[30:33]
	v_mfma_f32_16x16x32_bf16 v[86:89], v[118:121], v[190:193], v[86:89]
	v_mfma_f32_16x16x32_bf16 v[22:25], v[126:129], v[190:193], v[22:25]
	v_mfma_f32_16x16x32_bf16 v[78:81], v[118:121], v[198:201], v[78:81]
	v_mfma_f32_16x16x32_bf16 v[14:17], v[126:129], v[198:201], v[14:17]
	v_mfma_f32_16x16x32_bf16 v[70:73], v[118:121], v[206:209], v[70:73]
	v_mfma_f32_16x16x32_bf16 v[6:9], v[126:129], v[206:209], v[6:9]
	s_setprio 0
	s_setprio 1
	v_mfma_f32_16x16x32_bf16 v[90:93], v[130:133], v[176:179], v[90:93]
	v_mfma_f32_16x16x32_bf16 v[26:29], v[138:141], v[176:179], v[26:29]
	v_mfma_f32_16x16x32_bf16 v[82:85], v[130:133], v[186:189], v[82:85]
	v_mfma_f32_16x16x32_bf16 v[18:21], v[138:141], v[186:189], v[18:21]
	v_mfma_f32_16x16x32_bf16 v[74:77], v[130:133], v[194:197], v[74:77]
	v_mfma_f32_16x16x32_bf16 v[10:13], v[138:141], v[194:197], v[10:13]
	v_mfma_f32_16x16x32_bf16 v[66:69], v[130:133], v[202:205], v[66:69]
	v_mfma_f32_16x16x32_bf16 v[2:5], v[138:141], v[202:205], v[2:5]
	v_mfma_f32_16x16x32_bf16 v[90:93], v[134:137], v[182:185], v[90:93]
	v_mfma_f32_16x16x32_bf16 v[26:29], v[142:145], v[182:185], v[26:29]
	v_mfma_f32_16x16x32_bf16 v[82:85], v[134:137], v[190:193], v[82:85]
	v_mfma_f32_16x16x32_bf16 v[18:21], v[142:145], v[190:193], v[18:21]
	v_mfma_f32_16x16x32_bf16 v[74:77], v[134:137], v[198:201], v[74:77]
	v_mfma_f32_16x16x32_bf16 v[10:13], v[142:145], v[198:201], v[10:13]
	v_mfma_f32_16x16x32_bf16 v[66:69], v[134:137], v[206:209], v[66:69]
	v_mfma_f32_16x16x32_bf16 v[2:5], v[142:145], v[206:209], v[2:5]
	s_setprio 0
	s_barrier
	s_add_i32 s91, 0, 0x18000
	s_add_i32 s92, 0, 0x1c000
	v_add_u32_e32 v126, s91, v231
	v_add_u32_e32 v142, s92, v231
	ds_read_b128 v[114:117], v126
	ds_read_b128 v[118:121], v126 offset:1024
	ds_read_b128 v[122:125], v126 offset:2048
	ds_read_b128 v[126:129], v126 offset:3072
	ds_read_b128 v[130:133], v142
	ds_read_b128 v[134:137], v142 offset:1024
	ds_read_b128 v[138:141], v142 offset:2048
	ds_read_b128 v[142:145], v142 offset:3072
	s_add_u32 s56, s56, 0x40000
	s_addc_u32 s57, s57, 0
	s_mov_b32 m0, s81
	v_lshl_add_u64 v[228:229], s[56:57], 0, v[162:163]
	ds_read_b128 v[176:179], v233 offset:32768
	ds_read_b128 v[182:185], v233 offset:33792
	ds_read_b128 v[186:189], v233 offset:34816
	ds_read_b128 v[190:193], v233 offset:35840
	ds_read_b128 v[194:197], v233 offset:36864
	ds_read_b128 v[198:201], v233 offset:37888
	ds_read_b128 v[202:205], v233 offset:38912
	ds_read_b128 v[206:209], v233 offset:39936
	global_load_lds_dwordx4 v[228:229], off
	v_lshl_add_u64 v[228:229], s[56:57], 0, v[166:167]
	s_mov_b32 m0, s82
	s_nop 0
	global_load_lds_dwordx4 v[228:229], off
	s_waitcnt vmcnt(8)
	s_waitcnt lgkmcnt(0)
	s_barrier
	s_setprio 1
	s_waitcnt lgkmcnt(0)
	v_mfma_f32_16x16x32_bf16 v[158:161], v[114:117], v[176:179], v[158:161]
	v_mfma_f32_16x16x32_bf16 v[62:65], v[122:125], v[176:179], v[62:65]
	v_mfma_f32_16x16x32_bf16 v[150:153], v[114:117], v[186:189], v[150:153]
	v_mfma_f32_16x16x32_bf16 v[54:57], v[122:125], v[186:189], v[54:57]
	v_mfma_f32_16x16x32_bf16 v[110:113], v[114:117], v[194:197], v[110:113]
	v_mfma_f32_16x16x32_bf16 v[46:49], v[122:125], v[194:197], v[46:49]
	v_mfma_f32_16x16x32_bf16 v[102:105], v[114:117], v[202:205], v[102:105]
	v_mfma_f32_16x16x32_bf16 v[38:41], v[122:125], v[202:205], v[38:41]
	v_mfma_f32_16x16x32_bf16 v[158:161], v[118:121], v[182:185], v[158:161]
	v_mfma_f32_16x16x32_bf16 v[62:65], v[126:129], v[182:185], v[62:65]
	v_mfma_f32_16x16x32_bf16 v[150:153], v[118:121], v[190:193], v[150:153]
	v_mfma_f32_16x16x32_bf16 v[54:57], v[126:129], v[190:193], v[54:57]
	v_mfma_f32_16x16x32_bf16 v[110:113], v[118:121], v[198:201], v[110:113]
	v_mfma_f32_16x16x32_bf16 v[46:49], v[126:129], v[198:201], v[46:49]
	v_mfma_f32_16x16x32_bf16 v[102:105], v[118:121], v[206:209], v[102:105]
	v_mfma_f32_16x16x32_bf16 v[38:41], v[126:129], v[206:209], v[38:41]
	s_setprio 0
	s_setprio 1
	v_mfma_f32_16x16x32_bf16 v[154:157], v[130:133], v[176:179], v[154:157]
	v_mfma_f32_16x16x32_bf16 v[58:61], v[138:141], v[176:179], v[58:61]
	v_mfma_f32_16x16x32_bf16 v[146:149], v[130:133], v[186:189], v[146:149]
	v_mfma_f32_16x16x32_bf16 v[50:53], v[138:141], v[186:189], v[50:53]
	v_mfma_f32_16x16x32_bf16 v[106:109], v[130:133], v[194:197], v[106:109]
	v_mfma_f32_16x16x32_bf16 v[42:45], v[138:141], v[194:197], v[42:45]
	v_mfma_f32_16x16x32_bf16 v[98:101], v[130:133], v[202:205], v[98:101]
	v_mfma_f32_16x16x32_bf16 v[34:37], v[138:141], v[202:205], v[34:37]
	v_mfma_f32_16x16x32_bf16 v[154:157], v[134:137], v[182:185], v[154:157]
	v_mfma_f32_16x16x32_bf16 v[58:61], v[142:145], v[182:185], v[58:61]
	v_mfma_f32_16x16x32_bf16 v[146:149], v[134:137], v[190:193], v[146:149]
	v_mfma_f32_16x16x32_bf16 v[50:53], v[142:145], v[190:193], v[50:53]
	v_mfma_f32_16x16x32_bf16 v[106:109], v[134:137], v[198:201], v[106:109]
	v_mfma_f32_16x16x32_bf16 v[42:45], v[142:145], v[198:201], v[42:45]
	v_mfma_f32_16x16x32_bf16 v[98:101], v[134:137], v[206:209], v[98:101]
	v_mfma_f32_16x16x32_bf16 v[34:37], v[142:145], v[206:209], v[34:37]
	s_setprio 0
	s_barrier
; #define PG8_STAGE(bufoff, gbase, voff) do { _Pragma("unroll") for (int _i = 0; _i < 2; ++_i) \
;         __builtin_amdgcn_global_load_lds((const unsigned*)((const char*)(gbase) + (voff)[_i]), (LAS unsigned*)(lds + (bufoff) + ldsw + _i * 8192), 16, 0, 0); } while (0)
; #define PG8_LDA(dst, b, h) do { _Pragma("unroll") for (int m = 0; m < 4; ++m) _Pragma("unroll") for (int k = 0; k < 2; ++k) dst[m][k] = *(const LAS bf16x8*)(lds + PG8_SA(b, h) + aoff + m * 2048 + k * 1024); } while (0)
; #define PG8_MMA(ai, bj, At, Bt) do { __builtin_amdgcn_s_setprio(1); _Pragma("unroll") for (int m = 0; m < 4; ++m) _Pragma("unroll") for (int n = 0; n < 2; ++n) _Pragma("unroll") for (int k = 0; k < 2; ++k) \
;         acc[ai][bj][m][n] = __builtin_amdgcn_mfma_f32_16x16x32_bf16(Bt[n][k], At[m][k], acc[ai][bj][m][n], 0, 0, 0); __builtin_amdgcn_s_setprio(0); } while (0)
; #define PG8_WAIT_V(n) asm volatile("s_waitcnt vmcnt(" #n ")" ::: "memory")
; #define PG8_WAIT_L(n) asm volatile("s_waitcnt lgkmcnt(" #n ")" ::: "memory")
; #define PG8_BAR __builtin_amdgcn_s_barrier()
; #define PG8_SCHED __builtin_amdgcn_sched_barrier(0)
; #define PG8_STAGE(bufoff, gbase, voff) do { _Pragma("unroll") for (int _i = 0; _i < 2; ++_i) \
;         __builtin_amdgcn_global_load_lds((const unsigned*)((const char*)(gbase) + (voff)[_i]), (LAS unsigned*)(lds + (bufoff) + ldsw + _i * 8192), 16, 0, 0); } while (0)
; #define PG8_LDA(dst, b, h) do { _Pragma("unroll") for (int m = 0; m < 4; ++m) _Pragma("unroll") for (int k = 0; k < 2; ++k) dst[m][k] = *(const LAS bf16x8*)(lds + PG8_SA(b, h) + aoff + m * 2048 + k * 1024); } while (0)
; #define PG8_WAIT_V(n) asm volatile("s_waitcnt vmcnt(" #n ")" ::: "memory")
; #define PG8_WAIT_L(n) asm volatile("s_waitcnt lgkmcnt(" #n ")" ::: "memory")
; #define PG8_BAR __builtin_amdgcn_s_barrier()
; #define PG8_SCHED __builtin_amdgcn_sched_barrier(0)
; template <class Epi, class Sched>
; __device__ __forceinline__ void gemm_phase(LAS unsigned char* lds, const Gemm g, const Sched& S, const Epi& E) {
;     ...
;             PG8_LDA(At, 1, 1); PG8_STAGE(PG8_SB(1, 0), b3, voffB); PG8_STAGE(PG8_SB(1, 1), b3 + hstepB, voffB); PG8_STAGE(PG8_SA(1, 0), a3, voffA);
;             PG8_WAIT_V(8); PG8_WAIT_L(0); PG8_BAR; PG8_MMA(1, 0, At, B0); PG8_MMA(1, 1, At, B1); PG8_BAR; PG8_SCHED;
;         }
;         if (wr == 0) PG8_BAR;
	s_add_i32 s56, s91, s75
	v_lshl_add_u64 v[210:211], v[210:211], 0, s[86:87]
	s_mov_b32 m0, s56
	ds_read_b128 v[176:179], v233 offset:49152
	ds_read_b128 v[182:185], v233 offset:50176
	ds_read_b128 v[186:189], v233 offset:51200
	ds_read_b128 v[190:193], v233 offset:52224
	ds_read_b128 v[194:197], v233 offset:53248
	ds_read_b128 v[198:201], v233 offset:54272
	ds_read_b128 v[202:205], v233 offset:55296
	ds_read_b128 v[206:209], v233 offset:56320
	global_load_lds_dwordx4 v[210:211], off
	s_add_i32 m0, s56, 0x2000
	s_add_u32 s54, s54, 0x40080
	v_lshl_add_u64 v[210:211], v[212:213], 0, s[86:87]
	s_addc_u32 s55, s55, 0
	s_add_i32 s56, s92, s75
	global_load_lds_dwordx4 v[210:211], off
	v_lshl_add_u64 v[210:211], s[54:55], 0, v[164:165]
	s_mov_b32 m0, s56
	s_nop 0
	global_load_lds_dwordx4 v[210:211], off
	v_lshl_add_u64 v[210:211], s[54:55], 0, v[168:169]
	s_add_i32 m0, s56, 0x2000
	s_nop 0
	global_load_lds_dwordx4 v[210:211], off
	v_lshl_add_u64 v[210:211], v[214:215], 0, s[86:87]
	s_mov_b32 m0, s83
	s_nop 0
	global_load_lds_dwordx4 v[210:211], off
	v_lshl_add_u64 v[210:211], v[226:227], 0, s[86:87]
	s_mov_b32 m0, s84
	s_nop 0
	global_load_lds_dwordx4 v[210:211], off
	s_waitcnt vmcnt(8)
	s_waitcnt lgkmcnt(0)
	s_barrier
	s_setprio 1
	s_waitcnt lgkmcnt(0)
	v_mfma_f32_16x16x32_bf16 v[94:97], v[114:117], v[176:179], v[94:97]
	v_mfma_f32_16x16x32_bf16 v[30:33], v[122:125], v[176:179], v[30:33]
	v_mfma_f32_16x16x32_bf16 v[86:89], v[114:117], v[186:189], v[86:89]
	v_mfma_f32_16x16x32_bf16 v[22:25], v[122:125], v[186:189], v[22:25]
	v_mfma_f32_16x16x32_bf16 v[78:81], v[114:117], v[194:197], v[78:81]
	v_mfma_f32_16x16x32_bf16 v[14:17], v[122:125], v[194:197], v[14:17]
	v_mfma_f32_16x16x32_bf16 v[70:73], v[114:117], v[202:205], v[70:73]
	v_mfma_f32_16x16x32_bf16 v[6:9], v[122:125], v[202:205], v[6:9]
	v_mfma_f32_16x16x32_bf16 v[94:97], v[118:121], v[182:185], v[94:97]
	v_mfma_f32_16x16x32_bf16 v[30:33], v[126:129], v[182:185], v[30:33]
	v_mfma_f32_16x16x32_bf16 v[86:89], v[118:121], v[190:193], v[86:89]
	v_mfma_f32_16x16x32_bf16 v[22:25], v[126:129], v[190:193], v[22:25]
	v_mfma_f32_16x16x32_bf16 v[78:81], v[118:121], v[198:201], v[78:81]
	v_mfma_f32_16x16x32_bf16 v[14:17], v[126:129], v[198:201], v[14:17]
	v_mfma_f32_16x16x32_bf16 v[70:73], v[118:121], v[206:209], v[70:73]
	v_mfma_f32_16x16x32_bf16 v[6:9], v[126:129], v[206:209], v[6:9]
	s_setprio 0
	s_setprio 1
	v_mfma_f32_16x16x32_bf16 v[90:93], v[130:133], v[176:179], v[90:93]
	v_mfma_f32_16x16x32_bf16 v[26:29], v[138:141], v[176:179], v[26:29]
	v_mfma_f32_16x16x32_bf16 v[82:85], v[130:133], v[186:189], v[82:85]
	v_mfma_f32_16x16x32_bf16 v[18:21], v[138:141], v[186:189], v[18:21]
	v_mfma_f32_16x16x32_bf16 v[74:77], v[130:133], v[194:197], v[74:77]
	v_mfma_f32_16x16x32_bf16 v[10:13], v[138:141], v[194:197], v[10:13]
	v_mfma_f32_16x16x32_bf16 v[66:69], v[130:133], v[202:205], v[66:69]
	v_mfma_f32_16x16x32_bf16 v[2:5], v[138:141], v[202:205], v[2:5]
	v_mfma_f32_16x16x32_bf16 v[90:93], v[134:137], v[182:185], v[90:93]
	v_mfma_f32_16x16x32_bf16 v[26:29], v[142:145], v[182:185], v[26:29]
	v_mfma_f32_16x16x32_bf16 v[82:85], v[134:137], v[190:193], v[82:85]
	v_mfma_f32_16x16x32_bf16 v[18:21], v[142:145], v[190:193], v[18:21]
	v_mfma_f32_16x16x32_bf16 v[74:77], v[134:137], v[198:201], v[74:77]
	v_mfma_f32_16x16x32_bf16 v[10:13], v[142:145], v[198:201], v[10:13]
	v_mfma_f32_16x16x32_bf16 v[66:69], v[134:137], v[206:209], v[66:69]
	v_mfma_f32_16x16x32_bf16 v[2:5], v[142:145], v[206:209], v[2:5]
	s_setprio 0
	s_barrier
	s_add_i32 s90, s90, 2
	s_add_u32 s67, s67, 0x100
	s_addc_u32 s76, s76, 0
	s_add_u32 s52, s52, 0x100
	s_addc_u32 s53, s53, 0
	s_cmp_gt_u32 s90, 13
	s_cbranch_scc0 .LBB0_1131
	s_and_b64 vcc, exec, s[20:21]
	s_andn2_b64 vcc, vcc, s[12:13]
	s_cbranch_vccz .LBB0_1134
	s_barrier

; #define PG8_BAR __builtin_amdgcn_s_barrier()
; #define PG8_BAR __builtin_amdgcn_s_barrier()
; template <class Epi, class Sched>
; __device__ __forceinline__ void gemm_phase(LAS unsigned char* lds, const Gemm g, const Sched& S, const Epi& E) {
;     ...
;         if (!has_next) break;
; #pragma unroll
;         for (int a = 0; a < 2; ++a)
; #pragma unroll
;             for (int b = 0; b < 2; ++b)
; #pragma unroll
;                 for (int m = 0; m < 4; ++m)
; #pragma unroll
;                     for (int n = 0; n < 2; ++n) acc[a][b][m][n] = (f32x4){0.f, 0.f, 0.f, 0.f};
;         cur = nxt; cA = nA; cB = nB; ++ui;
;         if (wr == 1) PG8_BAR;
.LBB0_1150:
	s_or_b64 exec, exec, s[48:49]
	s_andn2_b64 vcc, exec, s[12:13]
	s_mov_b64 s[12:13], -1
	s_cbranch_vccnz .LBB0_1127
	s_branch .LBB0_1126

; #define PG8_STAGE(bufoff, gbase, voff) do { _Pragma("unroll") for (int _i = 0; _i < 2; ++_i) \
;         __builtin_amdgcn_global_load_lds((const unsigned*)((const char*)(gbase) + (voff)[_i]), (LAS unsigned*)(lds + (bufoff) + ldsw + _i * 8192), 16, 0, 0); } while (0)
; #define PG8_LDA(dst, b, h) do { _Pragma("unroll") for (int m = 0; m < 4; ++m) _Pragma("unroll") for (int k = 0; k < 2; ++k) dst[m][k] = *(const LAS bf16x8*)(lds + PG8_SA(b, h) + aoff + m * 2048 + k * 1024); } while (0)
; #define PG8_LDB(dst, b, h) do { _Pragma("unroll") for (int n = 0; n < 2; ++n) _Pragma("unroll") for (int k = 0; k < 2; ++k) dst[n][k] = *(const LAS bf16x8*)(lds + PG8_SB(b, h) + boff + n * 2048 + k * 1024); } while (0)
; #define PG8_MMA(ai, bj, At, Bt) do { __builtin_amdgcn_s_setprio(1); _Pragma("unroll") for (int m = 0; m < 4; ++m) _Pragma("unroll") for (int n = 0; n < 2; ++n) _Pragma("unroll") for (int k = 0; k < 2; ++k) \
;         acc[ai][bj][m][n] = __builtin_amdgcn_mfma_f32_16x16x32_bf16(Bt[n][k], At[m][k], acc[ai][bj][m][n], 0, 0, 0); __builtin_amdgcn_s_setprio(0); } while (0)
; #define PG8_WAIT_V(n) asm volatile("s_waitcnt vmcnt(" #n ")" ::: "memory")
; #define PG8_WAIT_L(n) asm volatile("s_waitcnt lgkmcnt(" #n ")" ::: "memory")
; #define PG8_BAR __builtin_amdgcn_s_barrier()
; #define PG8_SCHED __builtin_amdgcn_sched_barrier(0)
; #define PG8_WAIT_V(n) asm volatile("s_waitcnt vmcnt(" #n ")" ::: "memory")
; #define PG8_WAIT_L(n) asm volatile("s_waitcnt lgkmcnt(" #n ")" ::: "memory")
; template <class Epi, class Sched>
; __device__ __forceinline__ void gemm_phase(LAS unsigned char* lds, const Gemm g, const Sched& S, const Epi& E) {
;     ...
;         for (int t = 0; t < nt; t += 2) {
;             const bool last = (t == nt - 2);
;             const char* a1 = cA + (size_t)(t + 1) * kstep;
;             const char* a2 = last ? nA : cA + (size_t)(t + 2) * kstep; const char* b2 = last ? nB : cB + (size_t)(t + 2) * kstep;
;             const char* a3 = a2 + kstep; const char* b3 = b2 + kstep;
;             PG8_LDB(B0, 0, 0); PG8_LDB(B1, 0, 1); PG8_SCHED; PG8_LDA(At, 0, 0); PG8_STAGE(PG8_SA(1, 1), a1 + hstepA, voffA);
;             PG8_WAIT_V(8); PG8_WAIT_L(0); PG8_BAR; PG8_MMA(0, 0, At, B0); PG8_MMA(0, 1, At, B1); PG8_BAR; PG8_SCHED;
;             PG8_LDA(At, 0, 1); PG8_STAGE(PG8_SB(0, 0), b2, voffB); PG8_STAGE(PG8_SB(0, 1), b2 + hstepB, voffB); PG8_STAGE(PG8_SA(0, 0), a2, voffA);
.LBB0_1238:
	s_add_u32 s16, s14, 0x100
	s_addc_u32 s17, s15, 0
	s_add_i32 s48, 0, 0x10000
	s_cmp_eq_u32 s46, 40
	s_cselect_b32 s21, s7, s17
	s_cselect_b32 s20, s6, s16
	v_add_u32_e32 v146, s48, v148
	s_cselect_b32 s19, s13, s45
	s_cselect_b32 s18, s12, s44
	s_add_i32 s49, 0, 0x14000
	ds_read_b128 v[142:145], v146
	ds_read_b128 v[152:155], v146 offset:1024
	ds_read_b128 v[156:159], v146 offset:2048
	ds_read_b128 v[160:163], v146 offset:3072
	v_add_u32_e32 v146, s49, v148
	ds_read_b128 v[164:167], v146
	ds_read_b128 v[168:171], v146 offset:1024
	ds_read_b128 v[172:175], v146 offset:2048
	ds_read_b128 v[176:179], v146 offset:3072
	v_lshl_add_u64 v[146:147], s[14:15], 0, v[140:141]
	s_add_i32 m0, s27, 0xc000
	ds_read_b128 v[182:185], v150
	ds_read_b128 v[186:189], v150 offset:1024
	ds_read_b128 v[190:193], v150 offset:2048
	ds_read_b128 v[194:197], v150 offset:3072
	ds_read_b128 v[198:201], v150 offset:4096
	ds_read_b128 v[202:205], v150 offset:5120
	ds_read_b128 v[206:209], v150 offset:6144
	ds_read_b128 v[210:213], v150 offset:7168
	global_load_lds_dwordx4 v[146:147], off
	v_lshl_add_u64 v[146:147], s[14:15], 0, v[138:139]
	s_add_i32 m0, s27, 0xe000
	s_nop 0
	global_load_lds_dwordx4 v[146:147], off
	s_waitcnt vmcnt(8)
	s_waitcnt lgkmcnt(0)
	s_barrier
	s_setprio 1
	s_waitcnt lgkmcnt(0)
	v_mfma_f32_16x16x32_bf16 v[126:129], v[142:145], v[182:185], v[126:129]
	v_mfma_f32_16x16x32_bf16 v[122:125], v[156:159], v[182:185], v[122:125]
	v_mfma_f32_16x16x32_bf16 v[110:113], v[142:145], v[190:193], v[110:113]
	v_mfma_f32_16x16x32_bf16 v[106:109], v[156:159], v[190:193], v[106:109]
	v_mfma_f32_16x16x32_bf16 v[94:97], v[142:145], v[198:201], v[94:97]
	v_mfma_f32_16x16x32_bf16 v[90:93], v[156:159], v[198:201], v[90:93]
	v_mfma_f32_16x16x32_bf16 v[78:81], v[142:145], v[206:209], v[78:81]
	v_mfma_f32_16x16x32_bf16 v[74:77], v[156:159], v[206:209], v[74:77]
	v_mfma_f32_16x16x32_bf16 v[126:129], v[152:155], v[186:189], v[126:129]
	v_mfma_f32_16x16x32_bf16 v[122:125], v[160:163], v[186:189], v[122:125]
	v_mfma_f32_16x16x32_bf16 v[110:113], v[152:155], v[194:197], v[110:113]
	v_mfma_f32_16x16x32_bf16 v[106:109], v[160:163], v[194:197], v[106:109]
	v_mfma_f32_16x16x32_bf16 v[94:97], v[152:155], v[202:205], v[94:97]
	v_mfma_f32_16x16x32_bf16 v[90:93], v[160:163], v[202:205], v[90:93]
	v_mfma_f32_16x16x32_bf16 v[78:81], v[152:155], v[210:213], v[78:81]
	v_mfma_f32_16x16x32_bf16 v[74:77], v[160:163], v[210:213], v[74:77]
	s_setprio 0
	s_setprio 1
	v_mfma_f32_16x16x32_bf16 v[118:121], v[164:167], v[182:185], v[118:121]
	v_mfma_f32_16x16x32_bf16 v[114:117], v[172:175], v[182:185], v[114:117]
	v_mfma_f32_16x16x32_bf16 v[102:105], v[164:167], v[190:193], v[102:105]
	v_mfma_f32_16x16x32_bf16 v[98:101], v[172:175], v[190:193], v[98:101]
	v_mfma_f32_16x16x32_bf16 v[86:89], v[164:167], v[198:201], v[86:89]
	v_mfma_f32_16x16x32_bf16 v[82:85], v[172:175], v[198:201], v[82:85]
	v_mfma_f32_16x16x32_bf16 v[70:73], v[164:167], v[206:209], v[70:73]
	v_mfma_f32_16x16x32_bf16 v[66:69], v[172:175], v[206:209], v[66:69]
	v_mfma_f32_16x16x32_bf16 v[118:121], v[168:171], v[186:189], v[118:121]
	v_mfma_f32_16x16x32_bf16 v[114:117], v[176:179], v[186:189], v[114:117]
	v_mfma_f32_16x16x32_bf16 v[102:105], v[168:171], v[194:197], v[102:105]
	v_mfma_f32_16x16x32_bf16 v[98:101], v[176:179], v[194:197], v[98:101]
	v_mfma_f32_16x16x32_bf16 v[86:89], v[168:171], v[202:205], v[86:89]
	v_mfma_f32_16x16x32_bf16 v[82:85], v[176:179], v[202:205], v[82:85]
	v_mfma_f32_16x16x32_bf16 v[70:73], v[168:171], v[210:213], v[70:73]
	v_mfma_f32_16x16x32_bf16 v[66:69], v[176:179], v[210:213], v[66:69]
	s_setprio 0
	s_barrier
	s_add_i32 s14, s48, s26
	v_lshl_add_u64 v[146:147], s[18:19], 0, v[132:133]
	s_mov_b32 m0, s14
	ds_read_b128 v[182:185], v150 offset:16384
	ds_read_b128 v[186:189], v150 offset:17408
	ds_read_b128 v[190:193], v150 offset:18432
	ds_read_b128 v[194:197], v150 offset:19456
	ds_read_b128 v[198:201], v150 offset:20480
	ds_read_b128 v[202:205], v150 offset:21504
	ds_read_b128 v[206:209], v150 offset:22528
	ds_read_b128 v[210:213], v150 offset:23552
	global_load_lds_dwordx4 v[146:147], off
	s_add_i32 m0, s14, 0x2000
	s_add_u32 s14, s18, 0xb0000
	v_lshl_add_u64 v[214:215], s[18:19], 0, v[136:137]
	s_addc_u32 s15, s19, 0
	s_add_i32 s48, s49, s26
	global_load_lds_dwordx4 v[214:215], off
	v_lshl_add_u64 v[226:227], s[14:15], 0, v[132:133]
	s_mov_b32 m0, s48
	v_lshl_add_u64 v[228:229], s[20:21], 0, v[134:135]
	global_load_lds_dwordx4 v[226:227], off
	v_lshl_add_u64 v[226:227], s[14:15], 0, v[136:137]
	s_add_i32 m0, s48, 0x2000
	s_nop 0
	global_load_lds_dwordx4 v[226:227], off
	v_lshl_add_u64 v[226:227], s[20:21], 0, v[130:131]
	s_mov_b32 m0, s27
	s_nop 0
	global_load_lds_dwordx4 v[226:227], off
	s_mov_b32 m0, s28
	s_nop 0
	global_load_lds_dwordx4 v[228:229], off
	s_waitcnt vmcnt(8)
	s_waitcnt lgkmcnt(0)
	s_barrier
; #define PG8_STAGE(bufoff, gbase, voff) do { _Pragma("unroll") for (int _i = 0; _i < 2; ++_i) \
;         __builtin_amdgcn_global_load_lds((const unsigned*)((const char*)(gbase) + (voff)[_i]), (LAS unsigned*)(lds + (bufoff) + ldsw + _i * 8192), 16, 0, 0); } while (0)
; #define PG8_LDA(dst, b, h) do { _Pragma("unroll") for (int m = 0; m < 4; ++m) _Pragma("unroll") for (int k = 0; k < 2; ++k) dst[m][k] = *(const LAS bf16x8*)(lds + PG8_SA(b, h) + aoff + m * 2048 + k * 1024); } while (0)
; #define PG8_LDB(dst, b, h) do { _Pragma("unroll") for (int n = 0; n < 2; ++n) _Pragma("unroll") for (int k = 0; k < 2; ++k) dst[n][k] = *(const LAS bf16x8*)(lds + PG8_SB(b, h) + boff + n * 2048 + k * 1024); } while (0)
; #define PG8_MMA(ai, bj, At, Bt) do { __builtin_amdgcn_s_setprio(1); _Pragma("unroll") for (int m = 0; m < 4; ++m) _Pragma("unroll") for (int n = 0; n < 2; ++n) _Pragma("unroll") for (int k = 0; k < 2; ++k) \
;         acc[ai][bj][m][n] = __builtin_amdgcn_mfma_f32_16x16x32_bf16(Bt[n][k], At[m][k], acc[ai][bj][m][n], 0, 0, 0); __builtin_amdgcn_s_setprio(0); } while (0)
; #define PG8_WAIT_V(n) asm volatile("s_waitcnt vmcnt(" #n ")" ::: "memory")
; #define PG8_WAIT_L(n) asm volatile("s_waitcnt lgkmcnt(" #n ")" ::: "memory")
; #define PG8_BAR __builtin_amdgcn_s_barrier()
; #define PG8_SCHED __builtin_amdgcn_sched_barrier(0)
; #define PG8_STAGE(bufoff, gbase, voff) do { _Pragma("unroll") for (int _i = 0; _i < 2; ++_i) \
;         __builtin_amdgcn_global_load_lds((const unsigned*)((const char*)(gbase) + (voff)[_i]), (LAS unsigned*)(lds + (bufoff) + ldsw + _i * 8192), 16, 0, 0); } while (0)
; #define PG8_LDA(dst, b, h) do { _Pragma("unroll") for (int m = 0; m < 4; ++m) _Pragma("unroll") for (int k = 0; k < 2; ++k) dst[m][k] = *(const LAS bf16x8*)(lds + PG8_SA(b, h) + aoff + m * 2048 + k * 1024); } while (0)
; #define PG8_BAR __builtin_amdgcn_s_barrier()
; template <class Epi, class Sched>
; __device__ __forceinline__ void gemm_phase(LAS unsigned char* lds, const Gemm g, const Sched& S, const Epi& E) {
;     ...
;             PG8_WAIT_V(8); PG8_WAIT_L(0); PG8_BAR; PG8_MMA(1, 0, At, B0); PG8_MMA(1, 1, At, B1); PG8_BAR; PG8_SCHED;
;             PG8_LDB(B0, 1, 0); PG8_LDB(B1, 1, 1); PG8_SCHED; PG8_LDA(At, 1, 0); PG8_STAGE(PG8_SA(0, 1), a2 + hstepA, voffA);
;             PG8_WAIT_V(8); PG8_WAIT_L(0); PG8_BAR; PG8_MMA(0, 0, At, B0); PG8_MMA(0, 1, At, B1); PG8_BAR; PG8_SCHED;
	s_setprio 1
	s_waitcnt lgkmcnt(0)
	v_mfma_f32_16x16x32_bf16 v[62:65], v[142:145], v[182:185], v[62:65]
	v_mfma_f32_16x16x32_bf16 v[58:61], v[156:159], v[182:185], v[58:61]
	v_mfma_f32_16x16x32_bf16 v[46:49], v[142:145], v[190:193], v[46:49]
	v_mfma_f32_16x16x32_bf16 v[42:45], v[156:159], v[190:193], v[42:45]
	v_mfma_f32_16x16x32_bf16 v[30:33], v[142:145], v[198:201], v[30:33]
	v_mfma_f32_16x16x32_bf16 v[26:29], v[156:159], v[198:201], v[26:29]
	v_mfma_f32_16x16x32_bf16 v[14:17], v[142:145], v[206:209], v[14:17]
	v_mfma_f32_16x16x32_bf16 v[10:13], v[156:159], v[206:209], v[10:13]
	v_mfma_f32_16x16x32_bf16 v[62:65], v[152:155], v[186:189], v[62:65]
	v_mfma_f32_16x16x32_bf16 v[58:61], v[160:163], v[186:189], v[58:61]
	v_mfma_f32_16x16x32_bf16 v[46:49], v[152:155], v[194:197], v[46:49]
	v_mfma_f32_16x16x32_bf16 v[42:45], v[160:163], v[194:197], v[42:45]
	v_mfma_f32_16x16x32_bf16 v[30:33], v[152:155], v[202:205], v[30:33]
	v_mfma_f32_16x16x32_bf16 v[26:29], v[160:163], v[202:205], v[26:29]
	v_mfma_f32_16x16x32_bf16 v[14:17], v[152:155], v[210:213], v[14:17]
	v_mfma_f32_16x16x32_bf16 v[10:13], v[160:163], v[210:213], v[10:13]
	s_setprio 0
	s_setprio 1
	v_mfma_f32_16x16x32_bf16 v[54:57], v[164:167], v[182:185], v[54:57]
	v_mfma_f32_16x16x32_bf16 v[50:53], v[172:175], v[182:185], v[50:53]
	v_mfma_f32_16x16x32_bf16 v[38:41], v[164:167], v[190:193], v[38:41]
	v_mfma_f32_16x16x32_bf16 v[34:37], v[172:175], v[190:193], v[34:37]
	v_mfma_f32_16x16x32_bf16 v[22:25], v[164:167], v[198:201], v[22:25]
	v_mfma_f32_16x16x32_bf16 v[18:21], v[172:175], v[198:201], v[18:21]
	v_mfma_f32_16x16x32_bf16 v[6:9], v[164:167], v[206:209], v[6:9]
	v_mfma_f32_16x16x32_bf16 v[2:5], v[172:175], v[206:209], v[2:5]
	v_mfma_f32_16x16x32_bf16 v[54:57], v[168:171], v[186:189], v[54:57]
	v_mfma_f32_16x16x32_bf16 v[50:53], v[176:179], v[186:189], v[50:53]
	v_mfma_f32_16x16x32_bf16 v[38:41], v[168:171], v[194:197], v[38:41]
	v_mfma_f32_16x16x32_bf16 v[34:37], v[176:179], v[194:197], v[34:37]
	v_mfma_f32_16x16x32_bf16 v[22:25], v[168:171], v[202:205], v[22:25]
	v_mfma_f32_16x16x32_bf16 v[18:21], v[176:179], v[202:205], v[18:21]
	v_mfma_f32_16x16x32_bf16 v[6:9], v[168:171], v[210:213], v[6:9]
	v_mfma_f32_16x16x32_bf16 v[2:5], v[176:179], v[210:213], v[2:5]
	s_setprio 0
	s_barrier
	s_add_i32 s48, 0, 0x18000
	v_add_u32_e32 v151, s48, v148
	s_add_i32 s49, 0, 0x1c000
	ds_read_b128 v[142:145], v151
	ds_read_b128 v[152:155], v151 offset:1024
	ds_read_b128 v[156:159], v151 offset:2048
	ds_read_b128 v[160:163], v151 offset:3072
	v_add_u32_e32 v151, s49, v148
	ds_read_b128 v[164:167], v151
	ds_read_b128 v[168:171], v151 offset:1024
	ds_read_b128 v[172:175], v151 offset:2048
	ds_read_b128 v[176:179], v151 offset:3072
	s_add_u32 s14, s20, 0xb0000
	s_addc_u32 s15, s21, 0
	s_mov_b32 m0, s29
	v_lshl_add_u64 v[232:233], s[14:15], 0, v[130:131]
	ds_read_b128 v[182:185], v150 offset:32768
	ds_read_b128 v[186:189], v150 offset:33792
	ds_read_b128 v[190:193], v150 offset:34816
	ds_read_b128 v[194:197], v150 offset:35840
	ds_read_b128 v[198:201], v150 offset:36864
	ds_read_b128 v[202:205], v150 offset:37888
	ds_read_b128 v[206:209], v150 offset:38912
	ds_read_b128 v[210:213], v150 offset:39936
	global_load_lds_dwordx4 v[232:233], off
	v_lshl_add_u64 v[232:233], s[14:15], 0, v[134:135]
	s_mov_b32 m0, s30
	s_nop 0
	global_load_lds_dwordx4 v[232:233], off
	s_waitcnt vmcnt(8)
	s_waitcnt lgkmcnt(0)
	s_barrier
	s_setprio 1
	s_waitcnt lgkmcnt(0)
	v_mfma_f32_16x16x32_bf16 v[126:129], v[142:145], v[182:185], v[126:129]
	v_mfma_f32_16x16x32_bf16 v[122:125], v[156:159], v[182:185], v[122:125]
	v_mfma_f32_16x16x32_bf16 v[110:113], v[142:145], v[190:193], v[110:113]
	v_mfma_f32_16x16x32_bf16 v[106:109], v[156:159], v[190:193], v[106:109]
	v_mfma_f32_16x16x32_bf16 v[94:97], v[142:145], v[198:201], v[94:97]
	v_mfma_f32_16x16x32_bf16 v[90:93], v[156:159], v[198:201], v[90:93]
	v_mfma_f32_16x16x32_bf16 v[78:81], v[142:145], v[206:209], v[78:81]
	v_mfma_f32_16x16x32_bf16 v[74:77], v[156:159], v[206:209], v[74:77]
	v_mfma_f32_16x16x32_bf16 v[126:129], v[152:155], v[186:189], v[126:129]
	v_mfma_f32_16x16x32_bf16 v[122:125], v[160:163], v[186:189], v[122:125]
	v_mfma_f32_16x16x32_bf16 v[110:113], v[152:155], v[194:197], v[110:113]
	v_mfma_f32_16x16x32_bf16 v[106:109], v[160:163], v[194:197], v[106:109]
	v_mfma_f32_16x16x32_bf16 v[94:97], v[152:155], v[202:205], v[94:97]
	v_mfma_f32_16x16x32_bf16 v[90:93], v[160:163], v[202:205], v[90:93]
	v_mfma_f32_16x16x32_bf16 v[78:81], v[152:155], v[210:213], v[78:81]
	v_mfma_f32_16x16x32_bf16 v[74:77], v[160:163], v[210:213], v[74:77]
	s_setprio 0
	s_setprio 1
	v_mfma_f32_16x16x32_bf16 v[118:121], v[164:167], v[182:185], v[118:121]
	v_mfma_f32_16x16x32_bf16 v[114:117], v[172:175], v[182:185], v[114:117]
	v_mfma_f32_16x16x32_bf16 v[102:105], v[164:167], v[190:193], v[102:105]
	v_mfma_f32_16x16x32_bf16 v[98:101], v[172:175], v[190:193], v[98:101]
	v_mfma_f32_16x16x32_bf16 v[86:89], v[164:167], v[198:201], v[86:89]
	v_mfma_f32_16x16x32_bf16 v[82:85], v[172:175], v[198:201], v[82:85]
	v_mfma_f32_16x16x32_bf16 v[70:73], v[164:167], v[206:209], v[70:73]
	v_mfma_f32_16x16x32_bf16 v[66:69], v[172:175], v[206:209], v[66:69]
	v_mfma_f32_16x16x32_bf16 v[118:121], v[168:171], v[186:189], v[118:121]
	v_mfma_f32_16x16x32_bf16 v[114:117], v[176:179], v[186:189], v[114:117]
	v_mfma_f32_16x16x32_bf16 v[102:105], v[168:171], v[194:197], v[102:105]
	v_mfma_f32_16x16x32_bf16 v[98:101], v[176:179], v[194:197], v[98:101]
	v_mfma_f32_16x16x32_bf16 v[86:89], v[168:171], v[202:205], v[86:89]
	v_mfma_f32_16x16x32_bf16 v[82:85], v[176:179], v[202:205], v[82:85]
	v_mfma_f32_16x16x32_bf16 v[70:73], v[168:171], v[210:213], v[70:73]
	v_mfma_f32_16x16x32_bf16 v[66:69], v[176:179], v[210:213], v[66:69]
	s_setprio 0
	s_barrier
; #define PG8_STAGE(bufoff, gbase, voff) do { _Pragma("unroll") for (int _i = 0; _i < 2; ++_i) \
;         __builtin_amdgcn_global_load_lds((const unsigned*)((const char*)(gbase) + (voff)[_i]), (LAS unsigned*)(lds + (bufoff) + ldsw + _i * 8192), 16, 0, 0); } while (0)
; #define PG8_LDA(dst, b, h) do { _Pragma("unroll") for (int m = 0; m < 4; ++m) _Pragma("unroll") for (int k = 0; k < 2; ++k) dst[m][k] = *(const LAS bf16x8*)(lds + PG8_SA(b, h) + aoff + m * 2048 + k * 1024); } while (0)
; #define PG8_MMA(ai, bj, At, Bt) do { __builtin_amdgcn_s_setprio(1); _Pragma("unroll") for (int m = 0; m < 4; ++m) _Pragma("unroll") for (int n = 0; n < 2; ++n) _Pragma("unroll") for (int k = 0; k < 2; ++k) \
;         acc[ai][bj][m][n] = __builtin_amdgcn_mfma_f32_16x16x32_bf16(Bt[n][k], At[m][k], acc[ai][bj][m][n], 0, 0, 0); __builtin_amdgcn_s_setprio(0); } while (0)
; #define PG8_WAIT_V(n) asm volatile("s_waitcnt vmcnt(" #n ")" ::: "memory")
; #define PG8_WAIT_L(n) asm volatile("s_waitcnt lgkmcnt(" #n ")" ::: "memory")
; #define PG8_BAR __builtin_amdgcn_s_barrier()
; #define PG8_SCHED __builtin_amdgcn_sched_barrier(0)
; #define PG8_STAGE(bufoff, gbase, voff) do { _Pragma("unroll") for (int _i = 0; _i < 2; ++_i) \
;         __builtin_amdgcn_global_load_lds((const unsigned*)((const char*)(gbase) + (voff)[_i]), (LAS unsigned*)(lds + (bufoff) + ldsw + _i * 8192), 16, 0, 0); } while (0)
; #define PG8_LDA(dst, b, h) do { _Pragma("unroll") for (int m = 0; m < 4; ++m) _Pragma("unroll") for (int k = 0; k < 2; ++k) dst[m][k] = *(const LAS bf16x8*)(lds + PG8_SA(b, h) + aoff + m * 2048 + k * 1024); } while (0)
; #define PG8_WAIT_V(n) asm volatile("s_waitcnt vmcnt(" #n ")" ::: "memory")
; #define PG8_WAIT_L(n) asm volatile("s_waitcnt lgkmcnt(" #n ")" ::: "memory")
; #define PG8_BAR __builtin_amdgcn_s_barrier()
; #define PG8_SCHED __builtin_amdgcn_sched_barrier(0)
; template <class Epi, class Sched>
; __device__ __forceinline__ void gemm_phase(LAS unsigned char* lds, const Gemm g, const Sched& S, const Epi& E) {
;     ...
;             PG8_LDA(At, 1, 1); PG8_STAGE(PG8_SB(1, 0), b3, voffB); PG8_STAGE(PG8_SB(1, 1), b3 + hstepB, voffB); PG8_STAGE(PG8_SA(1, 0), a3, voffA);
;             PG8_WAIT_V(8); PG8_WAIT_L(0); PG8_BAR; PG8_MMA(1, 0, At, B0); PG8_MMA(1, 1, At, B1); PG8_BAR; PG8_SCHED;
;         }
;         if (wr == 0) PG8_BAR;
	s_add_i32 s14, s48, s26
	v_lshl_add_u64 v[146:147], v[146:147], 0, s[86:87]
	s_mov_b32 m0, s14
	ds_read_b128 v[182:185], v150 offset:49152
	ds_read_b128 v[186:189], v150 offset:50176
	ds_read_b128 v[190:193], v150 offset:51200
	ds_read_b128 v[194:197], v150 offset:52224
	ds_read_b128 v[198:201], v150 offset:53248
	ds_read_b128 v[202:205], v150 offset:54272
	ds_read_b128 v[206:209], v150 offset:55296
	ds_read_b128 v[210:213], v150 offset:56320
	global_load_lds_dwordx4 v[146:147], off
	s_add_i32 m0, s14, 0x2000
	s_add_u32 s14, s18, 0xb0080
	v_lshl_add_u64 v[146:147], v[214:215], 0, s[86:87]
	s_addc_u32 s15, s19, 0
	s_add_i32 s18, s49, s26
	global_load_lds_dwordx4 v[146:147], off
	v_lshl_add_u64 v[146:147], s[14:15], 0, v[132:133]
	s_mov_b32 m0, s18
	s_nop 0
	global_load_lds_dwordx4 v[146:147], off
	v_lshl_add_u64 v[146:147], s[14:15], 0, v[136:137]
	s_add_i32 m0, s18, 0x2000
	s_nop 0
	global_load_lds_dwordx4 v[146:147], off
	v_lshl_add_u64 v[146:147], v[226:227], 0, s[86:87]
	s_mov_b32 m0, s31
	s_nop 0
	global_load_lds_dwordx4 v[146:147], off
	v_lshl_add_u64 v[146:147], v[228:229], 0, s[86:87]
	s_mov_b32 m0, s38
	s_nop 0
	global_load_lds_dwordx4 v[146:147], off
	s_waitcnt vmcnt(8)
	s_waitcnt lgkmcnt(0)
	s_barrier
	s_setprio 1
	s_waitcnt lgkmcnt(0)
	v_mfma_f32_16x16x32_bf16 v[62:65], v[142:145], v[182:185], v[62:65]
	v_mfma_f32_16x16x32_bf16 v[58:61], v[156:159], v[182:185], v[58:61]
	v_mfma_f32_16x16x32_bf16 v[46:49], v[142:145], v[190:193], v[46:49]
	v_mfma_f32_16x16x32_bf16 v[42:45], v[156:159], v[190:193], v[42:45]
	v_mfma_f32_16x16x32_bf16 v[30:33], v[142:145], v[198:201], v[30:33]
	v_mfma_f32_16x16x32_bf16 v[26:29], v[156:159], v[198:201], v[26:29]
	v_mfma_f32_16x16x32_bf16 v[14:17], v[142:145], v[206:209], v[14:17]
	v_mfma_f32_16x16x32_bf16 v[10:13], v[156:159], v[206:209], v[10:13]
	v_mfma_f32_16x16x32_bf16 v[62:65], v[152:155], v[186:189], v[62:65]
	v_mfma_f32_16x16x32_bf16 v[58:61], v[160:163], v[186:189], v[58:61]
	v_mfma_f32_16x16x32_bf16 v[46:49], v[152:155], v[194:197], v[46:49]
	v_mfma_f32_16x16x32_bf16 v[42:45], v[160:163], v[194:197], v[42:45]
	v_mfma_f32_16x16x32_bf16 v[30:33], v[152:155], v[202:205], v[30:33]
	v_mfma_f32_16x16x32_bf16 v[26:29], v[160:163], v[202:205], v[26:29]
	v_mfma_f32_16x16x32_bf16 v[14:17], v[152:155], v[210:213], v[14:17]
	v_mfma_f32_16x16x32_bf16 v[10:13], v[160:163], v[210:213], v[10:13]
	s_setprio 0
	s_setprio 1
	v_mfma_f32_16x16x32_bf16 v[54:57], v[164:167], v[182:185], v[54:57]
	v_mfma_f32_16x16x32_bf16 v[50:53], v[172:175], v[182:185], v[50:53]
	v_mfma_f32_16x16x32_bf16 v[38:41], v[164:167], v[190:193], v[38:41]
	v_mfma_f32_16x16x32_bf16 v[34:37], v[172:175], v[190:193], v[34:37]
	v_mfma_f32_16x16x32_bf16 v[22:25], v[164:167], v[198:201], v[22:25]
	v_mfma_f32_16x16x32_bf16 v[18:21], v[172:175], v[198:201], v[18:21]
	v_mfma_f32_16x16x32_bf16 v[6:9], v[164:167], v[206:209], v[6:9]
	v_mfma_f32_16x16x32_bf16 v[2:5], v[172:175], v[206:209], v[2:5]
	v_mfma_f32_16x16x32_bf16 v[54:57], v[168:171], v[186:189], v[54:57]
	v_mfma_f32_16x16x32_bf16 v[50:53], v[176:179], v[186:189], v[50:53]
	v_mfma_f32_16x16x32_bf16 v[38:41], v[168:171], v[194:197], v[38:41]
	v_mfma_f32_16x16x32_bf16 v[34:37], v[176:179], v[194:197], v[34:37]
	v_mfma_f32_16x16x32_bf16 v[22:25], v[168:171], v[202:205], v[22:25]
	v_mfma_f32_16x16x32_bf16 v[18:21], v[176:179], v[202:205], v[18:21]
	v_mfma_f32_16x16x32_bf16 v[6:9], v[168:171], v[210:213], v[6:9]
	v_mfma_f32_16x16x32_bf16 v[2:5], v[176:179], v[210:213], v[2:5]
	s_setprio 0
	s_barrier
	s_add_i32 s46, s46, 2
	s_add_u32 s44, s44, 0x100
	s_addc_u32 s45, s45, 0
	s_cmp_gt_u32 s46, 41
	s_mov_b64 s[14:15], s[16:17]
	s_cbranch_scc0 .LBB0_1238
	s_and_b64 vcc, exec, s[10:11]
	s_and_b64 vcc, vcc, s[4:5]
	s_cbranch_vccz .LBB0_1241
	s_barrier
.LBB0_1241:
	v_lshl_add_u32 v144, s42, 8, v1
	v_lshl_or_b32 v142, s43, 8, v149
	v_ashrrev_i32_e32 v145, 31, v144
	v_ashrrev_i32_e32 v143, 31, v142
	v_lshlrev_b64 v[146:147], 12, v[144:145]
	v_lshl_add_u64 v[152:153], s[8:9], 0, v[146:147]
	v_lshlrev_b64 v[146:147], 2, v[142:143]
	v_lshl_add_u64 v[142:143], v[152:153], 0, v[146:147]
	global_load_dwordx4 v[152:155], v[142:143], off
	global_load_dwordx4 v[156:159], v[142:143], off offset:16
	s_mov_b64 s[14:15], 0x80000
	s_waitcnt vmcnt(0) lgkmcnt(0)
	v_pk_add_f32 v[128:129], v[128:129], v[154:155]
	v_pk_add_f32 v[126:127], v[126:127], v[152:153]
	v_pk_add_f32 v[124:125], v[124:125], v[158:159]
	v_pk_add_f32 v[122:123], v[122:123], v[156:157]
	global_store_dwordx4 v[142:143], v[126:129], off
	global_store_dwordx4 v[142:143], v[122:125], off offset:16
	global_load_dwordx4 v[122:125], v[142:143], off offset:512
	s_nop 0
	global_load_dwordx4 v[126:129], v[142:143], off offset:528
	s_waitcnt vmcnt(0) lgkmcnt(0)
	v_pk_add_f32 v[120:121], v[120:121], v[124:125]
	v_pk_add_f32 v[116:117], v[116:117], v[128:129]
	v_pk_add_f32 v[114:115], v[114:115], v[126:127]
	global_store_dwordx4 v[142:143], v[114:117], off offset:528
	v_pk_add_f32 v[118:119], v[118:119], v[122:123]
	global_store_dwordx4 v[142:143], v[118:121], off offset:512
	v_or_b32_e32 v114, 16, v144
	v_ashrrev_i32_e32 v115, 31, v114
	v_lshlrev_b64 v[114:115], 12, v[114:115]
	v_lshl_add_u64 v[114:115], s[8:9], 0, v[114:115]
	v_lshl_add_u64 v[122:123], v[114:115], 0, v[146:147]
	global_load_dwordx4 v[114:117], v[122:123], off
	global_load_dwordx4 v[118:121], v[122:123], off offset:16
	s_waitcnt vmcnt(0) lgkmcnt(0)
	v_pk_add_f32 v[112:113], v[112:113], v[116:117]
	v_pk_add_f32 v[110:111], v[110:111], v[114:115]
	v_pk_add_f32 v[108:109], v[108:109], v[120:121]
	v_pk_add_f32 v[106:107], v[106:107], v[118:119]
	global_store_dwordx4 v[122:123], v[110:113], off
	global_store_dwordx4 v[122:123], v[106:109], off offset:16
	global_load_dwordx4 v[106:109], v[122:123], off offset:512
	s_nop 0
	global_load_dwordx4 v[110:113], v[122:123], off offset:528
	s_waitcnt vmcnt(0) lgkmcnt(0)
; #define PG8_BAR __builtin_amdgcn_s_barrier()
; #define PG8_BAR __builtin_amdgcn_s_barrier()
; template <class Epi, class Sched>
; __device__ __forceinline__ void gemm_phase(LAS unsigned char* lds, const Gemm g, const Sched& S, const Epi& E) {
;     ...
;         cur = nxt; cA = nA; cB = nB; ++ui;
;         if (wr == 1) PG8_BAR;
	v_pk_add_f32 v[104:105], v[104:105], v[108:109]
	v_pk_add_f32 v[100:101], v[100:101], v[112:113]
	v_pk_add_f32 v[98:99], v[98:99], v[110:111]
	global_store_dwordx4 v[122:123], v[98:101], off offset:528
	v_pk_add_f32 v[102:103], v[102:103], v[106:107]
	global_store_dwordx4 v[122:123], v[102:105], off offset:512
	v_or_b32_e32 v98, 32, v144
	v_ashrrev_i32_e32 v99, 31, v98
	v_lshlrev_b64 v[98:99], 12, v[98:99]
	v_lshl_add_u64 v[98:99], s[8:9], 0, v[98:99]
	v_lshl_add_u64 v[106:107], v[98:99], 0, v[146:147]
	global_load_dwordx4 v[98:101], v[106:107], off
	global_load_dwordx4 v[102:105], v[106:107], off offset:16
	s_waitcnt vmcnt(0) lgkmcnt(0)
	v_pk_add_f32 v[96:97], v[96:97], v[100:101]
	v_pk_add_f32 v[94:95], v[94:95], v[98:99]
	v_pk_add_f32 v[92:93], v[92:93], v[104:105]
	v_pk_add_f32 v[90:91], v[90:91], v[102:103]
	global_store_dwordx4 v[106:107], v[94:97], off
	global_store_dwordx4 v[106:107], v[90:93], off offset:16
	global_load_dwordx4 v[90:93], v[106:107], off offset:512
	s_nop 0
	global_load_dwordx4 v[94:97], v[106:107], off offset:528
	s_waitcnt vmcnt(0) lgkmcnt(0)
	v_pk_add_f32 v[88:89], v[88:89], v[92:93]
	v_pk_add_f32 v[84:85], v[84:85], v[96:97]
	v_pk_add_f32 v[82:83], v[82:83], v[94:95]
	global_store_dwordx4 v[106:107], v[82:85], off offset:528
	v_pk_add_f32 v[86:87], v[86:87], v[90:91]
	global_store_dwordx4 v[106:107], v[86:89], off offset:512
	v_or_b32_e32 v82, 48, v144
	v_ashrrev_i32_e32 v83, 31, v82
	v_lshlrev_b64 v[82:83], 12, v[82:83]
	v_lshl_add_u64 v[82:83], s[8:9], 0, v[82:83]
	v_lshl_add_u64 v[90:91], v[82:83], 0, v[146:147]
	global_load_dwordx4 v[82:85], v[90:91], off
	global_load_dwordx4 v[86:89], v[90:91], off offset:16
	s_waitcnt vmcnt(0) lgkmcnt(0)
	v_pk_add_f32 v[80:81], v[80:81], v[84:85]
	v_pk_add_f32 v[78:79], v[78:79], v[82:83]
	v_pk_add_f32 v[76:77], v[76:77], v[88:89]
	v_pk_add_f32 v[74:75], v[74:75], v[86:87]
	global_store_dwordx4 v[90:91], v[78:81], off
	global_store_dwordx4 v[90:91], v[74:77], off offset:16
	global_load_dwordx4 v[74:77], v[90:91], off offset:512
	s_nop 0
	global_load_dwordx4 v[78:81], v[90:91], off offset:528
	s_waitcnt vmcnt(0) lgkmcnt(0)
	v_pk_add_f32 v[72:73], v[72:73], v[76:77]
	v_pk_add_f32 v[70:71], v[70:71], v[74:75]
	v_pk_add_f32 v[68:69], v[68:69], v[80:81]
	v_pk_add_f32 v[66:67], v[66:67], v[78:79]
	v_lshl_add_u64 v[74:75], v[142:143], 0, s[14:15]
	s_mov_b32 s14, 0x80000
	global_store_dwordx4 v[90:91], v[70:73], off offset:512
	global_store_dwordx4 v[90:91], v[66:69], off offset:528
	v_add_co_u32_e32 v76, vcc, s14, v142
	s_mov_b64 s[14:15], 0x90000
	s_nop 0
	v_addc_co_u32_e32 v77, vcc, 0, v143, vcc
	global_load_dwordx4 v[66:69], v[76:77], off
	global_load_dwordx4 v[70:73], v[74:75], off offset:16
	s_waitcnt vmcnt(0) lgkmcnt(0)
	v_pk_add_f32 v[64:65], v[64:65], v[68:69]
	v_pk_add_f32 v[62:63], v[62:63], v[66:67]
	v_pk_add_f32 v[60:61], v[60:61], v[72:73]
	v_pk_add_f32 v[58:59], v[58:59], v[70:71]
	global_store_dwordx4 v[76:77], v[62:65], off
	global_store_dwordx4 v[74:75], v[58:61], off offset:16
	global_load_dwordx4 v[58:61], v[74:75], off offset:512
	s_nop 0
	global_load_dwordx4 v[62:65], v[74:75], off offset:528
	s_waitcnt vmcnt(0) lgkmcnt(0)
	v_pk_add_f32 v[54:55], v[54:55], v[58:59]
	v_lshl_add_u64 v[58:59], v[142:143], 0, s[14:15]
	s_mov_b32 s14, 0x90000
	v_pk_add_f32 v[56:57], v[56:57], v[60:61]
	v_pk_add_f32 v[52:53], v[52:53], v[64:65]
	v_pk_add_f32 v[50:51], v[50:51], v[62:63]
	v_add_co_u32_e32 v60, vcc, s14, v142
	global_store_dwordx4 v[74:75], v[54:57], off offset:512
	global_store_dwordx4 v[74:75], v[50:53], off offset:528
	v_addc_co_u32_e32 v61, vcc, 0, v143, vcc
	global_load_dwordx4 v[50:53], v[60:61], off
	global_load_dwordx4 v[54:57], v[58:59], off offset:16
	s_mov_b64 s[14:15], 0xa0000
	s_waitcnt vmcnt(0) lgkmcnt(0)
	v_pk_add_f32 v[48:49], v[48:49], v[52:53]
	v_pk_add_f32 v[46:47], v[46:47], v[50:51]
	v_pk_add_f32 v[44:45], v[44:45], v[56:57]
	v_pk_add_f32 v[42:43], v[42:43], v[54:55]
	global_store_dwordx4 v[60:61], v[46:49], off
	global_store_dwordx4 v[58:59], v[42:45], off offset:16
	global_load_dwordx4 v[42:45], v[58:59], off offset:512
	s_nop 0
	global_load_dwordx4 v[46:49], v[58:59], off offset:528
	s_waitcnt vmcnt(0) lgkmcnt(0)
	v_pk_add_f32 v[38:39], v[38:39], v[42:43]
	v_lshl_add_u64 v[42:43], v[142:143], 0, s[14:15]
	s_mov_b32 s14, 0xa0000
	v_pk_add_f32 v[40:41], v[40:41], v[44:45]
	v_pk_add_f32 v[36:37], v[36:37], v[48:49]
	v_pk_add_f32 v[34:35], v[34:35], v[46:47]
	v_add_co_u32_e32 v44, vcc, s14, v142
	global_store_dwordx4 v[58:59], v[38:41], off offset:512
	global_store_dwordx4 v[58:59], v[34:37], off offset:528
	v_addc_co_u32_e32 v45, vcc, 0, v143, vcc
	global_load_dwordx4 v[34:37], v[44:45], off
	global_load_dwordx4 v[38:41], v[42:43], off offset:16
	s_mov_b64 s[14:15], 0xb0000
	s_waitcnt vmcnt(0) lgkmcnt(0)
	v_pk_add_f32 v[32:33], v[32:33], v[36:37]
	v_pk_add_f32 v[30:31], v[30:31], v[34:35]
	v_pk_add_f32 v[28:29], v[28:29], v[40:41]
	v_pk_add_f32 v[26:27], v[26:27], v[38:39]
	global_store_dwordx4 v[44:45], v[30:33], off
	global_store_dwordx4 v[42:43], v[26:29], off offset:16
	global_load_dwordx4 v[26:29], v[42:43], off offset:512
	s_nop 0
	global_load_dwordx4 v[30:33], v[42:43], off offset:528
	s_waitcnt vmcnt(0) lgkmcnt(0)
	v_pk_add_f32 v[24:25], v[24:25], v[28:29]
	v_pk_add_f32 v[20:21], v[20:21], v[32:33]
	v_pk_add_f32 v[18:19], v[18:19], v[30:31]
	global_store_dwordx4 v[42:43], v[18:21], off offset:528
	v_pk_add_f32 v[22:23], v[22:23], v[26:27]
	global_store_dwordx4 v[42:43], v[22:25], off offset:512
	v_lshl_add_u64 v[18:19], v[142:143], 0, s[14:15]
	s_mov_b32 s14, 0xb0000
	v_add_co_u32_e32 v28, vcc, s14, v142
	s_mov_b64 s[14:15], -1
	s_nop 0
	v_addc_co_u32_e32 v29, vcc, 0, v143, vcc
	global_load_dwordx4 v[20:23], v[28:29], off
	global_load_dwordx4 v[24:27], v[18:19], off offset:16
	s_and_b64 vcc, exec, s[4:5]
	s_waitcnt vmcnt(0) lgkmcnt(0)
	v_pk_add_f32 v[16:17], v[16:17], v[22:23]
	v_pk_add_f32 v[14:15], v[14:15], v[20:21]
	v_pk_add_f32 v[12:13], v[12:13], v[26:27]
	v_pk_add_f32 v[10:11], v[10:11], v[24:25]
	global_store_dwordx4 v[28:29], v[14:17], off
	global_store_dwordx4 v[18:19], v[10:13], off offset:16
	global_load_dwordx4 v[10:13], v[18:19], off offset:512
	s_nop 0
	global_load_dwordx4 v[14:17], v[18:19], off offset:528
	s_waitcnt vmcnt(0) lgkmcnt(0)
	v_pk_add_f32 v[8:9], v[8:9], v[12:13]
	v_pk_add_f32 v[6:7], v[6:7], v[10:11]
	v_pk_add_f32 v[4:5], v[4:5], v[16:17]
	v_pk_add_f32 v[2:3], v[2:3], v[14:15]
	global_store_dwordx4 v[18:19], v[6:9], off offset:512
	global_store_dwordx4 v[18:19], v[2:5], off offset:528
	s_cbranch_vccnz .LBB0_1226
	s_branch .LBB0_1225
